# v34 plus MFMAs inside each 16-MFMA block reordered so consecutive MFMAs share one input operand (same-accumulator pairs kept 8 apart)
# speedup vs baseline: 1.0035x; 1.0035x over previous
; #define PG8_STAGE(bufoff, gbase, voff) do { _Pragma("unroll") for (int _i = 0; _i < 2; ++_i) \
;         __builtin_amdgcn_global_load_lds((const unsigned*)((const char*)(gbase) + (voff)[_i]), (PG8_LAS unsigned*)(lds + (bufoff) + ldsw + _i * 8192), 16, 0, 0); } while (0)
; #define PG8_LDA(dst, b, h) do { _Pragma("unroll") for (int m = 0; m < 4; ++m) _Pragma("unroll") for (int k = 0; k < 2; ++k) dst[m][k] = *(const PG8_LAS bf16x8*)(lds + PG8_SA(b, h) + aoff + m * 2048 + k * 1024); } while (0)
; #define PG8_LDB(dst, b, h) do { _Pragma("unroll") for (int n = 0; n < 2; ++n) _Pragma("unroll") for (int k = 0; k < 2; ++k) dst[n][k] = *(const PG8_LAS bf16x8*)(lds + PG8_SB(b, h) + boff + n * 2048 + k * 1024); } while (0)
; #define PG8_MMA(ai, bj, At, Bt) do { __builtin_amdgcn_s_setprio(1); _Pragma("unroll") for (int m = 0; m < 4; ++m) _Pragma("unroll") for (int n = 0; n < 2; ++n) _Pragma("unroll") for (int k = 0; k < 2; ++k) \
;         acc[ai][bj][m][n] = mma16<Epi::I8>(Bt[n][k], At[m][k], acc[ai][bj][m][n]); __builtin_amdgcn_s_setprio(0); } while (0)
; #define PG8_WAIT_V(n) asm volatile("s_waitcnt vmcnt(" #n ")" ::: "memory")
; #define PG8_WAIT_L(n) asm volatile("s_waitcnt lgkmcnt(" #n ")" ::: "memory")
; template <class Epi, class Sched, bool ALIGN_EPI = false, bool SP2 = false>
; __device__ __forceinline__ void gemm_phase(PG8_LAS unsigned char* lds, const Gemm g, const Sched& S, const Epi& E) {
;     ...
;         for (int t = 0; t < nt; t += 2) {
;             const bool last = (t == nt - 2);
;             const char* a1 = cA + (size_t)(t + 1) * kstep;
;             const char* a2 = last ? nA : cA + (size_t)(t + 2) * kstep; const char* b2 = last ? nB : cB + (size_t)(t + 2) * kstep;
;             const char* a3 = a2 + kstep; const char* b3 = b2 + kstep;
;             if (last && has_next) S.a_ready(nxt);
;             if constexpr (SP2) {
;             PG8_LDB(B0, 0, 0); PG8_LDB(B1, 0, 1); PG8_SCHED; PG8_LDA(At, 0, 0); PG8_STAGE(PG8_SA(1, 1), a1 + hstep, voffA);
;             PG8_WAIT_V(8); PG8_WAIT_L(0); PG8_BAR; PG8_MMA(0, 0, At, B0); PG8_MMA(0, 1, At, B1); PG8_BAR; PG8_SCHED;
;             PG8_LDA(At, 0, 1); PG8_STAGE(PG8_SB(0, 0), b2, voffB); PG8_STAGE(PG8_SB(0, 1), b2 + hstep, voffB); PG8_STAGE(PG8_SA(0, 0), a2, voffA);
;             PG8_WAIT_V(8); PG8_WAIT_L(0); PG8_BAR; PG8_MMA(1, 0, At, B0); PG8_MMA(1, 1, At, B1); PG8_BAR; PG8_SCHED;
.Lpeel80:
	s_add_u32 s8, s0, 0x100
	s_addc_u32 s9, s1, 0
	s_add_i32 vcc_hi, 0, 0x10000
	s_cmp_eq_u32 vcc_lo, 12
	s_cselect_b32 s13, s66, s9
	s_cselect_b32 s12, s67, s8
	s_cselect_b32 s7, s82, s97
	s_cselect_b32 s6, s83, s96
	s_add_i32 s4, 0, 0x14000
	v_add_u32_e32 v38, vcc_hi, v242
	v_add_u32_e32 v158, s4, v242
	ds_read_b128 v[18:21], v38
	ds_read_b128 v[22:25], v38 offset:1024
	ds_read_b128 v[34:37], v38 offset:2048
	ds_read_b128 v[38:41], v38 offset:3072
	ds_read_b128 v[130:133], v158
	ds_read_b128 v[134:137], v158 offset:1024
	ds_read_b128 v[154:157], v158 offset:2048
	ds_read_b128 v[158:161], v158 offset:3072
	s_add_i32 m0, s11, 0xc000
	ds_read_b128 v[162:165], v243
	ds_read_b128 v[166:169], v243 offset:1024
	ds_read_b128 v[170:173], v243 offset:2048
	ds_read_b128 v[174:177], v243 offset:3072
	ds_read_b128 v[178:181], v243 offset:4096
	ds_read_b128 v[182:185], v243 offset:5120
	ds_read_b128 v[186:189], v243 offset:6144
	ds_read_b128 v[190:193], v243 offset:7168
	global_load_lds_dwordx4 v216, s[0:1]
	s_add_i32 m0, s11, 0xe000
	s_nop 0
	global_load_lds_dwordx4 v218, s[0:1]
	s_waitcnt vmcnt(8)
	s_waitcnt lgkmcnt(0)
	s_barrier
	s_setprio 1
	s_waitcnt lgkmcnt(0)
	v_mfma_i32_16x16x64_i8 v[150:153], v[18:21], v[162:165], 0
	v_mfma_i32_16x16x64_i8 v[146:149], v[34:37], v[162:165], 0
	v_mfma_i32_16x16x64_i8 v[110:113], v[34:37], v[170:173], 0
	v_mfma_i32_16x16x64_i8 v[118:121], v[18:21], v[170:173], 0
	v_mfma_i32_16x16x64_i8 v[54:57], v[18:21], v[178:181], 0
	v_mfma_i32_16x16x64_i8 v[30:33], v[34:37], v[178:181], 0
	v_mfma_i32_16x16x64_i8 v[58:61], v[34:37], v[186:189], 0
	v_mfma_i32_16x16x64_i8 v[94:97], v[18:21], v[186:189], 0
	v_mfma_i32_16x16x64_i8 v[150:153], v[22:25], v[166:169], v[150:153]
	v_mfma_i32_16x16x64_i8 v[146:149], v[38:41], v[166:169], v[146:149]
	v_mfma_i32_16x16x64_i8 v[110:113], v[38:41], v[174:177], v[110:113]
	v_mfma_i32_16x16x64_i8 v[118:121], v[22:25], v[174:177], v[118:121]
	v_mfma_i32_16x16x64_i8 v[54:57], v[22:25], v[182:185], v[54:57]
	v_mfma_i32_16x16x64_i8 v[30:33], v[38:41], v[182:185], v[30:33]
	v_mfma_i32_16x16x64_i8 v[58:61], v[38:41], v[190:193], v[58:61]
	v_mfma_i32_16x16x64_i8 v[94:97], v[22:25], v[190:193], v[94:97]
	s_setprio 0
	s_setprio 1
	v_mfma_i32_16x16x64_i8 v[142:145], v[130:133], v[162:165], 0
	v_mfma_i32_16x16x64_i8 v[138:141], v[154:157], v[162:165], 0
	v_mfma_i32_16x16x64_i8 v[98:101], v[154:157], v[170:173], 0
	v_mfma_i32_16x16x64_i8 v[102:105], v[130:133], v[170:173], 0
	v_mfma_i32_16x16x64_i8 v[42:45], v[130:133], v[178:181], 0
	v_mfma_i32_16x16x64_i8 v[26:29], v[154:157], v[178:181], 0
	v_mfma_i32_16x16x64_i8 v[62:65], v[154:157], v[186:189], 0
	v_mfma_i32_16x16x64_i8 v[78:81], v[130:133], v[186:189], 0
	v_mfma_i32_16x16x64_i8 v[142:145], v[134:137], v[166:169], v[142:145]
	v_mfma_i32_16x16x64_i8 v[138:141], v[158:161], v[166:169], v[138:141]
	v_mfma_i32_16x16x64_i8 v[98:101], v[158:161], v[174:177], v[98:101]
	v_mfma_i32_16x16x64_i8 v[102:105], v[134:137], v[174:177], v[102:105]
	v_mfma_i32_16x16x64_i8 v[42:45], v[134:137], v[182:185], v[42:45]
	v_mfma_i32_16x16x64_i8 v[26:29], v[158:161], v[182:185], v[26:29]
	v_mfma_i32_16x16x64_i8 v[62:65], v[158:161], v[190:193], v[62:65]
	v_mfma_i32_16x16x64_i8 v[78:81], v[134:137], v[190:193], v[78:81]
	s_setprio 0
	s_barrier
	s_add_i32 s0, vcc_hi, s69
	v_lshl_add_u64 v[198:199], s[6:7], 0, v[0:1]
	s_mov_b32 m0, s0
	ds_read_b128 v[162:165], v243 offset:16384
	ds_read_b128 v[166:169], v243 offset:17408
	ds_read_b128 v[170:173], v243 offset:18432
	ds_read_b128 v[174:177], v243 offset:19456
	ds_read_b128 v[178:181], v243 offset:20480
	ds_read_b128 v[182:185], v243 offset:21504
	ds_read_b128 v[186:189], v243 offset:22528
	ds_read_b128 v[190:193], v243 offset:23552
	global_load_lds_dwordx4 v[198:199], off
	s_add_i32 m0, s0, 0x2000
	s_add_u32 s0, s6, 0x40000
	v_lshl_add_u64 v[200:201], s[6:7], 0, v[214:215]
	s_addc_u32 s1, s7, 0
	s_add_i32 s4, s4, s69
	global_load_lds_dwordx4 v[200:201], off
	s_mov_b32 m0, s4
	v_lshl_add_u64 v[206:207], s[12:13], 0, v[210:211]
	global_load_lds_dwordx4 v0, s[0:1]
	s_add_i32 m0, s4, 0x2000
	v_lshl_add_u64 v[220:221], s[12:13], 0, v[212:213]
	global_load_lds_dwordx4 v214, s[0:1]
	s_mov_b32 m0, s11
	s_nop 0
	global_load_lds_dwordx4 v[206:207], off
	s_mov_b32 m0, s71
	s_nop 0
	global_load_lds_dwordx4 v[220:221], off
	s_waitcnt vmcnt(8)
	s_waitcnt lgkmcnt(0)
	s_barrier
	s_setprio 1
	s_waitcnt lgkmcnt(0)
	v_mfma_i32_16x16x64_i8 v[106:109], v[18:21], v[162:165], 0
	v_mfma_i32_16x16x64_i8 v[46:49], v[34:37], v[162:165], 0
	v_mfma_i32_16x16x64_i8 v[6:9], v[34:37], v[170:173], 0
	v_mfma_i32_16x16x64_i8 v[14:17], v[18:21], v[170:173], 0
	v_mfma_i32_16x16x64_i8 v[90:93], v[18:21], v[178:181], 0
	v_mfma_i32_16x16x64_i8 v[86:89], v[34:37], v[178:181], 0
	v_mfma_i32_16x16x64_i8 v[18:21], v[18:21], v[186:189], 0
	v_mfma_i32_16x16x64_i8 v[106:109], v[22:25], v[166:169], v[106:109]
	v_mfma_i32_16x16x64_i8 v[46:49], v[38:41], v[166:169], v[46:49]
	v_mfma_i32_16x16x64_i8 v[6:9], v[38:41], v[174:177], v[6:9]
	v_mfma_i32_16x16x64_i8 v[14:17], v[22:25], v[174:177], v[14:17]
	v_mfma_i32_16x16x64_i8 v[90:93], v[22:25], v[182:185], v[90:93]
	v_mfma_i32_16x16x64_i8 v[86:89], v[38:41], v[182:185], v[86:89]
	v_mfma_i32_16x16x64_i8 v[18:21], v[22:25], v[190:193], v[18:21]
	v_mfma_i32_16x16x64_i8 v[22:25], v[34:37], v[186:189], 0
	v_mfma_i32_16x16x64_i8 v[22:25], v[38:41], v[190:193], v[22:25]
	s_setprio 0
	s_setprio 1
	v_mfma_i32_16x16x64_i8 v[38:41], v[154:157], v[162:165], 0
	v_mfma_i32_16x16x64_i8 v[2:5], v[154:157], v[170:173], 0
	v_mfma_i32_16x16x64_i8 v[10:13], v[130:133], v[170:173], 0
	v_mfma_i32_16x16x64_i8 v[50:53], v[130:133], v[178:181], 0
	v_mfma_i32_16x16x64_i8 v[34:37], v[130:133], v[162:165], 0
	v_mfma_i32_16x16x64_i8 v[82:85], v[134:137], v[182:185], v[50:53]
	v_mfma_i32_16x16x64_i8 v[50:53], v[154:157], v[178:181], 0
	v_mfma_i32_16x16x64_i8 v[2:5], v[158:161], v[174:177], v[2:5]
	v_mfma_i32_16x16x64_i8 v[10:13], v[134:137], v[174:177], v[10:13]
	v_mfma_i32_16x16x64_i8 v[38:41], v[158:161], v[166:169], v[38:41]
	v_mfma_i32_16x16x64_i8 v[34:37], v[134:137], v[166:169], v[34:37]
	v_mfma_i32_16x16x64_i8 v[74:77], v[158:161], v[182:185], v[50:53]
	v_mfma_i32_16x16x64_i8 v[50:53], v[130:133], v[186:189], 0
	v_mfma_i32_16x16x64_i8 v[122:125], v[134:137], v[190:193], v[50:53]
	v_mfma_i32_16x16x64_i8 v[50:53], v[154:157], v[186:189], 0
	v_mfma_i32_16x16x64_i8 v[70:73], v[158:161], v[190:193], v[50:53]
	s_setprio 0
	s_barrier
; #define PG8_STAGE(bufoff, gbase, voff) do { _Pragma("unroll") for (int _i = 0; _i < 2; ++_i) \
;         __builtin_amdgcn_global_load_lds((const unsigned*)((const char*)(gbase) + (voff)[_i]), (PG8_LAS unsigned*)(lds + (bufoff) + ldsw + _i * 8192), 16, 0, 0); } while (0)
; #define PG8_LDA(dst, b, h) do { _Pragma("unroll") for (int m = 0; m < 4; ++m) _Pragma("unroll") for (int k = 0; k < 2; ++k) dst[m][k] = *(const PG8_LAS bf16x8*)(lds + PG8_SA(b, h) + aoff + m * 2048 + k * 1024); } while (0)
; #define PG8_LDB(dst, b, h) do { _Pragma("unroll") for (int n = 0; n < 2; ++n) _Pragma("unroll") for (int k = 0; k < 2; ++k) dst[n][k] = *(const PG8_LAS bf16x8*)(lds + PG8_SB(b, h) + boff + n * 2048 + k * 1024); } while (0)
; #define PG8_MMA(ai, bj, At, Bt) do { __builtin_amdgcn_s_setprio(1); _Pragma("unroll") for (int m = 0; m < 4; ++m) _Pragma("unroll") for (int n = 0; n < 2; ++n) _Pragma("unroll") for (int k = 0; k < 2; ++k) \
;         acc[ai][bj][m][n] = mma16<Epi::I8>(Bt[n][k], At[m][k], acc[ai][bj][m][n]); __builtin_amdgcn_s_setprio(0); } while (0)
; #define PG8_WAIT_V(n) asm volatile("s_waitcnt vmcnt(" #n ")" ::: "memory")
; #define PG8_WAIT_L(n) asm volatile("s_waitcnt lgkmcnt(" #n ")" ::: "memory")
; #define PG8_BAR __builtin_amdgcn_s_barrier()
; #define PG8_SCHED __builtin_amdgcn_sched_barrier(0)
; template <class Epi, class Sched, bool ALIGN_EPI = false, bool SP2 = false>
; __device__ __forceinline__ void gemm_phase(PG8_LAS unsigned char* lds, const Gemm g, const Sched& S, const Epi& E) {
;     ...
;         for (int t = 0; t < nt; t += 2) {
;     ...
;             PG8_LDB(B0, 1, 0); PG8_LDB(B1, 1, 1); PG8_SCHED; PG8_LDA(At, 1, 0); PG8_STAGE(PG8_SA(0, 1), a2 + hstep, voffA);
;             PG8_WAIT_V(8); PG8_WAIT_L(0); PG8_BAR; PG8_MMA(0, 0, At, B0); PG8_MMA(0, 1, At, B1); PG8_BAR; PG8_SCHED;
;             PG8_LDA(At, 1, 1); PG8_STAGE(PG8_SB(1, 0), b3, voffB); PG8_STAGE(PG8_SB(1, 1), b3 + hstep, voffB); PG8_STAGE(PG8_SA(1, 0), a3, voffA);
;             PG8_WAIT_V(8); PG8_WAIT_L(0); PG8_BAR; PG8_MMA(1, 0, At, B0); PG8_MMA(1, 1, At, B1); PG8_BAR; PG8_SCHED;
	s_add_i32 s4, 0, 0x18000
	v_add_u32_e32 v126, s4, v242
	s_add_i32 s5, 0, 0x1c000
	ds_read_b128 v[50:53], v126
	ds_read_b128 v[66:69], v126 offset:1024
	ds_read_b128 v[114:117], v126 offset:2048
	ds_read_b128 v[130:133], v126 offset:3072
	v_add_u32_e32 v126, s5, v242
	ds_read_b128 v[134:137], v126
	ds_read_b128 v[154:157], v126 offset:1024
	ds_read_b128 v[158:161], v126 offset:2048
	ds_read_b128 v[162:165], v126 offset:3072
	s_add_u32 s0, s12, 0x40000
	s_addc_u32 s1, s13, 0
	s_mov_b32 m0, s80
	ds_read_b128 v[126:129], v243 offset:32768
	ds_read_b128 v[166:169], v243 offset:33792
	ds_read_b128 v[170:173], v243 offset:34816
	ds_read_b128 v[174:177], v243 offset:35840
	ds_read_b128 v[178:181], v243 offset:36864
	ds_read_b128 v[182:185], v243 offset:37888
	ds_read_b128 v[186:189], v243 offset:38912
	ds_read_b128 v[190:193], v243 offset:39936
	global_load_lds_dwordx4 v210, s[0:1]
	s_mov_b32 m0, s81
	s_nop 0
	global_load_lds_dwordx4 v212, s[0:1]
	s_waitcnt vmcnt(8)
	s_waitcnt lgkmcnt(0)
	s_barrier
	s_setprio 1
	s_waitcnt lgkmcnt(0)
	v_mfma_i32_16x16x64_i8 v[150:153], v[50:53], v[126:129], v[150:153]
	v_mfma_i32_16x16x64_i8 v[146:149], v[114:117], v[126:129], v[146:149]
	v_mfma_i32_16x16x64_i8 v[110:113], v[114:117], v[170:173], v[110:113]
	v_mfma_i32_16x16x64_i8 v[118:121], v[50:53], v[170:173], v[118:121]
	v_mfma_i32_16x16x64_i8 v[54:57], v[50:53], v[178:181], v[54:57]
	v_mfma_i32_16x16x64_i8 v[30:33], v[114:117], v[178:181], v[30:33]
	v_mfma_i32_16x16x64_i8 v[58:61], v[114:117], v[186:189], v[58:61]
	v_mfma_i32_16x16x64_i8 v[94:97], v[50:53], v[186:189], v[94:97]
	v_mfma_i32_16x16x64_i8 v[150:153], v[66:69], v[166:169], v[150:153]
	v_mfma_i32_16x16x64_i8 v[146:149], v[130:133], v[166:169], v[146:149]
	v_mfma_i32_16x16x64_i8 v[110:113], v[130:133], v[174:177], v[110:113]
	v_mfma_i32_16x16x64_i8 v[118:121], v[66:69], v[174:177], v[118:121]
	v_mfma_i32_16x16x64_i8 v[54:57], v[66:69], v[182:185], v[54:57]
	v_mfma_i32_16x16x64_i8 v[30:33], v[130:133], v[182:185], v[30:33]
	v_mfma_i32_16x16x64_i8 v[58:61], v[130:133], v[190:193], v[58:61]
	v_mfma_i32_16x16x64_i8 v[94:97], v[66:69], v[190:193], v[94:97]
	s_setprio 0
	s_setprio 1
	v_mfma_i32_16x16x64_i8 v[142:145], v[134:137], v[126:129], v[142:145]
	v_mfma_i32_16x16x64_i8 v[126:129], v[158:161], v[126:129], v[138:141]
	v_mfma_i32_16x16x64_i8 v[98:101], v[158:161], v[170:173], v[98:101]
	v_mfma_i32_16x16x64_i8 v[102:105], v[134:137], v[170:173], v[102:105]
	v_mfma_i32_16x16x64_i8 v[42:45], v[134:137], v[178:181], v[42:45]
	v_mfma_i32_16x16x64_i8 v[26:29], v[158:161], v[178:181], v[26:29]
	v_mfma_i32_16x16x64_i8 v[62:65], v[158:161], v[186:189], v[62:65]
	v_mfma_i32_16x16x64_i8 v[78:81], v[134:137], v[186:189], v[78:81]
	v_mfma_i32_16x16x64_i8 v[142:145], v[154:157], v[166:169], v[142:145]
	v_mfma_i32_16x16x64_i8 v[138:141], v[162:165], v[166:169], v[126:129]
	v_mfma_i32_16x16x64_i8 v[98:101], v[162:165], v[174:177], v[98:101]
	v_mfma_i32_16x16x64_i8 v[102:105], v[154:157], v[174:177], v[102:105]
	v_mfma_i32_16x16x64_i8 v[42:45], v[154:157], v[182:185], v[42:45]
	v_mfma_i32_16x16x64_i8 v[26:29], v[162:165], v[182:185], v[26:29]
	v_mfma_i32_16x16x64_i8 v[62:65], v[162:165], v[190:193], v[62:65]
	v_mfma_i32_16x16x64_i8 v[78:81], v[154:157], v[190:193], v[78:81]
	s_setprio 0
	s_barrier
	s_add_i32 s0, s4, s69
	v_lshl_add_u64 v[126:127], v[198:199], 0, s[92:93]
	s_mov_b32 m0, s0
	ds_read_b128 v[166:169], v243 offset:49152
	ds_read_b128 v[170:173], v243 offset:50176
	ds_read_b128 v[174:177], v243 offset:51200
	ds_read_b128 v[178:181], v243 offset:52224
	ds_read_b128 v[182:185], v243 offset:53248
	ds_read_b128 v[186:189], v243 offset:54272
	ds_read_b128 v[190:193], v243 offset:55296
	ds_read_b128 v[194:197], v243 offset:56320
	global_load_lds_dwordx4 v[126:127], off
	s_add_i32 m0, s0, 0x2000
	s_add_u32 s0, s6, 0x40080
	v_lshl_add_u64 v[126:127], v[200:201], 0, s[92:93]
	s_addc_u32 s1, s7, 0
	s_add_i32 s4, s5, s69
	global_load_lds_dwordx4 v[126:127], off
	s_mov_b32 m0, s4
	s_nop 0
	global_load_lds_dwordx4 v0, s[0:1]
	s_add_i32 m0, s4, 0x2000
	s_nop 0
	global_load_lds_dwordx4 v214, s[0:1]
	v_lshl_add_u64 v[126:127], v[206:207], 0, s[92:93]
	s_mov_b32 m0, s84
	s_nop 0
	global_load_lds_dwordx4 v[126:127], off
	v_lshl_add_u64 v[126:127], v[220:221], 0, s[92:93]
	s_mov_b32 m0, s85
	s_nop 0
	global_load_lds_dwordx4 v[126:127], off
	s_waitcnt vmcnt(8)
	s_waitcnt lgkmcnt(0)
	s_barrier
	s_setprio 1
	s_waitcnt lgkmcnt(0)
	v_mfma_i32_16x16x64_i8 v[18:21], v[50:53], v[190:193], v[18:21]
	v_mfma_i32_16x16x64_i8 v[106:109], v[50:53], v[166:169], v[106:109]
	v_mfma_i32_16x16x64_i8 v[46:49], v[114:117], v[166:169], v[46:49]
	v_mfma_i32_16x16x64_i8 v[6:9], v[114:117], v[174:177], v[6:9]
	v_mfma_i32_16x16x64_i8 v[14:17], v[50:53], v[174:177], v[14:17]
	v_mfma_i32_16x16x64_i8 v[90:93], v[50:53], v[182:185], v[90:93]
	v_mfma_i32_16x16x64_i8 v[86:89], v[114:117], v[182:185], v[86:89]
	v_mfma_i32_16x16x64_i8 v[126:129], v[66:69], v[194:197], v[18:21]
	v_mfma_i32_16x16x64_i8 v[106:109], v[66:69], v[170:173], v[106:109]
	v_mfma_i32_16x16x64_i8 v[46:49], v[130:133], v[170:173], v[46:49]
	v_mfma_i32_16x16x64_i8 v[6:9], v[130:133], v[178:181], v[6:9]
	v_mfma_i32_16x16x64_i8 v[14:17], v[66:69], v[178:181], v[14:17]
	v_mfma_i32_16x16x64_i8 v[90:93], v[66:69], v[186:189], v[90:93]
	v_mfma_i32_16x16x64_i8 v[86:89], v[130:133], v[186:189], v[86:89]
	v_mfma_i32_16x16x64_i8 v[18:21], v[114:117], v[190:193], v[22:25]
	v_mfma_i32_16x16x64_i8 v[66:69], v[130:133], v[194:197], v[18:21]
	s_setprio 0
	s_setprio 1
	v_mfma_i32_16x16x64_i8 v[18:21], v[134:137], v[166:169], v[34:37]
	v_mfma_i32_16x16x64_i8 v[10:13], v[134:137], v[174:177], v[10:13]
	v_mfma_i32_16x16x64_i8 v[2:5], v[158:161], v[174:177], v[2:5]
	v_mfma_i32_16x16x64_i8 v[114:117], v[154:157], v[170:173], v[18:21]
	v_mfma_i32_16x16x64_i8 v[18:21], v[158:161], v[166:169], v[38:41]
	v_mfma_i32_16x16x64_i8 v[50:53], v[162:165], v[170:173], v[18:21]
	v_mfma_i32_16x16x64_i8 v[18:21], v[134:137], v[182:185], v[82:85]
	v_mfma_i32_16x16x64_i8 v[10:13], v[154:157], v[178:181], v[10:13]
	v_mfma_i32_16x16x64_i8 v[2:5], v[162:165], v[178:181], v[2:5]
	v_mfma_i32_16x16x64_i8 v[82:85], v[154:157], v[186:189], v[18:21]
	v_mfma_i32_16x16x64_i8 v[18:21], v[158:161], v[182:185], v[74:77]
	v_mfma_i32_16x16x64_i8 v[74:77], v[162:165], v[186:189], v[18:21]
	v_mfma_i32_16x16x64_i8 v[18:21], v[134:137], v[190:193], v[122:125]
	v_mfma_i32_16x16x64_i8 v[122:125], v[154:157], v[194:197], v[18:21]
	v_mfma_i32_16x16x64_i8 v[18:21], v[158:161], v[190:193], v[70:73]
	v_mfma_i32_16x16x64_i8 v[70:73], v[162:165], v[194:197], v[18:21]
	s_setprio 0
	s_barrier
	s_add_i32 vcc_lo, vcc_lo, 2
	s_add_u32 s96, s96, 0x100
	s_addc_u32 s97, s97, 0
	s_cmp_gt_u32 vcc_lo, 13
	s_mov_b64 s[0:1], s[8:9]
	s_cbranch_scc0 .LBB0_80
	s_branch .Lpeelx80
; #define PG8_STAGE(bufoff, gbase, voff) do { _Pragma("unroll") for (int _i = 0; _i < 2; ++_i) \
;         __builtin_amdgcn_global_load_lds((const unsigned*)((const char*)(gbase) + (voff)[_i]), (PG8_LAS unsigned*)(lds + (bufoff) + ldsw + _i * 8192), 16, 0, 0); } while (0)
; #define PG8_LDA(dst, b, h) do { _Pragma("unroll") for (int m = 0; m < 4; ++m) _Pragma("unroll") for (int k = 0; k < 2; ++k) dst[m][k] = *(const PG8_LAS bf16x8*)(lds + PG8_SA(b, h) + aoff + m * 2048 + k * 1024); } while (0)
; #define PG8_LDB(dst, b, h) do { _Pragma("unroll") for (int n = 0; n < 2; ++n) _Pragma("unroll") for (int k = 0; k < 2; ++k) dst[n][k] = *(const PG8_LAS bf16x8*)(lds + PG8_SB(b, h) + boff + n * 2048 + k * 1024); } while (0)
; #define PG8_MMA(ai, bj, At, Bt) do { __builtin_amdgcn_s_setprio(1); _Pragma("unroll") for (int m = 0; m < 4; ++m) _Pragma("unroll") for (int n = 0; n < 2; ++n) _Pragma("unroll") for (int k = 0; k < 2; ++k) \
;         acc[ai][bj][m][n] = mma16<Epi::I8>(Bt[n][k], At[m][k], acc[ai][bj][m][n]); __builtin_amdgcn_s_setprio(0); } while (0)
; #define PG8_WAIT_V(n) asm volatile("s_waitcnt vmcnt(" #n ")" ::: "memory")
; #define PG8_WAIT_L(n) asm volatile("s_waitcnt lgkmcnt(" #n ")" ::: "memory")
; template <class Epi, class Sched, bool ALIGN_EPI = false, bool SP2 = false>
; __device__ __forceinline__ void gemm_phase(PG8_LAS unsigned char* lds, const Gemm g, const Sched& S, const Epi& E) {
;     ...
;         for (int t = 0; t < nt; t += 2) {
;             const bool last = (t == nt - 2);
;             const char* a1 = cA + (size_t)(t + 1) * kstep;
;             const char* a2 = last ? nA : cA + (size_t)(t + 2) * kstep; const char* b2 = last ? nB : cB + (size_t)(t + 2) * kstep;
;             const char* a3 = a2 + kstep; const char* b3 = b2 + kstep;
;             if (last && has_next) S.a_ready(nxt);
;             if constexpr (SP2) {
;             PG8_LDB(B0, 0, 0); PG8_LDB(B1, 0, 1); PG8_SCHED; PG8_LDA(At, 0, 0); PG8_STAGE(PG8_SA(1, 1), a1 + hstep, voffA);
;             PG8_WAIT_V(8); PG8_WAIT_L(0); PG8_BAR; PG8_MMA(0, 0, At, B0); PG8_MMA(0, 1, At, B1); PG8_BAR; PG8_SCHED;
;             PG8_LDA(At, 0, 1); PG8_STAGE(PG8_SB(0, 0), b2, voffB); PG8_STAGE(PG8_SB(0, 1), b2 + hstep, voffB); PG8_STAGE(PG8_SA(0, 0), a2, voffA);
;             PG8_WAIT_V(8); PG8_WAIT_L(0); PG8_BAR; PG8_MMA(1, 0, At, B0); PG8_MMA(1, 1, At, B1); PG8_BAR; PG8_SCHED;
.LBB0_80:
	s_add_u32 s8, s0, 0x100
	s_addc_u32 s9, s1, 0
	s_add_i32 vcc_hi, 0, 0x10000
	s_cmp_eq_u32 vcc_lo, 12
	s_cselect_b32 s13, s66, s9
	s_cselect_b32 s12, s67, s8
	s_cselect_b32 s7, s82, s97
	s_cselect_b32 s6, s83, s96
	s_add_i32 s4, 0, 0x14000
	v_add_u32_e32 v38, vcc_hi, v242
	v_add_u32_e32 v158, s4, v242
	ds_read_b128 v[18:21], v38
	ds_read_b128 v[22:25], v38 offset:1024
	ds_read_b128 v[34:37], v38 offset:2048
	ds_read_b128 v[38:41], v38 offset:3072
	ds_read_b128 v[130:133], v158
	ds_read_b128 v[134:137], v158 offset:1024
	ds_read_b128 v[154:157], v158 offset:2048
	ds_read_b128 v[158:161], v158 offset:3072
	s_add_i32 m0, s11, 0xc000
	ds_read_b128 v[162:165], v243
	ds_read_b128 v[166:169], v243 offset:1024
	ds_read_b128 v[170:173], v243 offset:2048
	ds_read_b128 v[174:177], v243 offset:3072
	ds_read_b128 v[178:181], v243 offset:4096
	ds_read_b128 v[182:185], v243 offset:5120
	ds_read_b128 v[186:189], v243 offset:6144
	ds_read_b128 v[190:193], v243 offset:7168
	global_load_lds_dwordx4 v216, s[0:1]
	s_add_i32 m0, s11, 0xe000
	s_nop 0
	global_load_lds_dwordx4 v218, s[0:1]
	s_waitcnt vmcnt(8)
	s_waitcnt lgkmcnt(0)
	s_barrier
	s_setprio 1
	s_waitcnt lgkmcnt(0)
	v_mfma_i32_16x16x64_i8 v[150:153], v[18:21], v[162:165], v[150:153]
	v_mfma_i32_16x16x64_i8 v[146:149], v[34:37], v[162:165], v[146:149]
	v_mfma_i32_16x16x64_i8 v[110:113], v[34:37], v[170:173], v[110:113]
	v_mfma_i32_16x16x64_i8 v[118:121], v[18:21], v[170:173], v[118:121]
	v_mfma_i32_16x16x64_i8 v[54:57], v[18:21], v[178:181], v[54:57]
	v_mfma_i32_16x16x64_i8 v[30:33], v[34:37], v[178:181], v[30:33]
	v_mfma_i32_16x16x64_i8 v[58:61], v[34:37], v[186:189], v[58:61]
	v_mfma_i32_16x16x64_i8 v[94:97], v[18:21], v[186:189], v[94:97]
	v_mfma_i32_16x16x64_i8 v[150:153], v[22:25], v[166:169], v[150:153]
	v_mfma_i32_16x16x64_i8 v[146:149], v[38:41], v[166:169], v[146:149]
	v_mfma_i32_16x16x64_i8 v[110:113], v[38:41], v[174:177], v[110:113]
	v_mfma_i32_16x16x64_i8 v[118:121], v[22:25], v[174:177], v[118:121]
	v_mfma_i32_16x16x64_i8 v[54:57], v[22:25], v[182:185], v[54:57]
	v_mfma_i32_16x16x64_i8 v[30:33], v[38:41], v[182:185], v[30:33]
	v_mfma_i32_16x16x64_i8 v[58:61], v[38:41], v[190:193], v[58:61]
	v_mfma_i32_16x16x64_i8 v[94:97], v[22:25], v[190:193], v[94:97]
	s_setprio 0
	s_setprio 1
	v_mfma_i32_16x16x64_i8 v[142:145], v[130:133], v[162:165], v[142:145]
	v_mfma_i32_16x16x64_i8 v[138:141], v[154:157], v[162:165], v[138:141]
	v_mfma_i32_16x16x64_i8 v[98:101], v[154:157], v[170:173], v[98:101]
	v_mfma_i32_16x16x64_i8 v[102:105], v[130:133], v[170:173], v[102:105]
	v_mfma_i32_16x16x64_i8 v[42:45], v[130:133], v[178:181], v[42:45]
	v_mfma_i32_16x16x64_i8 v[26:29], v[154:157], v[178:181], v[26:29]
	v_mfma_i32_16x16x64_i8 v[62:65], v[154:157], v[186:189], v[62:65]
	v_mfma_i32_16x16x64_i8 v[78:81], v[130:133], v[186:189], v[78:81]
	v_mfma_i32_16x16x64_i8 v[142:145], v[134:137], v[166:169], v[142:145]
	v_mfma_i32_16x16x64_i8 v[138:141], v[158:161], v[166:169], v[138:141]
	v_mfma_i32_16x16x64_i8 v[98:101], v[158:161], v[174:177], v[98:101]
	v_mfma_i32_16x16x64_i8 v[102:105], v[134:137], v[174:177], v[102:105]
	v_mfma_i32_16x16x64_i8 v[42:45], v[134:137], v[182:185], v[42:45]
	v_mfma_i32_16x16x64_i8 v[26:29], v[158:161], v[182:185], v[26:29]
	v_mfma_i32_16x16x64_i8 v[62:65], v[158:161], v[190:193], v[62:65]
	v_mfma_i32_16x16x64_i8 v[78:81], v[134:137], v[190:193], v[78:81]
	s_setprio 0
	s_barrier
	s_add_i32 s0, vcc_hi, s69
	v_lshl_add_u64 v[198:199], s[6:7], 0, v[0:1]
	s_mov_b32 m0, s0
	ds_read_b128 v[162:165], v243 offset:16384
	ds_read_b128 v[166:169], v243 offset:17408
	ds_read_b128 v[170:173], v243 offset:18432
	ds_read_b128 v[174:177], v243 offset:19456
	ds_read_b128 v[178:181], v243 offset:20480
	ds_read_b128 v[182:185], v243 offset:21504
	ds_read_b128 v[186:189], v243 offset:22528
	ds_read_b128 v[190:193], v243 offset:23552
	global_load_lds_dwordx4 v[198:199], off
	s_add_i32 m0, s0, 0x2000
	s_add_u32 s0, s6, 0x40000
	v_lshl_add_u64 v[200:201], s[6:7], 0, v[214:215]
	s_addc_u32 s1, s7, 0
	s_add_i32 s4, s4, s69
	global_load_lds_dwordx4 v[200:201], off
	s_mov_b32 m0, s4
	v_lshl_add_u64 v[206:207], s[12:13], 0, v[210:211]
	global_load_lds_dwordx4 v0, s[0:1]
	s_add_i32 m0, s4, 0x2000
	v_lshl_add_u64 v[220:221], s[12:13], 0, v[212:213]
	global_load_lds_dwordx4 v214, s[0:1]
	s_mov_b32 m0, s11
	s_nop 0
	global_load_lds_dwordx4 v[206:207], off
	s_mov_b32 m0, s71
	s_nop 0
	global_load_lds_dwordx4 v[220:221], off
	s_waitcnt vmcnt(8)
	s_waitcnt lgkmcnt(0)
	s_barrier
	s_setprio 1
	s_waitcnt lgkmcnt(0)
	v_mfma_i32_16x16x64_i8 v[106:109], v[18:21], v[162:165], v[106:109]
	v_mfma_i32_16x16x64_i8 v[46:49], v[34:37], v[162:165], v[46:49]
	v_mfma_i32_16x16x64_i8 v[6:9], v[34:37], v[170:173], v[6:9]
	v_mfma_i32_16x16x64_i8 v[14:17], v[18:21], v[170:173], v[14:17]
	v_mfma_i32_16x16x64_i8 v[90:93], v[18:21], v[178:181], v[90:93]
	v_mfma_i32_16x16x64_i8 v[86:89], v[34:37], v[178:181], v[86:89]
	v_mfma_i32_16x16x64_i8 v[18:21], v[18:21], v[186:189], v[126:129]
	v_mfma_i32_16x16x64_i8 v[106:109], v[22:25], v[166:169], v[106:109]
	v_mfma_i32_16x16x64_i8 v[46:49], v[38:41], v[166:169], v[46:49]
	v_mfma_i32_16x16x64_i8 v[6:9], v[38:41], v[174:177], v[6:9]
	v_mfma_i32_16x16x64_i8 v[14:17], v[22:25], v[174:177], v[14:17]
	v_mfma_i32_16x16x64_i8 v[90:93], v[22:25], v[182:185], v[90:93]
	v_mfma_i32_16x16x64_i8 v[86:89], v[38:41], v[182:185], v[86:89]
	v_mfma_i32_16x16x64_i8 v[18:21], v[22:25], v[190:193], v[18:21]
	v_mfma_i32_16x16x64_i8 v[22:25], v[34:37], v[186:189], v[66:69]
	v_mfma_i32_16x16x64_i8 v[22:25], v[38:41], v[190:193], v[22:25]
	s_setprio 0
	s_setprio 1
	v_mfma_i32_16x16x64_i8 v[38:41], v[154:157], v[162:165], v[50:53]
	v_mfma_i32_16x16x64_i8 v[2:5], v[154:157], v[170:173], v[2:5]
	v_mfma_i32_16x16x64_i8 v[10:13], v[130:133], v[170:173], v[10:13]
	v_mfma_i32_16x16x64_i8 v[50:53], v[130:133], v[178:181], v[82:85]
	v_mfma_i32_16x16x64_i8 v[34:37], v[130:133], v[162:165], v[114:117]
	v_mfma_i32_16x16x64_i8 v[82:85], v[134:137], v[182:185], v[50:53]
	v_mfma_i32_16x16x64_i8 v[50:53], v[154:157], v[178:181], v[74:77]
	v_mfma_i32_16x16x64_i8 v[2:5], v[158:161], v[174:177], v[2:5]
	v_mfma_i32_16x16x64_i8 v[10:13], v[134:137], v[174:177], v[10:13]
	v_mfma_i32_16x16x64_i8 v[38:41], v[158:161], v[166:169], v[38:41]
	v_mfma_i32_16x16x64_i8 v[34:37], v[134:137], v[166:169], v[34:37]
	v_mfma_i32_16x16x64_i8 v[74:77], v[158:161], v[182:185], v[50:53]
	v_mfma_i32_16x16x64_i8 v[50:53], v[130:133], v[186:189], v[122:125]
	v_mfma_i32_16x16x64_i8 v[122:125], v[134:137], v[190:193], v[50:53]
	v_mfma_i32_16x16x64_i8 v[50:53], v[154:157], v[186:189], v[70:73]
	v_mfma_i32_16x16x64_i8 v[70:73], v[158:161], v[190:193], v[50:53]
	s_setprio 0
	s_barrier
; #define PG8_STAGE(bufoff, gbase, voff) do { _Pragma("unroll") for (int _i = 0; _i < 2; ++_i) \
;         __builtin_amdgcn_global_load_lds((const unsigned*)((const char*)(gbase) + (voff)[_i]), (PG8_LAS unsigned*)(lds + (bufoff) + ldsw + _i * 8192), 16, 0, 0); } while (0)
; #define PG8_LDA(dst, b, h) do { _Pragma("unroll") for (int m = 0; m < 4; ++m) _Pragma("unroll") for (int k = 0; k < 2; ++k) dst[m][k] = *(const PG8_LAS bf16x8*)(lds + PG8_SA(b, h) + aoff + m * 2048 + k * 1024); } while (0)
; #define PG8_LDB(dst, b, h) do { _Pragma("unroll") for (int n = 0; n < 2; ++n) _Pragma("unroll") for (int k = 0; k < 2; ++k) dst[n][k] = *(const PG8_LAS bf16x8*)(lds + PG8_SB(b, h) + boff + n * 2048 + k * 1024); } while (0)
; #define PG8_MMA(ai, bj, At, Bt) do { __builtin_amdgcn_s_setprio(1); _Pragma("unroll") for (int m = 0; m < 4; ++m) _Pragma("unroll") for (int n = 0; n < 2; ++n) _Pragma("unroll") for (int k = 0; k < 2; ++k) \
;         acc[ai][bj][m][n] = mma16<Epi::I8>(Bt[n][k], At[m][k], acc[ai][bj][m][n]); __builtin_amdgcn_s_setprio(0); } while (0)
; #define PG8_WAIT_V(n) asm volatile("s_waitcnt vmcnt(" #n ")" ::: "memory")
; #define PG8_WAIT_L(n) asm volatile("s_waitcnt lgkmcnt(" #n ")" ::: "memory")
; #define PG8_BAR __builtin_amdgcn_s_barrier()
; #define PG8_SCHED __builtin_amdgcn_sched_barrier(0)
; template <class Epi, class Sched, bool ALIGN_EPI = false, bool SP2 = false>
; __device__ __forceinline__ void gemm_phase(PG8_LAS unsigned char* lds, const Gemm g, const Sched& S, const Epi& E) {
;     ...
;         for (int t = 0; t < nt; t += 2) {
;     ...
;             PG8_LDB(B0, 1, 0); PG8_LDB(B1, 1, 1); PG8_SCHED; PG8_LDA(At, 1, 0); PG8_STAGE(PG8_SA(0, 1), a2 + hstep, voffA);
;             PG8_WAIT_V(8); PG8_WAIT_L(0); PG8_BAR; PG8_MMA(0, 0, At, B0); PG8_MMA(0, 1, At, B1); PG8_BAR; PG8_SCHED;
;             PG8_LDA(At, 1, 1); PG8_STAGE(PG8_SB(1, 0), b3, voffB); PG8_STAGE(PG8_SB(1, 1), b3 + hstep, voffB); PG8_STAGE(PG8_SA(1, 0), a3, voffA);
;             PG8_WAIT_V(8); PG8_WAIT_L(0); PG8_BAR; PG8_MMA(1, 0, At, B0); PG8_MMA(1, 1, At, B1); PG8_BAR; PG8_SCHED;
	s_add_i32 s4, 0, 0x18000
	v_add_u32_e32 v126, s4, v242
	s_add_i32 s5, 0, 0x1c000
	ds_read_b128 v[50:53], v126
	ds_read_b128 v[66:69], v126 offset:1024
	ds_read_b128 v[114:117], v126 offset:2048
	ds_read_b128 v[130:133], v126 offset:3072
	v_add_u32_e32 v126, s5, v242
	ds_read_b128 v[134:137], v126
	ds_read_b128 v[154:157], v126 offset:1024
	ds_read_b128 v[158:161], v126 offset:2048
	ds_read_b128 v[162:165], v126 offset:3072
	s_add_u32 s0, s12, 0x40000
	s_addc_u32 s1, s13, 0
	s_mov_b32 m0, s80
	ds_read_b128 v[126:129], v243 offset:32768
	ds_read_b128 v[166:169], v243 offset:33792
	ds_read_b128 v[170:173], v243 offset:34816
	ds_read_b128 v[174:177], v243 offset:35840
	ds_read_b128 v[178:181], v243 offset:36864
	ds_read_b128 v[182:185], v243 offset:37888
	ds_read_b128 v[186:189], v243 offset:38912
	ds_read_b128 v[190:193], v243 offset:39936
	global_load_lds_dwordx4 v210, s[0:1]
	s_mov_b32 m0, s81
	s_nop 0
	global_load_lds_dwordx4 v212, s[0:1]
	s_waitcnt vmcnt(8)
	s_waitcnt lgkmcnt(0)
	s_barrier
	s_setprio 1
	s_waitcnt lgkmcnt(0)
	v_mfma_i32_16x16x64_i8 v[150:153], v[50:53], v[126:129], v[150:153]
	v_mfma_i32_16x16x64_i8 v[146:149], v[114:117], v[126:129], v[146:149]
	v_mfma_i32_16x16x64_i8 v[110:113], v[114:117], v[170:173], v[110:113]
	v_mfma_i32_16x16x64_i8 v[118:121], v[50:53], v[170:173], v[118:121]
	v_mfma_i32_16x16x64_i8 v[54:57], v[50:53], v[178:181], v[54:57]
	v_mfma_i32_16x16x64_i8 v[30:33], v[114:117], v[178:181], v[30:33]
	v_mfma_i32_16x16x64_i8 v[58:61], v[114:117], v[186:189], v[58:61]
	v_mfma_i32_16x16x64_i8 v[94:97], v[50:53], v[186:189], v[94:97]
	v_mfma_i32_16x16x64_i8 v[150:153], v[66:69], v[166:169], v[150:153]
	v_mfma_i32_16x16x64_i8 v[146:149], v[130:133], v[166:169], v[146:149]
	v_mfma_i32_16x16x64_i8 v[110:113], v[130:133], v[174:177], v[110:113]
	v_mfma_i32_16x16x64_i8 v[118:121], v[66:69], v[174:177], v[118:121]
	v_mfma_i32_16x16x64_i8 v[54:57], v[66:69], v[182:185], v[54:57]
	v_mfma_i32_16x16x64_i8 v[30:33], v[130:133], v[182:185], v[30:33]
	v_mfma_i32_16x16x64_i8 v[58:61], v[130:133], v[190:193], v[58:61]
	v_mfma_i32_16x16x64_i8 v[94:97], v[66:69], v[190:193], v[94:97]
	s_setprio 0
	s_setprio 1
	v_mfma_i32_16x16x64_i8 v[142:145], v[134:137], v[126:129], v[142:145]
	v_mfma_i32_16x16x64_i8 v[126:129], v[158:161], v[126:129], v[138:141]
	v_mfma_i32_16x16x64_i8 v[98:101], v[158:161], v[170:173], v[98:101]
	v_mfma_i32_16x16x64_i8 v[102:105], v[134:137], v[170:173], v[102:105]
	v_mfma_i32_16x16x64_i8 v[42:45], v[134:137], v[178:181], v[42:45]
	v_mfma_i32_16x16x64_i8 v[26:29], v[158:161], v[178:181], v[26:29]
	v_mfma_i32_16x16x64_i8 v[62:65], v[158:161], v[186:189], v[62:65]
	v_mfma_i32_16x16x64_i8 v[78:81], v[134:137], v[186:189], v[78:81]
	v_mfma_i32_16x16x64_i8 v[142:145], v[154:157], v[166:169], v[142:145]
	v_mfma_i32_16x16x64_i8 v[138:141], v[162:165], v[166:169], v[126:129]
	v_mfma_i32_16x16x64_i8 v[98:101], v[162:165], v[174:177], v[98:101]
	v_mfma_i32_16x16x64_i8 v[102:105], v[154:157], v[174:177], v[102:105]
	v_mfma_i32_16x16x64_i8 v[42:45], v[154:157], v[182:185], v[42:45]
	v_mfma_i32_16x16x64_i8 v[26:29], v[162:165], v[182:185], v[26:29]
	v_mfma_i32_16x16x64_i8 v[62:65], v[162:165], v[190:193], v[62:65]
	v_mfma_i32_16x16x64_i8 v[78:81], v[154:157], v[190:193], v[78:81]
	s_setprio 0
	s_barrier
	s_add_i32 s0, s4, s69
	v_lshl_add_u64 v[126:127], v[198:199], 0, s[92:93]
	s_mov_b32 m0, s0
	ds_read_b128 v[166:169], v243 offset:49152
	ds_read_b128 v[170:173], v243 offset:50176
	ds_read_b128 v[174:177], v243 offset:51200
	ds_read_b128 v[178:181], v243 offset:52224
	ds_read_b128 v[182:185], v243 offset:53248
	ds_read_b128 v[186:189], v243 offset:54272
	ds_read_b128 v[190:193], v243 offset:55296
	ds_read_b128 v[194:197], v243 offset:56320
	global_load_lds_dwordx4 v[126:127], off
	s_add_i32 m0, s0, 0x2000
	s_add_u32 s0, s6, 0x40080
	v_lshl_add_u64 v[126:127], v[200:201], 0, s[92:93]
	s_addc_u32 s1, s7, 0
	s_add_i32 s4, s5, s69
	global_load_lds_dwordx4 v[126:127], off
	s_mov_b32 m0, s4
	s_nop 0
	global_load_lds_dwordx4 v0, s[0:1]
	s_add_i32 m0, s4, 0x2000
	s_nop 0
	global_load_lds_dwordx4 v214, s[0:1]
	v_lshl_add_u64 v[126:127], v[206:207], 0, s[92:93]
	s_mov_b32 m0, s84
	s_nop 0
	global_load_lds_dwordx4 v[126:127], off
	v_lshl_add_u64 v[126:127], v[220:221], 0, s[92:93]
	s_mov_b32 m0, s85
	s_nop 0
	global_load_lds_dwordx4 v[126:127], off
	s_waitcnt vmcnt(8)
	s_waitcnt lgkmcnt(0)
	s_barrier
	s_setprio 1
	s_waitcnt lgkmcnt(0)
	v_mfma_i32_16x16x64_i8 v[18:21], v[50:53], v[190:193], v[18:21]
	v_mfma_i32_16x16x64_i8 v[106:109], v[50:53], v[166:169], v[106:109]
	v_mfma_i32_16x16x64_i8 v[46:49], v[114:117], v[166:169], v[46:49]
	v_mfma_i32_16x16x64_i8 v[6:9], v[114:117], v[174:177], v[6:9]
	v_mfma_i32_16x16x64_i8 v[14:17], v[50:53], v[174:177], v[14:17]
	v_mfma_i32_16x16x64_i8 v[90:93], v[50:53], v[182:185], v[90:93]
	v_mfma_i32_16x16x64_i8 v[86:89], v[114:117], v[182:185], v[86:89]
	v_mfma_i32_16x16x64_i8 v[126:129], v[66:69], v[194:197], v[18:21]
	v_mfma_i32_16x16x64_i8 v[106:109], v[66:69], v[170:173], v[106:109]
	v_mfma_i32_16x16x64_i8 v[46:49], v[130:133], v[170:173], v[46:49]
	v_mfma_i32_16x16x64_i8 v[6:9], v[130:133], v[178:181], v[6:9]
	v_mfma_i32_16x16x64_i8 v[14:17], v[66:69], v[178:181], v[14:17]
	v_mfma_i32_16x16x64_i8 v[90:93], v[66:69], v[186:189], v[90:93]
	v_mfma_i32_16x16x64_i8 v[86:89], v[130:133], v[186:189], v[86:89]
	v_mfma_i32_16x16x64_i8 v[18:21], v[114:117], v[190:193], v[22:25]
	v_mfma_i32_16x16x64_i8 v[66:69], v[130:133], v[194:197], v[18:21]
	s_setprio 0
	s_setprio 1
	v_mfma_i32_16x16x64_i8 v[18:21], v[134:137], v[166:169], v[34:37]
	v_mfma_i32_16x16x64_i8 v[10:13], v[134:137], v[174:177], v[10:13]
	v_mfma_i32_16x16x64_i8 v[2:5], v[158:161], v[174:177], v[2:5]
	v_mfma_i32_16x16x64_i8 v[114:117], v[154:157], v[170:173], v[18:21]
	v_mfma_i32_16x16x64_i8 v[18:21], v[158:161], v[166:169], v[38:41]
	v_mfma_i32_16x16x64_i8 v[50:53], v[162:165], v[170:173], v[18:21]
	v_mfma_i32_16x16x64_i8 v[18:21], v[134:137], v[182:185], v[82:85]
	v_mfma_i32_16x16x64_i8 v[10:13], v[154:157], v[178:181], v[10:13]
	v_mfma_i32_16x16x64_i8 v[2:5], v[162:165], v[178:181], v[2:5]
	v_mfma_i32_16x16x64_i8 v[82:85], v[154:157], v[186:189], v[18:21]
	v_mfma_i32_16x16x64_i8 v[18:21], v[158:161], v[182:185], v[74:77]
	v_mfma_i32_16x16x64_i8 v[74:77], v[162:165], v[186:189], v[18:21]
	v_mfma_i32_16x16x64_i8 v[18:21], v[134:137], v[190:193], v[122:125]
	v_mfma_i32_16x16x64_i8 v[122:125], v[154:157], v[194:197], v[18:21]
	v_mfma_i32_16x16x64_i8 v[18:21], v[158:161], v[190:193], v[70:73]
	v_mfma_i32_16x16x64_i8 v[70:73], v[162:165], v[194:197], v[18:21]
	s_setprio 0
	s_barrier
	s_add_i32 vcc_lo, vcc_lo, 2
	s_add_u32 s96, s96, 0x100
	s_addc_u32 s97, s97, 0
	s_cmp_gt_u32 vcc_lo, 13
	s_mov_b64 s[0:1], s[8:9]
	s_cbranch_scc0 .LBB0_80

; #define PG8_STAGE(bufoff, gbase, voff) do { _Pragma("unroll") for (int _i = 0; _i < 2; ++_i) \
;         __builtin_amdgcn_global_load_lds((const unsigned*)((const char*)(gbase) + (voff)[_i]), (PG8_LAS unsigned*)(lds + (bufoff) + ldsw + _i * 8192), 16, 0, 0); } while (0)
; #define PG8_LDA(dst, b, h) do { _Pragma("unroll") for (int m = 0; m < 4; ++m) _Pragma("unroll") for (int k = 0; k < 2; ++k) dst[m][k] = *(const PG8_LAS bf16x8*)(lds + PG8_SA(b, h) + aoff + m * 2048 + k * 1024); } while (0)
; #define PG8_LDB(dst, b, h) do { _Pragma("unroll") for (int n = 0; n < 2; ++n) _Pragma("unroll") for (int k = 0; k < 2; ++k) dst[n][k] = *(const PG8_LAS bf16x8*)(lds + PG8_SB(b, h) + boff + n * 2048 + k * 1024); } while (0)
; #define PG8_MMA(ai, bj, At, Bt) do { __builtin_amdgcn_s_setprio(1); _Pragma("unroll") for (int m = 0; m < 4; ++m) _Pragma("unroll") for (int n = 0; n < 2; ++n) _Pragma("unroll") for (int k = 0; k < 2; ++k) \
;         acc[ai][bj][m][n] = mma16<Epi::I8>(Bt[n][k], At[m][k], acc[ai][bj][m][n]); __builtin_amdgcn_s_setprio(0); } while (0)
; #define PG8_WAIT_V(n) asm volatile("s_waitcnt vmcnt(" #n ")" ::: "memory")
; #define PG8_WAIT_L(n) asm volatile("s_waitcnt lgkmcnt(" #n ")" ::: "memory")
; #define PG8_BAR __builtin_amdgcn_s_barrier()
; #define PG8_SCHED __builtin_amdgcn_sched_barrier(0)
; template <class Epi, class Sched, bool ALIGN_EPI = false, bool SP2 = false>
; __device__ __forceinline__ void gemm_phase(PG8_LAS unsigned char* lds, const Gemm g, const Sched& S, const Epi& E) {
;     ...
;             const bool last = (t == nt - 2);
;             const char* a1 = cA + (size_t)(t + 1) * kstep;
;             const char* a2 = last ? nA : cA + (size_t)(t + 2) * kstep; const char* b2 = last ? nB : cB + (size_t)(t + 2) * kstep;
;             const char* a3 = a2 + kstep; const char* b3 = b2 + kstep;
;             if (last && has_next) S.a_ready(nxt);
;             if constexpr (SP2) {
;             PG8_LDB(B0, 0, 0); PG8_LDB(B1, 0, 1); PG8_SCHED; PG8_LDA(At, 0, 0); PG8_STAGE(PG8_SA(1, 1), a1 + hstep, voffA);
;             PG8_WAIT_V(8); PG8_WAIT_L(0); PG8_BAR; PG8_MMA(0, 0, At, B0); PG8_MMA(0, 1, At, B1); PG8_BAR; PG8_SCHED;
;             PG8_LDA(At, 0, 1); PG8_STAGE(PG8_SB(0, 0), b2, voffB); PG8_STAGE(PG8_SB(0, 1), b2 + hstep, voffB); PG8_STAGE(PG8_SA(0, 0), a2, voffA);
.Lpeel175:
	s_add_i32 vcc_lo, s8, 2
	s_add_u32 s4, s6, 0x80
	s_addc_u32 s5, s7, 0
	s_add_i32 vcc_hi, 0, 0x10000
	s_cmp_eq_u32 s13, s8
	s_cselect_b32 s9, s1, s5
	s_cselect_b32 s8, s0, s4
	s_cselect_b32 s5, s97, s85
	s_cselect_b32 s4, s96, s67
	s_add_i32 s84, 0, 0x14000
	v_add_u32_e32 v122, vcc_hi, v248
	v_add_u32_e32 v154, s84, v248
	ds_read_b128 v[98:101], v122
	ds_read_b128 v[102:105], v122 offset:1024
	ds_read_b128 v[114:117], v122 offset:2048
	ds_read_b128 v[122:125], v122 offset:3072
	ds_read_b128 v[130:133], v154
	ds_read_b128 v[138:141], v154 offset:1024
	ds_read_b128 v[146:149], v154 offset:2048
	ds_read_b128 v[154:157], v154 offset:3072
	v_lshl_add_u64 v[206:207], s[6:7], 0, v[200:201]
	s_add_i32 m0, s81, 0xc000
	ds_read_b128 v[162:165], v249
	ds_read_b128 v[166:169], v249 offset:1024
	ds_read_b128 v[170:173], v249 offset:2048
	ds_read_b128 v[174:177], v249 offset:3072
	ds_read_b128 v[178:181], v249 offset:4096
	ds_read_b128 v[182:185], v249 offset:5120
	ds_read_b128 v[186:189], v249 offset:6144
	ds_read_b128 v[190:193], v249 offset:7168
	global_load_lds_dwordx4 v[206:207], off
	v_lshl_add_u64 v[206:207], s[6:7], 0, v[210:211]
	s_add_i32 m0, s81, 0xe000
	s_nop 0
	global_load_lds_dwordx4 v[206:207], off
	s_waitcnt vmcnt(8)
	s_waitcnt lgkmcnt(0)
	s_barrier
	s_setprio 1
	s_waitcnt lgkmcnt(0)
	v_mfma_f32_16x16x32_bf16 v[158:161], v[98:101], v[162:165], 0
	v_mfma_f32_16x16x32_bf16 v[150:153], v[114:117], v[162:165], 0
	v_mfma_f32_16x16x32_bf16 v[118:121], v[114:117], v[170:173], 0
	v_mfma_f32_16x16x32_bf16 v[126:129], v[98:101], v[170:173], 0
	v_mfma_f32_16x16x32_bf16 v[94:97], v[98:101], v[178:181], 0
	v_mfma_f32_16x16x32_bf16 v[90:93], v[114:117], v[178:181], 0
	v_mfma_f32_16x16x32_bf16 v[74:77], v[114:117], v[186:189], 0
	v_mfma_f32_16x16x32_bf16 v[78:81], v[98:101], v[186:189], 0
	v_mfma_f32_16x16x32_bf16 v[158:161], v[102:105], v[166:169], v[158:161]
	v_mfma_f32_16x16x32_bf16 v[150:153], v[122:125], v[166:169], v[150:153]
	v_mfma_f32_16x16x32_bf16 v[118:121], v[122:125], v[174:177], v[118:121]
	v_mfma_f32_16x16x32_bf16 v[126:129], v[102:105], v[174:177], v[126:129]
	v_mfma_f32_16x16x32_bf16 v[94:97], v[102:105], v[182:185], v[94:97]
	v_mfma_f32_16x16x32_bf16 v[90:93], v[122:125], v[182:185], v[90:93]
	v_mfma_f32_16x16x32_bf16 v[74:77], v[122:125], v[190:193], v[74:77]
	v_mfma_f32_16x16x32_bf16 v[78:81], v[102:105], v[190:193], v[78:81]
	s_setprio 0
	s_setprio 1
	v_mfma_f32_16x16x32_bf16 v[142:145], v[130:133], v[162:165], 0
	v_mfma_f32_16x16x32_bf16 v[134:137], v[146:149], v[162:165], 0
	v_mfma_f32_16x16x32_bf16 v[106:109], v[146:149], v[170:173], 0
	v_mfma_f32_16x16x32_bf16 v[110:113], v[130:133], v[170:173], 0
	v_mfma_f32_16x16x32_bf16 v[86:89], v[130:133], v[178:181], 0
	v_mfma_f32_16x16x32_bf16 v[82:85], v[146:149], v[178:181], 0
	v_mfma_f32_16x16x32_bf16 v[66:69], v[146:149], v[186:189], 0
	v_mfma_f32_16x16x32_bf16 v[70:73], v[130:133], v[186:189], 0
	v_mfma_f32_16x16x32_bf16 v[142:145], v[138:141], v[166:169], v[142:145]
	v_mfma_f32_16x16x32_bf16 v[134:137], v[154:157], v[166:169], v[134:137]
	v_mfma_f32_16x16x32_bf16 v[106:109], v[154:157], v[174:177], v[106:109]
	v_mfma_f32_16x16x32_bf16 v[110:113], v[138:141], v[174:177], v[110:113]
	v_mfma_f32_16x16x32_bf16 v[86:89], v[138:141], v[182:185], v[86:89]
	v_mfma_f32_16x16x32_bf16 v[82:85], v[154:157], v[182:185], v[82:85]
	v_mfma_f32_16x16x32_bf16 v[66:69], v[154:157], v[190:193], v[66:69]
	v_mfma_f32_16x16x32_bf16 v[70:73], v[138:141], v[190:193], v[70:73]
	s_setprio 0
	s_barrier
	s_add_i32 vcc_hi, vcc_hi, s80
	v_lshl_add_u64 v[206:207], s[4:5], 0, v[0:1]
	s_mov_b32 m0, vcc_hi
	ds_read_b128 v[162:165], v249 offset:16384
	ds_read_b128 v[166:169], v249 offset:17408
	ds_read_b128 v[170:173], v249 offset:18432
	ds_read_b128 v[174:177], v249 offset:19456
	ds_read_b128 v[178:181], v249 offset:20480
	ds_read_b128 v[182:185], v249 offset:21504
	ds_read_b128 v[186:189], v249 offset:22528
	ds_read_b128 v[190:193], v249 offset:23552
	global_load_lds_dwordx4 v[206:207], off
	s_add_i32 m0, vcc_hi, 0x2000
	v_lshl_add_u64 v[212:213], s[4:5], 0, v[198:199]
	s_add_u32 s4, s4, s58
	s_addc_u32 s5, s5, 0
	s_add_i32 s84, s84, s80
	global_load_lds_dwordx4 v[212:213], off
	v_lshl_add_u64 v[214:215], s[4:5], 0, v[0:1]
	s_mov_b32 m0, s84
	v_lshl_add_u64 v[216:217], s[4:5], 0, v[198:199]
	global_load_lds_dwordx4 v[214:215], off
	s_add_i32 m0, s84, 0x2000
	v_lshl_add_u64 v[218:219], s[8:9], 0, v[194:195]
	global_load_lds_dwordx4 v[216:217], off
	s_mov_b32 m0, s81
	v_lshl_add_u64 v[220:221], s[8:9], 0, v[196:197]
	global_load_lds_dwordx4 v[218:219], off
	s_mov_b32 m0, s70
	s_nop 0
	global_load_lds_dwordx4 v[220:221], off
	s_waitcnt vmcnt(8)
	s_waitcnt lgkmcnt(0)
	s_barrier
; #define PG8_STAGE(bufoff, gbase, voff) do { _Pragma("unroll") for (int _i = 0; _i < 2; ++_i) \
;         __builtin_amdgcn_global_load_lds((const unsigned*)((const char*)(gbase) + (voff)[_i]), (PG8_LAS unsigned*)(lds + (bufoff) + ldsw + _i * 8192), 16, 0, 0); } while (0)
; #define PG8_LDA(dst, b, h) do { _Pragma("unroll") for (int m = 0; m < 4; ++m) _Pragma("unroll") for (int k = 0; k < 2; ++k) dst[m][k] = *(const PG8_LAS bf16x8*)(lds + PG8_SA(b, h) + aoff + m * 2048 + k * 1024); } while (0)
; #define PG8_LDB(dst, b, h) do { _Pragma("unroll") for (int n = 0; n < 2; ++n) _Pragma("unroll") for (int k = 0; k < 2; ++k) dst[n][k] = *(const PG8_LAS bf16x8*)(lds + PG8_SB(b, h) + boff + n * 2048 + k * 1024); } while (0)
; #define PG8_MMA(ai, bj, At, Bt) do { __builtin_amdgcn_s_setprio(1); _Pragma("unroll") for (int m = 0; m < 4; ++m) _Pragma("unroll") for (int n = 0; n < 2; ++n) _Pragma("unroll") for (int k = 0; k < 2; ++k) \
;         acc[ai][bj][m][n] = mma16<Epi::I8>(Bt[n][k], At[m][k], acc[ai][bj][m][n]); __builtin_amdgcn_s_setprio(0); } while (0)
; #define PG8_WAIT_V(n) asm volatile("s_waitcnt vmcnt(" #n ")" ::: "memory")
; #define PG8_WAIT_L(n) asm volatile("s_waitcnt lgkmcnt(" #n ")" ::: "memory")
; #define PG8_BAR __builtin_amdgcn_s_barrier()
; #define PG8_SCHED __builtin_amdgcn_sched_barrier(0)
; template <class Epi, class Sched, bool ALIGN_EPI = false, bool SP2 = false>
; __device__ __forceinline__ void gemm_phase(PG8_LAS unsigned char* lds, const Gemm g, const Sched& S, const Epi& E) {
;     ...
;             PG8_WAIT_V(8); PG8_WAIT_L(0); PG8_BAR; PG8_MMA(1, 0, At, B0); PG8_MMA(1, 1, At, B1); PG8_BAR; PG8_SCHED;
;             PG8_LDB(B0, 1, 0); PG8_LDB(B1, 1, 1); PG8_SCHED; PG8_LDA(At, 1, 0); PG8_STAGE(PG8_SA(0, 1), a2 + hstep, voffA);
;             PG8_WAIT_V(8); PG8_WAIT_L(0); PG8_BAR; PG8_MMA(0, 0, At, B0); PG8_MMA(0, 1, At, B1); PG8_BAR; PG8_SCHED;
	s_setprio 1
	s_waitcnt lgkmcnt(0)
	v_mfma_f32_16x16x32_bf16 v[62:65], v[98:101], v[162:165], 0
	v_mfma_f32_16x16x32_bf16 v[58:61], v[114:117], v[162:165], 0
	v_mfma_f32_16x16x32_bf16 v[42:45], v[114:117], v[170:173], 0
	v_mfma_f32_16x16x32_bf16 v[46:49], v[98:101], v[170:173], 0
	v_mfma_f32_16x16x32_bf16 v[30:33], v[98:101], v[178:181], 0
	v_mfma_f32_16x16x32_bf16 v[26:29], v[114:117], v[178:181], 0
	v_mfma_f32_16x16x32_bf16 v[10:13], v[114:117], v[186:189], 0
	v_mfma_f32_16x16x32_bf16 v[14:17], v[98:101], v[186:189], 0
	v_mfma_f32_16x16x32_bf16 v[62:65], v[102:105], v[166:169], v[62:65]
	v_mfma_f32_16x16x32_bf16 v[58:61], v[122:125], v[166:169], v[58:61]
	v_mfma_f32_16x16x32_bf16 v[42:45], v[122:125], v[174:177], v[42:45]
	v_mfma_f32_16x16x32_bf16 v[46:49], v[102:105], v[174:177], v[46:49]
	v_mfma_f32_16x16x32_bf16 v[30:33], v[102:105], v[182:185], v[30:33]
	v_mfma_f32_16x16x32_bf16 v[26:29], v[122:125], v[182:185], v[26:29]
	v_mfma_f32_16x16x32_bf16 v[10:13], v[122:125], v[190:193], v[10:13]
	v_mfma_f32_16x16x32_bf16 v[14:17], v[102:105], v[190:193], v[14:17]
	s_setprio 0
	s_setprio 1
	v_mfma_f32_16x16x32_bf16 v[54:57], v[130:133], v[162:165], 0
	v_mfma_f32_16x16x32_bf16 v[50:53], v[146:149], v[162:165], 0
	v_mfma_f32_16x16x32_bf16 v[34:37], v[146:149], v[170:173], 0
	v_mfma_f32_16x16x32_bf16 v[38:41], v[130:133], v[170:173], 0
	v_mfma_f32_16x16x32_bf16 v[22:25], v[130:133], v[178:181], 0
	v_mfma_f32_16x16x32_bf16 v[18:21], v[146:149], v[178:181], 0
	v_mfma_f32_16x16x32_bf16 v[2:5], v[146:149], v[186:189], 0
	v_mfma_f32_16x16x32_bf16 v[6:9], v[130:133], v[186:189], 0
	v_mfma_f32_16x16x32_bf16 v[54:57], v[138:141], v[166:169], v[54:57]
	v_mfma_f32_16x16x32_bf16 v[50:53], v[154:157], v[166:169], v[50:53]
	v_mfma_f32_16x16x32_bf16 v[34:37], v[154:157], v[174:177], v[34:37]
	v_mfma_f32_16x16x32_bf16 v[38:41], v[138:141], v[174:177], v[38:41]
	v_mfma_f32_16x16x32_bf16 v[22:25], v[138:141], v[182:185], v[22:25]
	v_mfma_f32_16x16x32_bf16 v[18:21], v[154:157], v[182:185], v[18:21]
	v_mfma_f32_16x16x32_bf16 v[2:5], v[154:157], v[190:193], v[2:5]
	v_mfma_f32_16x16x32_bf16 v[6:9], v[138:141], v[190:193], v[6:9]
	s_setprio 0
	s_barrier
	s_add_i32 s84, 0, 0x18000
	s_add_i32 vcc_hi, 0, 0x1c000
	v_add_u32_e32 v122, s84, v248
	v_add_u32_e32 v154, vcc_hi, v248
	ds_read_b128 v[98:101], v122
	ds_read_b128 v[102:105], v122 offset:1024
	ds_read_b128 v[114:117], v122 offset:2048
	ds_read_b128 v[122:125], v122 offset:3072
	ds_read_b128 v[130:133], v154
	ds_read_b128 v[138:141], v154 offset:1024
	ds_read_b128 v[146:149], v154 offset:2048
	ds_read_b128 v[154:157], v154 offset:3072
	s_add_u32 s4, s8, s58
	s_addc_u32 s5, s9, 0
	s_mov_b32 m0, s71
	v_lshl_add_u64 v[222:223], s[4:5], 0, v[194:195]
	ds_read_b128 v[162:165], v249 offset:32768
	ds_read_b128 v[166:169], v249 offset:33792
	ds_read_b128 v[170:173], v249 offset:34816
	ds_read_b128 v[174:177], v249 offset:35840
	ds_read_b128 v[178:181], v249 offset:36864
	ds_read_b128 v[182:185], v249 offset:37888
	ds_read_b128 v[186:189], v249 offset:38912
	ds_read_b128 v[190:193], v249 offset:39936
	global_load_lds_dwordx4 v[222:223], off
	v_lshl_add_u64 v[222:223], s[4:5], 0, v[196:197]
	s_mov_b32 m0, s12
	s_nop 0
	global_load_lds_dwordx4 v[222:223], off
	s_waitcnt vmcnt(8)
	s_waitcnt lgkmcnt(0)
	s_barrier
	s_setprio 1
	s_waitcnt lgkmcnt(0)
	v_mfma_f32_16x16x32_bf16 v[158:161], v[98:101], v[162:165], v[158:161]
	v_mfma_f32_16x16x32_bf16 v[150:153], v[114:117], v[162:165], v[150:153]
	v_mfma_f32_16x16x32_bf16 v[118:121], v[114:117], v[170:173], v[118:121]
	v_mfma_f32_16x16x32_bf16 v[126:129], v[98:101], v[170:173], v[126:129]
	v_mfma_f32_16x16x32_bf16 v[94:97], v[98:101], v[178:181], v[94:97]
	v_mfma_f32_16x16x32_bf16 v[90:93], v[114:117], v[178:181], v[90:93]
	v_mfma_f32_16x16x32_bf16 v[74:77], v[114:117], v[186:189], v[74:77]
	v_mfma_f32_16x16x32_bf16 v[78:81], v[98:101], v[186:189], v[78:81]
	v_mfma_f32_16x16x32_bf16 v[158:161], v[102:105], v[166:169], v[158:161]
	v_mfma_f32_16x16x32_bf16 v[150:153], v[122:125], v[166:169], v[150:153]
	v_mfma_f32_16x16x32_bf16 v[118:121], v[122:125], v[174:177], v[118:121]
	v_mfma_f32_16x16x32_bf16 v[126:129], v[102:105], v[174:177], v[126:129]
	v_mfma_f32_16x16x32_bf16 v[94:97], v[102:105], v[182:185], v[94:97]
	v_mfma_f32_16x16x32_bf16 v[90:93], v[122:125], v[182:185], v[90:93]
	v_mfma_f32_16x16x32_bf16 v[74:77], v[122:125], v[190:193], v[74:77]
	v_mfma_f32_16x16x32_bf16 v[78:81], v[102:105], v[190:193], v[78:81]
	s_setprio 0
	s_setprio 1
	v_mfma_f32_16x16x32_bf16 v[142:145], v[130:133], v[162:165], v[142:145]
	v_mfma_f32_16x16x32_bf16 v[134:137], v[146:149], v[162:165], v[134:137]
	v_mfma_f32_16x16x32_bf16 v[106:109], v[146:149], v[170:173], v[106:109]
	v_mfma_f32_16x16x32_bf16 v[110:113], v[130:133], v[170:173], v[110:113]
	v_mfma_f32_16x16x32_bf16 v[86:89], v[130:133], v[178:181], v[86:89]
	v_mfma_f32_16x16x32_bf16 v[82:85], v[146:149], v[178:181], v[82:85]
	v_mfma_f32_16x16x32_bf16 v[66:69], v[146:149], v[186:189], v[66:69]
	v_mfma_f32_16x16x32_bf16 v[70:73], v[130:133], v[186:189], v[70:73]
	v_mfma_f32_16x16x32_bf16 v[142:145], v[138:141], v[166:169], v[142:145]
	v_mfma_f32_16x16x32_bf16 v[134:137], v[154:157], v[166:169], v[134:137]
	v_mfma_f32_16x16x32_bf16 v[106:109], v[154:157], v[174:177], v[106:109]
	v_mfma_f32_16x16x32_bf16 v[110:113], v[138:141], v[174:177], v[110:113]
	v_mfma_f32_16x16x32_bf16 v[86:89], v[138:141], v[182:185], v[86:89]
	v_mfma_f32_16x16x32_bf16 v[82:85], v[154:157], v[182:185], v[82:85]
	v_mfma_f32_16x16x32_bf16 v[66:69], v[154:157], v[190:193], v[66:69]
	v_mfma_f32_16x16x32_bf16 v[70:73], v[138:141], v[190:193], v[70:73]
	s_setprio 0
	s_barrier
; #define PG8_STAGE(bufoff, gbase, voff) do { _Pragma("unroll") for (int _i = 0; _i < 2; ++_i) \
;         __builtin_amdgcn_global_load_lds((const unsigned*)((const char*)(gbase) + (voff)[_i]), (PG8_LAS unsigned*)(lds + (bufoff) + ldsw + _i * 8192), 16, 0, 0); } while (0)
; #define PG8_LDA(dst, b, h) do { _Pragma("unroll") for (int m = 0; m < 4; ++m) _Pragma("unroll") for (int k = 0; k < 2; ++k) dst[m][k] = *(const PG8_LAS bf16x8*)(lds + PG8_SA(b, h) + aoff + m * 2048 + k * 1024); } while (0)
; #define PG8_LDB(dst, b, h) do { _Pragma("unroll") for (int n = 0; n < 2; ++n) _Pragma("unroll") for (int k = 0; k < 2; ++k) dst[n][k] = *(const PG8_LAS bf16x8*)(lds + PG8_SB(b, h) + boff + n * 2048 + k * 1024); } while (0)
; #define PG8_MMA(ai, bj, At, Bt) do { __builtin_amdgcn_s_setprio(1); _Pragma("unroll") for (int m = 0; m < 4; ++m) _Pragma("unroll") for (int n = 0; n < 2; ++n) _Pragma("unroll") for (int k = 0; k < 2; ++k) \
;         acc[ai][bj][m][n] = mma16<Epi::I8>(Bt[n][k], At[m][k], acc[ai][bj][m][n]); __builtin_amdgcn_s_setprio(0); } while (0)
; #define PG8_WAIT_V(n) asm volatile("s_waitcnt vmcnt(" #n ")" ::: "memory")
; #define PG8_WAIT_L(n) asm volatile("s_waitcnt lgkmcnt(" #n ")" ::: "memory")
; #define PG8_BAR __builtin_amdgcn_s_barrier()
; template <class Epi, class Sched, bool ALIGN_EPI = false, bool SP2 = false>
; __device__ __forceinline__ void gemm_phase(PG8_LAS unsigned char* lds, const Gemm g, const Sched& S, const Epi& E) {
;     ...
;             const bool last = (t == nt - 2);
;             const char* a1 = cA + (size_t)(t + 1) * kstep;
;             const char* a2 = last ? nA : cA + (size_t)(t + 2) * kstep; const char* b2 = last ? nB : cB + (size_t)(t + 2) * kstep;
;             const char* a3 = a2 + kstep; const char* b3 = b2 + kstep;
;             if (last && has_next) S.a_ready(nxt);
;             if constexpr (SP2) {
;             PG8_LDB(B0, 0, 0); PG8_LDB(B1, 0, 1); PG8_SCHED; PG8_LDA(At, 0, 0); PG8_STAGE(PG8_SA(1, 1), a1 + hstep, voffA);
;             PG8_WAIT_V(8); PG8_WAIT_L(0); PG8_BAR; PG8_MMA(0, 0, At, B0); PG8_MMA(0, 1, At, B1); PG8_BAR; PG8_SCHED;
;     ...
;             PG8_LDA(At, 1, 1); PG8_STAGE(PG8_SB(1, 0), b3, voffB); PG8_STAGE(PG8_SB(1, 1), b3 + hstep, voffB); PG8_STAGE(PG8_SA(1, 0), a3, voffA);
;             PG8_WAIT_V(8); PG8_WAIT_L(0); PG8_BAR; PG8_MMA(1, 0, At, B0); PG8_MMA(1, 1, At, B1); PG8_BAR; PG8_SCHED;
	s_add_i32 s4, s84, s80
	v_lshl_add_u64 v[206:207], v[206:207], 0, s[92:93]
	s_mov_b32 m0, s4
	ds_read_b128 v[162:165], v249 offset:49152
	ds_read_b128 v[166:169], v249 offset:50176
	ds_read_b128 v[170:173], v249 offset:51200
	ds_read_b128 v[174:177], v249 offset:52224
	ds_read_b128 v[178:181], v249 offset:53248
	ds_read_b128 v[182:185], v249 offset:54272
	ds_read_b128 v[186:189], v249 offset:55296
	ds_read_b128 v[190:193], v249 offset:56320
	global_load_lds_dwordx4 v[206:207], off
	v_lshl_add_u64 v[206:207], v[212:213], 0, s[92:93]
	s_add_i32 m0, s4, 0x2000
	s_add_i32 s4, vcc_hi, s80
	global_load_lds_dwordx4 v[206:207], off
	v_lshl_add_u64 v[206:207], v[214:215], 0, s[92:93]
	s_mov_b32 m0, s4
	s_nop 0
	global_load_lds_dwordx4 v[206:207], off
	v_lshl_add_u64 v[206:207], v[216:217], 0, s[92:93]
	s_add_i32 m0, s4, 0x2000
	s_nop 0
	global_load_lds_dwordx4 v[206:207], off
	v_lshl_add_u64 v[206:207], v[218:219], 0, s[92:93]
	s_mov_b32 m0, s10
	s_nop 0
	global_load_lds_dwordx4 v[206:207], off
	v_lshl_add_u64 v[206:207], v[220:221], 0, s[92:93]
	s_mov_b32 m0, s11
	s_nop 0
	global_load_lds_dwordx4 v[206:207], off
	s_waitcnt vmcnt(8)
	s_waitcnt lgkmcnt(0)
	s_barrier
	s_setprio 1
	s_waitcnt lgkmcnt(0)
	v_mfma_f32_16x16x32_bf16 v[62:65], v[98:101], v[162:165], v[62:65]
	v_mfma_f32_16x16x32_bf16 v[58:61], v[114:117], v[162:165], v[58:61]
	v_mfma_f32_16x16x32_bf16 v[42:45], v[114:117], v[170:173], v[42:45]
	v_mfma_f32_16x16x32_bf16 v[46:49], v[98:101], v[170:173], v[46:49]
	v_mfma_f32_16x16x32_bf16 v[30:33], v[98:101], v[178:181], v[30:33]
	v_mfma_f32_16x16x32_bf16 v[26:29], v[114:117], v[178:181], v[26:29]
	v_mfma_f32_16x16x32_bf16 v[10:13], v[114:117], v[186:189], v[10:13]
	v_mfma_f32_16x16x32_bf16 v[14:17], v[98:101], v[186:189], v[14:17]
	v_mfma_f32_16x16x32_bf16 v[62:65], v[102:105], v[166:169], v[62:65]
	v_mfma_f32_16x16x32_bf16 v[58:61], v[122:125], v[166:169], v[58:61]
	v_mfma_f32_16x16x32_bf16 v[42:45], v[122:125], v[174:177], v[42:45]
	v_mfma_f32_16x16x32_bf16 v[46:49], v[102:105], v[174:177], v[46:49]
	v_mfma_f32_16x16x32_bf16 v[30:33], v[102:105], v[182:185], v[30:33]
	v_mfma_f32_16x16x32_bf16 v[26:29], v[122:125], v[182:185], v[26:29]
	v_mfma_f32_16x16x32_bf16 v[10:13], v[122:125], v[190:193], v[10:13]
	v_mfma_f32_16x16x32_bf16 v[14:17], v[102:105], v[190:193], v[14:17]
	s_setprio 0
	s_setprio 1
	v_mfma_f32_16x16x32_bf16 v[54:57], v[130:133], v[162:165], v[54:57]
	v_mfma_f32_16x16x32_bf16 v[50:53], v[146:149], v[162:165], v[50:53]
	v_mfma_f32_16x16x32_bf16 v[34:37], v[146:149], v[170:173], v[34:37]
	v_mfma_f32_16x16x32_bf16 v[38:41], v[130:133], v[170:173], v[38:41]
	v_mfma_f32_16x16x32_bf16 v[22:25], v[130:133], v[178:181], v[22:25]
	v_mfma_f32_16x16x32_bf16 v[18:21], v[146:149], v[178:181], v[18:21]
	v_mfma_f32_16x16x32_bf16 v[2:5], v[146:149], v[186:189], v[2:5]
	v_mfma_f32_16x16x32_bf16 v[6:9], v[130:133], v[186:189], v[6:9]
	v_mfma_f32_16x16x32_bf16 v[54:57], v[138:141], v[166:169], v[54:57]
	v_mfma_f32_16x16x32_bf16 v[50:53], v[154:157], v[166:169], v[50:53]
	v_mfma_f32_16x16x32_bf16 v[34:37], v[154:157], v[174:177], v[34:37]
	v_mfma_f32_16x16x32_bf16 v[38:41], v[138:141], v[174:177], v[38:41]
	v_mfma_f32_16x16x32_bf16 v[22:25], v[138:141], v[182:185], v[22:25]
	v_mfma_f32_16x16x32_bf16 v[18:21], v[154:157], v[182:185], v[18:21]
	v_mfma_f32_16x16x32_bf16 v[2:5], v[154:157], v[190:193], v[2:5]
	v_mfma_f32_16x16x32_bf16 v[6:9], v[138:141], v[190:193], v[6:9]
	s_setprio 0
	s_barrier
	s_add_u32 s6, s6, 0x100
	s_addc_u32 s7, s7, 0
	s_add_u32 s67, s67, 0x100
	s_addc_u32 s85, s85, 0
	s_cmp_ge_u32 vcc_lo, s69
	s_mov_b32 s8, vcc_lo
	s_cbranch_scc0 .LBB0_175
	s_branch .Lpeelx175
.LBB0_175:
	s_add_i32 vcc_lo, s8, 2
	s_add_u32 s4, s6, 0x80
	s_addc_u32 s5, s7, 0
	s_add_i32 vcc_hi, 0, 0x10000
	s_cmp_eq_u32 s13, s8
	s_cselect_b32 s9, s1, s5
	s_cselect_b32 s8, s0, s4
	s_cselect_b32 s5, s97, s85
	s_cselect_b32 s4, s96, s67
	s_add_i32 s84, 0, 0x14000
	v_add_u32_e32 v122, vcc_hi, v248
	v_add_u32_e32 v154, s84, v248
	ds_read_b128 v[98:101], v122
	ds_read_b128 v[102:105], v122 offset:1024
	ds_read_b128 v[114:117], v122 offset:2048
	ds_read_b128 v[122:125], v122 offset:3072
	ds_read_b128 v[130:133], v154
	ds_read_b128 v[138:141], v154 offset:1024
	ds_read_b128 v[146:149], v154 offset:2048
	ds_read_b128 v[154:157], v154 offset:3072
	v_lshl_add_u64 v[206:207], s[6:7], 0, v[200:201]
	s_add_i32 m0, s81, 0xc000
	ds_read_b128 v[162:165], v249
	ds_read_b128 v[166:169], v249 offset:1024
	ds_read_b128 v[170:173], v249 offset:2048
	ds_read_b128 v[174:177], v249 offset:3072
	ds_read_b128 v[178:181], v249 offset:4096
	ds_read_b128 v[182:185], v249 offset:5120
	ds_read_b128 v[186:189], v249 offset:6144
	ds_read_b128 v[190:193], v249 offset:7168
	global_load_lds_dwordx4 v[206:207], off
	v_lshl_add_u64 v[206:207], s[6:7], 0, v[210:211]
	s_add_i32 m0, s81, 0xe000
	s_nop 0
	global_load_lds_dwordx4 v[206:207], off
	s_waitcnt vmcnt(8)
	s_waitcnt lgkmcnt(0)
	s_barrier
; #define PG8_STAGE(bufoff, gbase, voff) do { _Pragma("unroll") for (int _i = 0; _i < 2; ++_i) \
;         __builtin_amdgcn_global_load_lds((const unsigned*)((const char*)(gbase) + (voff)[_i]), (PG8_LAS unsigned*)(lds + (bufoff) + ldsw + _i * 8192), 16, 0, 0); } while (0)
; #define PG8_LDA(dst, b, h) do { _Pragma("unroll") for (int m = 0; m < 4; ++m) _Pragma("unroll") for (int k = 0; k < 2; ++k) dst[m][k] = *(const PG8_LAS bf16x8*)(lds + PG8_SA(b, h) + aoff + m * 2048 + k * 1024); } while (0)
; #define PG8_MMA(ai, bj, At, Bt) do { __builtin_amdgcn_s_setprio(1); _Pragma("unroll") for (int m = 0; m < 4; ++m) _Pragma("unroll") for (int n = 0; n < 2; ++n) _Pragma("unroll") for (int k = 0; k < 2; ++k) \
;         acc[ai][bj][m][n] = mma16<Epi::I8>(Bt[n][k], At[m][k], acc[ai][bj][m][n]); __builtin_amdgcn_s_setprio(0); } while (0)
; #define PG8_WAIT_V(n) asm volatile("s_waitcnt vmcnt(" #n ")" ::: "memory")
; #define PG8_WAIT_L(n) asm volatile("s_waitcnt lgkmcnt(" #n ")" ::: "memory")
; #define PG8_BAR __builtin_amdgcn_s_barrier()
; #define PG8_SCHED __builtin_amdgcn_sched_barrier(0)
; template <class Epi, class Sched, bool ALIGN_EPI = false, bool SP2 = false>
; __device__ __forceinline__ void gemm_phase(PG8_LAS unsigned char* lds, const Gemm g, const Sched& S, const Epi& E) {
;     ...
;             PG8_WAIT_V(8); PG8_WAIT_L(0); PG8_BAR; PG8_MMA(0, 0, At, B0); PG8_MMA(0, 1, At, B1); PG8_BAR; PG8_SCHED;
;             PG8_LDA(At, 0, 1); PG8_STAGE(PG8_SB(0, 0), b2, voffB); PG8_STAGE(PG8_SB(0, 1), b2 + hstep, voffB); PG8_STAGE(PG8_SA(0, 0), a2, voffA);
;             PG8_WAIT_V(8); PG8_WAIT_L(0); PG8_BAR; PG8_MMA(1, 0, At, B0); PG8_MMA(1, 1, At, B1); PG8_BAR; PG8_SCHED;
	s_setprio 1
	s_waitcnt lgkmcnt(0)
	v_mfma_f32_16x16x32_bf16 v[158:161], v[98:101], v[162:165], v[158:161]
	v_mfma_f32_16x16x32_bf16 v[150:153], v[114:117], v[162:165], v[150:153]
	v_mfma_f32_16x16x32_bf16 v[118:121], v[114:117], v[170:173], v[118:121]
	v_mfma_f32_16x16x32_bf16 v[126:129], v[98:101], v[170:173], v[126:129]
	v_mfma_f32_16x16x32_bf16 v[94:97], v[98:101], v[178:181], v[94:97]
	v_mfma_f32_16x16x32_bf16 v[90:93], v[114:117], v[178:181], v[90:93]
	v_mfma_f32_16x16x32_bf16 v[74:77], v[114:117], v[186:189], v[74:77]
	v_mfma_f32_16x16x32_bf16 v[78:81], v[98:101], v[186:189], v[78:81]
	v_mfma_f32_16x16x32_bf16 v[158:161], v[102:105], v[166:169], v[158:161]
	v_mfma_f32_16x16x32_bf16 v[150:153], v[122:125], v[166:169], v[150:153]
	v_mfma_f32_16x16x32_bf16 v[118:121], v[122:125], v[174:177], v[118:121]
	v_mfma_f32_16x16x32_bf16 v[126:129], v[102:105], v[174:177], v[126:129]
	v_mfma_f32_16x16x32_bf16 v[94:97], v[102:105], v[182:185], v[94:97]
	v_mfma_f32_16x16x32_bf16 v[90:93], v[122:125], v[182:185], v[90:93]
	v_mfma_f32_16x16x32_bf16 v[74:77], v[122:125], v[190:193], v[74:77]
	v_mfma_f32_16x16x32_bf16 v[78:81], v[102:105], v[190:193], v[78:81]
	s_setprio 0
	s_setprio 1
	v_mfma_f32_16x16x32_bf16 v[142:145], v[130:133], v[162:165], v[142:145]
	v_mfma_f32_16x16x32_bf16 v[134:137], v[146:149], v[162:165], v[134:137]
	v_mfma_f32_16x16x32_bf16 v[106:109], v[146:149], v[170:173], v[106:109]
	v_mfma_f32_16x16x32_bf16 v[110:113], v[130:133], v[170:173], v[110:113]
	v_mfma_f32_16x16x32_bf16 v[86:89], v[130:133], v[178:181], v[86:89]
	v_mfma_f32_16x16x32_bf16 v[82:85], v[146:149], v[178:181], v[82:85]
	v_mfma_f32_16x16x32_bf16 v[66:69], v[146:149], v[186:189], v[66:69]
	v_mfma_f32_16x16x32_bf16 v[70:73], v[130:133], v[186:189], v[70:73]
	v_mfma_f32_16x16x32_bf16 v[142:145], v[138:141], v[166:169], v[142:145]
	v_mfma_f32_16x16x32_bf16 v[134:137], v[154:157], v[166:169], v[134:137]
	v_mfma_f32_16x16x32_bf16 v[106:109], v[154:157], v[174:177], v[106:109]
	v_mfma_f32_16x16x32_bf16 v[110:113], v[138:141], v[174:177], v[110:113]
	v_mfma_f32_16x16x32_bf16 v[86:89], v[138:141], v[182:185], v[86:89]
	v_mfma_f32_16x16x32_bf16 v[82:85], v[154:157], v[182:185], v[82:85]
	v_mfma_f32_16x16x32_bf16 v[66:69], v[154:157], v[190:193], v[66:69]
	v_mfma_f32_16x16x32_bf16 v[70:73], v[138:141], v[190:193], v[70:73]
	s_setprio 0
	s_barrier
	s_add_i32 vcc_hi, vcc_hi, s80
	v_lshl_add_u64 v[206:207], s[4:5], 0, v[0:1]
	s_mov_b32 m0, vcc_hi
	ds_read_b128 v[162:165], v249 offset:16384
	ds_read_b128 v[166:169], v249 offset:17408
	ds_read_b128 v[170:173], v249 offset:18432
	ds_read_b128 v[174:177], v249 offset:19456
	ds_read_b128 v[178:181], v249 offset:20480
	ds_read_b128 v[182:185], v249 offset:21504
	ds_read_b128 v[186:189], v249 offset:22528
	ds_read_b128 v[190:193], v249 offset:23552
	global_load_lds_dwordx4 v[206:207], off
	s_add_i32 m0, vcc_hi, 0x2000
	v_lshl_add_u64 v[212:213], s[4:5], 0, v[198:199]
	s_add_u32 s4, s4, s58
	s_addc_u32 s5, s5, 0
	s_add_i32 s84, s84, s80
	global_load_lds_dwordx4 v[212:213], off
	v_lshl_add_u64 v[214:215], s[4:5], 0, v[0:1]
	s_mov_b32 m0, s84
	v_lshl_add_u64 v[216:217], s[4:5], 0, v[198:199]
	global_load_lds_dwordx4 v[214:215], off
	s_add_i32 m0, s84, 0x2000
	v_lshl_add_u64 v[218:219], s[8:9], 0, v[194:195]
	global_load_lds_dwordx4 v[216:217], off
	s_mov_b32 m0, s81
	v_lshl_add_u64 v[220:221], s[8:9], 0, v[196:197]
	global_load_lds_dwordx4 v[218:219], off
	s_mov_b32 m0, s70
	s_nop 0
	global_load_lds_dwordx4 v[220:221], off
	s_waitcnt vmcnt(8)
	s_waitcnt lgkmcnt(0)
	s_barrier
	s_setprio 1
	s_waitcnt lgkmcnt(0)
	v_mfma_f32_16x16x32_bf16 v[62:65], v[98:101], v[162:165], v[62:65]
	v_mfma_f32_16x16x32_bf16 v[58:61], v[114:117], v[162:165], v[58:61]
	v_mfma_f32_16x16x32_bf16 v[42:45], v[114:117], v[170:173], v[42:45]
	v_mfma_f32_16x16x32_bf16 v[46:49], v[98:101], v[170:173], v[46:49]
	v_mfma_f32_16x16x32_bf16 v[30:33], v[98:101], v[178:181], v[30:33]
	v_mfma_f32_16x16x32_bf16 v[26:29], v[114:117], v[178:181], v[26:29]
	v_mfma_f32_16x16x32_bf16 v[10:13], v[114:117], v[186:189], v[10:13]
	v_mfma_f32_16x16x32_bf16 v[14:17], v[98:101], v[186:189], v[14:17]
	v_mfma_f32_16x16x32_bf16 v[62:65], v[102:105], v[166:169], v[62:65]
	v_mfma_f32_16x16x32_bf16 v[58:61], v[122:125], v[166:169], v[58:61]
	v_mfma_f32_16x16x32_bf16 v[42:45], v[122:125], v[174:177], v[42:45]
	v_mfma_f32_16x16x32_bf16 v[46:49], v[102:105], v[174:177], v[46:49]
	v_mfma_f32_16x16x32_bf16 v[30:33], v[102:105], v[182:185], v[30:33]
	v_mfma_f32_16x16x32_bf16 v[26:29], v[122:125], v[182:185], v[26:29]
	v_mfma_f32_16x16x32_bf16 v[10:13], v[122:125], v[190:193], v[10:13]
	v_mfma_f32_16x16x32_bf16 v[14:17], v[102:105], v[190:193], v[14:17]
	s_setprio 0
	s_setprio 1
	v_mfma_f32_16x16x32_bf16 v[54:57], v[130:133], v[162:165], v[54:57]
	v_mfma_f32_16x16x32_bf16 v[50:53], v[146:149], v[162:165], v[50:53]
	v_mfma_f32_16x16x32_bf16 v[34:37], v[146:149], v[170:173], v[34:37]
	v_mfma_f32_16x16x32_bf16 v[38:41], v[130:133], v[170:173], v[38:41]
	v_mfma_f32_16x16x32_bf16 v[22:25], v[130:133], v[178:181], v[22:25]
	v_mfma_f32_16x16x32_bf16 v[18:21], v[146:149], v[178:181], v[18:21]
	v_mfma_f32_16x16x32_bf16 v[2:5], v[146:149], v[186:189], v[2:5]
	v_mfma_f32_16x16x32_bf16 v[6:9], v[130:133], v[186:189], v[6:9]
	v_mfma_f32_16x16x32_bf16 v[54:57], v[138:141], v[166:169], v[54:57]
	v_mfma_f32_16x16x32_bf16 v[50:53], v[154:157], v[166:169], v[50:53]
	v_mfma_f32_16x16x32_bf16 v[34:37], v[154:157], v[174:177], v[34:37]
	v_mfma_f32_16x16x32_bf16 v[38:41], v[138:141], v[174:177], v[38:41]
	v_mfma_f32_16x16x32_bf16 v[22:25], v[138:141], v[182:185], v[22:25]
	v_mfma_f32_16x16x32_bf16 v[18:21], v[154:157], v[182:185], v[18:21]
	v_mfma_f32_16x16x32_bf16 v[2:5], v[154:157], v[190:193], v[2:5]
	v_mfma_f32_16x16x32_bf16 v[6:9], v[138:141], v[190:193], v[6:9]
	s_setprio 0
	s_barrier
; #define PG8_STAGE(bufoff, gbase, voff) do { _Pragma("unroll") for (int _i = 0; _i < 2; ++_i) \
;         __builtin_amdgcn_global_load_lds((const unsigned*)((const char*)(gbase) + (voff)[_i]), (PG8_LAS unsigned*)(lds + (bufoff) + ldsw + _i * 8192), 16, 0, 0); } while (0)
; #define PG8_LDA(dst, b, h) do { _Pragma("unroll") for (int m = 0; m < 4; ++m) _Pragma("unroll") for (int k = 0; k < 2; ++k) dst[m][k] = *(const PG8_LAS bf16x8*)(lds + PG8_SA(b, h) + aoff + m * 2048 + k * 1024); } while (0)
; #define PG8_LDB(dst, b, h) do { _Pragma("unroll") for (int n = 0; n < 2; ++n) _Pragma("unroll") for (int k = 0; k < 2; ++k) dst[n][k] = *(const PG8_LAS bf16x8*)(lds + PG8_SB(b, h) + boff + n * 2048 + k * 1024); } while (0)
; #define PG8_MMA(ai, bj, At, Bt) do { __builtin_amdgcn_s_setprio(1); _Pragma("unroll") for (int m = 0; m < 4; ++m) _Pragma("unroll") for (int n = 0; n < 2; ++n) _Pragma("unroll") for (int k = 0; k < 2; ++k) \
;         acc[ai][bj][m][n] = mma16<Epi::I8>(Bt[n][k], At[m][k], acc[ai][bj][m][n]); __builtin_amdgcn_s_setprio(0); } while (0)
; #define PG8_WAIT_V(n) asm volatile("s_waitcnt vmcnt(" #n ")" ::: "memory")
; #define PG8_WAIT_L(n) asm volatile("s_waitcnt lgkmcnt(" #n ")" ::: "memory")
; #define PG8_BAR __builtin_amdgcn_s_barrier()
; #define PG8_SCHED __builtin_amdgcn_sched_barrier(0)
; template <class Epi, class Sched, bool ALIGN_EPI = false, bool SP2 = false>
; __device__ __forceinline__ void gemm_phase(PG8_LAS unsigned char* lds, const Gemm g, const Sched& S, const Epi& E) {
;     ...
;             PG8_LDB(B0, 1, 0); PG8_LDB(B1, 1, 1); PG8_SCHED; PG8_LDA(At, 1, 0); PG8_STAGE(PG8_SA(0, 1), a2 + hstep, voffA);
;             PG8_WAIT_V(8); PG8_WAIT_L(0); PG8_BAR; PG8_MMA(0, 0, At, B0); PG8_MMA(0, 1, At, B1); PG8_BAR; PG8_SCHED;
	s_add_i32 s84, 0, 0x18000
	s_add_i32 vcc_hi, 0, 0x1c000
	v_add_u32_e32 v122, s84, v248
	v_add_u32_e32 v154, vcc_hi, v248
	ds_read_b128 v[98:101], v122
	ds_read_b128 v[102:105], v122 offset:1024
	ds_read_b128 v[114:117], v122 offset:2048
	ds_read_b128 v[122:125], v122 offset:3072
	ds_read_b128 v[130:133], v154
	ds_read_b128 v[138:141], v154 offset:1024
	ds_read_b128 v[146:149], v154 offset:2048
	ds_read_b128 v[154:157], v154 offset:3072
	s_add_u32 s4, s8, s58
	s_addc_u32 s5, s9, 0
	s_mov_b32 m0, s71
	v_lshl_add_u64 v[222:223], s[4:5], 0, v[194:195]
	ds_read_b128 v[162:165], v249 offset:32768
	ds_read_b128 v[166:169], v249 offset:33792
	ds_read_b128 v[170:173], v249 offset:34816
	ds_read_b128 v[174:177], v249 offset:35840
	ds_read_b128 v[178:181], v249 offset:36864
	ds_read_b128 v[182:185], v249 offset:37888
	ds_read_b128 v[186:189], v249 offset:38912
	ds_read_b128 v[190:193], v249 offset:39936
	global_load_lds_dwordx4 v[222:223], off
	v_lshl_add_u64 v[222:223], s[4:5], 0, v[196:197]
	s_mov_b32 m0, s12
	s_nop 0
	global_load_lds_dwordx4 v[222:223], off
	s_waitcnt vmcnt(8)
	s_waitcnt lgkmcnt(0)
	s_barrier
	s_setprio 1
	s_waitcnt lgkmcnt(0)
	v_mfma_f32_16x16x32_bf16 v[158:161], v[98:101], v[162:165], v[158:161]
	v_mfma_f32_16x16x32_bf16 v[150:153], v[114:117], v[162:165], v[150:153]
	v_mfma_f32_16x16x32_bf16 v[118:121], v[114:117], v[170:173], v[118:121]
	v_mfma_f32_16x16x32_bf16 v[126:129], v[98:101], v[170:173], v[126:129]
	v_mfma_f32_16x16x32_bf16 v[94:97], v[98:101], v[178:181], v[94:97]
	v_mfma_f32_16x16x32_bf16 v[90:93], v[114:117], v[178:181], v[90:93]
	v_mfma_f32_16x16x32_bf16 v[74:77], v[114:117], v[186:189], v[74:77]
	v_mfma_f32_16x16x32_bf16 v[78:81], v[98:101], v[186:189], v[78:81]
	v_mfma_f32_16x16x32_bf16 v[158:161], v[102:105], v[166:169], v[158:161]
	v_mfma_f32_16x16x32_bf16 v[150:153], v[122:125], v[166:169], v[150:153]
	v_mfma_f32_16x16x32_bf16 v[118:121], v[122:125], v[174:177], v[118:121]
	v_mfma_f32_16x16x32_bf16 v[126:129], v[102:105], v[174:177], v[126:129]
	v_mfma_f32_16x16x32_bf16 v[94:97], v[102:105], v[182:185], v[94:97]
	v_mfma_f32_16x16x32_bf16 v[90:93], v[122:125], v[182:185], v[90:93]
	v_mfma_f32_16x16x32_bf16 v[74:77], v[122:125], v[190:193], v[74:77]
	v_mfma_f32_16x16x32_bf16 v[78:81], v[102:105], v[190:193], v[78:81]
	s_setprio 0
	s_setprio 1
	v_mfma_f32_16x16x32_bf16 v[142:145], v[130:133], v[162:165], v[142:145]
	v_mfma_f32_16x16x32_bf16 v[134:137], v[146:149], v[162:165], v[134:137]
	v_mfma_f32_16x16x32_bf16 v[106:109], v[146:149], v[170:173], v[106:109]
	v_mfma_f32_16x16x32_bf16 v[110:113], v[130:133], v[170:173], v[110:113]
	v_mfma_f32_16x16x32_bf16 v[86:89], v[130:133], v[178:181], v[86:89]
	v_mfma_f32_16x16x32_bf16 v[82:85], v[146:149], v[178:181], v[82:85]
	v_mfma_f32_16x16x32_bf16 v[66:69], v[146:149], v[186:189], v[66:69]
	v_mfma_f32_16x16x32_bf16 v[70:73], v[130:133], v[186:189], v[70:73]
	v_mfma_f32_16x16x32_bf16 v[142:145], v[138:141], v[166:169], v[142:145]
	v_mfma_f32_16x16x32_bf16 v[134:137], v[154:157], v[166:169], v[134:137]
	v_mfma_f32_16x16x32_bf16 v[106:109], v[154:157], v[174:177], v[106:109]
	v_mfma_f32_16x16x32_bf16 v[110:113], v[138:141], v[174:177], v[110:113]
	v_mfma_f32_16x16x32_bf16 v[86:89], v[138:141], v[182:185], v[86:89]
	v_mfma_f32_16x16x32_bf16 v[82:85], v[154:157], v[182:185], v[82:85]
	v_mfma_f32_16x16x32_bf16 v[66:69], v[154:157], v[190:193], v[66:69]
	v_mfma_f32_16x16x32_bf16 v[70:73], v[138:141], v[190:193], v[70:73]
	s_setprio 0
	s_barrier
; #define PG8_STAGE(bufoff, gbase, voff) do { _Pragma("unroll") for (int _i = 0; _i < 2; ++_i) \
;         __builtin_amdgcn_global_load_lds((const unsigned*)((const char*)(gbase) + (voff)[_i]), (PG8_LAS unsigned*)(lds + (bufoff) + ldsw + _i * 8192), 16, 0, 0); } while (0)
; #define PG8_LDA(dst, b, h) do { _Pragma("unroll") for (int m = 0; m < 4; ++m) _Pragma("unroll") for (int k = 0; k < 2; ++k) dst[m][k] = *(const PG8_LAS bf16x8*)(lds + PG8_SA(b, h) + aoff + m * 2048 + k * 1024); } while (0)
; #define PG8_MMA(ai, bj, At, Bt) do { __builtin_amdgcn_s_setprio(1); _Pragma("unroll") for (int m = 0; m < 4; ++m) _Pragma("unroll") for (int n = 0; n < 2; ++n) _Pragma("unroll") for (int k = 0; k < 2; ++k) \
;         acc[ai][bj][m][n] = mma16<Epi::I8>(Bt[n][k], At[m][k], acc[ai][bj][m][n]); __builtin_amdgcn_s_setprio(0); } while (0)
; #define PG8_WAIT_V(n) asm volatile("s_waitcnt vmcnt(" #n ")" ::: "memory")
; #define PG8_WAIT_L(n) asm volatile("s_waitcnt lgkmcnt(" #n ")" ::: "memory")
; #define PG8_BAR __builtin_amdgcn_s_barrier()
; #define PG8_SCHED __builtin_amdgcn_sched_barrier(0)
; template <class Epi, class Sched, bool ALIGN_EPI = false, bool SP2 = false>
; __device__ __forceinline__ void gemm_phase(PG8_LAS unsigned char* lds, const Gemm g, const Sched& S, const Epi& E) {
;     ...
;         for (int t = 0; t < nt; t += 2) {
;     ...
;             PG8_LDA(At, 1, 1); PG8_STAGE(PG8_SB(1, 0), b3, voffB); PG8_STAGE(PG8_SB(1, 1), b3 + hstep, voffB); PG8_STAGE(PG8_SA(1, 0), a3, voffA);
;             PG8_WAIT_V(8); PG8_WAIT_L(0); PG8_BAR; PG8_MMA(1, 0, At, B0); PG8_MMA(1, 1, At, B1); PG8_BAR; PG8_SCHED;
	s_add_i32 s4, s84, s80
	v_lshl_add_u64 v[206:207], v[206:207], 0, s[92:93]
	s_mov_b32 m0, s4
	ds_read_b128 v[162:165], v249 offset:49152
	ds_read_b128 v[166:169], v249 offset:50176
	ds_read_b128 v[170:173], v249 offset:51200
	ds_read_b128 v[174:177], v249 offset:52224
	ds_read_b128 v[178:181], v249 offset:53248
	ds_read_b128 v[182:185], v249 offset:54272
	ds_read_b128 v[186:189], v249 offset:55296
	ds_read_b128 v[190:193], v249 offset:56320
	global_load_lds_dwordx4 v[206:207], off
	v_lshl_add_u64 v[206:207], v[212:213], 0, s[92:93]
	s_add_i32 m0, s4, 0x2000
	s_add_i32 s4, vcc_hi, s80
	global_load_lds_dwordx4 v[206:207], off
	v_lshl_add_u64 v[206:207], v[214:215], 0, s[92:93]
	s_mov_b32 m0, s4
	s_nop 0
	global_load_lds_dwordx4 v[206:207], off
	v_lshl_add_u64 v[206:207], v[216:217], 0, s[92:93]
	s_add_i32 m0, s4, 0x2000
	s_nop 0
	global_load_lds_dwordx4 v[206:207], off
	v_lshl_add_u64 v[206:207], v[218:219], 0, s[92:93]
	s_mov_b32 m0, s10
	s_nop 0
	global_load_lds_dwordx4 v[206:207], off
	v_lshl_add_u64 v[206:207], v[220:221], 0, s[92:93]
	s_mov_b32 m0, s11
	s_nop 0
	global_load_lds_dwordx4 v[206:207], off
	s_waitcnt vmcnt(8)
	s_waitcnt lgkmcnt(0)
	s_barrier
	s_setprio 1
	s_waitcnt lgkmcnt(0)
	v_mfma_f32_16x16x32_bf16 v[62:65], v[98:101], v[162:165], v[62:65]
	v_mfma_f32_16x16x32_bf16 v[58:61], v[114:117], v[162:165], v[58:61]
	v_mfma_f32_16x16x32_bf16 v[42:45], v[114:117], v[170:173], v[42:45]
	v_mfma_f32_16x16x32_bf16 v[46:49], v[98:101], v[170:173], v[46:49]
	v_mfma_f32_16x16x32_bf16 v[30:33], v[98:101], v[178:181], v[30:33]
	v_mfma_f32_16x16x32_bf16 v[26:29], v[114:117], v[178:181], v[26:29]
	v_mfma_f32_16x16x32_bf16 v[10:13], v[114:117], v[186:189], v[10:13]
	v_mfma_f32_16x16x32_bf16 v[14:17], v[98:101], v[186:189], v[14:17]
	v_mfma_f32_16x16x32_bf16 v[62:65], v[102:105], v[166:169], v[62:65]
	v_mfma_f32_16x16x32_bf16 v[58:61], v[122:125], v[166:169], v[58:61]
	v_mfma_f32_16x16x32_bf16 v[42:45], v[122:125], v[174:177], v[42:45]
	v_mfma_f32_16x16x32_bf16 v[46:49], v[102:105], v[174:177], v[46:49]
	v_mfma_f32_16x16x32_bf16 v[30:33], v[102:105], v[182:185], v[30:33]
	v_mfma_f32_16x16x32_bf16 v[26:29], v[122:125], v[182:185], v[26:29]
	v_mfma_f32_16x16x32_bf16 v[10:13], v[122:125], v[190:193], v[10:13]
	v_mfma_f32_16x16x32_bf16 v[14:17], v[102:105], v[190:193], v[14:17]
	s_setprio 0
	s_setprio 1
	v_mfma_f32_16x16x32_bf16 v[54:57], v[130:133], v[162:165], v[54:57]
	v_mfma_f32_16x16x32_bf16 v[50:53], v[146:149], v[162:165], v[50:53]
	v_mfma_f32_16x16x32_bf16 v[34:37], v[146:149], v[170:173], v[34:37]
	v_mfma_f32_16x16x32_bf16 v[38:41], v[130:133], v[170:173], v[38:41]
	v_mfma_f32_16x16x32_bf16 v[22:25], v[130:133], v[178:181], v[22:25]
	v_mfma_f32_16x16x32_bf16 v[18:21], v[146:149], v[178:181], v[18:21]
	v_mfma_f32_16x16x32_bf16 v[2:5], v[146:149], v[186:189], v[2:5]
	v_mfma_f32_16x16x32_bf16 v[6:9], v[130:133], v[186:189], v[6:9]
	v_mfma_f32_16x16x32_bf16 v[54:57], v[138:141], v[166:169], v[54:57]
	v_mfma_f32_16x16x32_bf16 v[50:53], v[154:157], v[166:169], v[50:53]
	v_mfma_f32_16x16x32_bf16 v[34:37], v[154:157], v[174:177], v[34:37]
	v_mfma_f32_16x16x32_bf16 v[38:41], v[138:141], v[174:177], v[38:41]
	v_mfma_f32_16x16x32_bf16 v[22:25], v[138:141], v[182:185], v[22:25]
	v_mfma_f32_16x16x32_bf16 v[18:21], v[154:157], v[182:185], v[18:21]
	v_mfma_f32_16x16x32_bf16 v[2:5], v[154:157], v[190:193], v[2:5]
	v_mfma_f32_16x16x32_bf16 v[6:9], v[138:141], v[190:193], v[6:9]
	s_setprio 0
	s_barrier
	s_add_u32 s6, s6, 0x100
	s_addc_u32 s7, s7, 0
	s_add_u32 s67, s67, 0x100
	s_addc_u32 s85, s85, 0
	s_cmp_ge_u32 vcc_lo, s69
	s_mov_b32 s8, vcc_lo
	s_cbranch_scc0 .LBB0_175

; #define PG8_STAGE(bufoff, gbase, voff) do { _Pragma("unroll") for (int _i = 0; _i < 2; ++_i) \
;         __builtin_amdgcn_global_load_lds((const unsigned*)((const char*)(gbase) + (voff)[_i]), (PG8_LAS unsigned*)(lds + (bufoff) + ldsw + _i * 8192), 16, 0, 0); } while (0)
; #define PG8_LDA(dst, b, h) do { _Pragma("unroll") for (int m = 0; m < 4; ++m) _Pragma("unroll") for (int k = 0; k < 2; ++k) dst[m][k] = *(const PG8_LAS bf16x8*)(lds + PG8_SA(b, h) + aoff + m * 2048 + k * 1024); } while (0)
; #define PG8_LDB(dst, b, h) do { _Pragma("unroll") for (int n = 0; n < 2; ++n) _Pragma("unroll") for (int k = 0; k < 2; ++k) dst[n][k] = *(const PG8_LAS bf16x8*)(lds + PG8_SB(b, h) + boff + n * 2048 + k * 1024); } while (0)
; #define PG8_MMA(ai, bj, At, Bt) do { __builtin_amdgcn_s_setprio(1); _Pragma("unroll") for (int m = 0; m < 4; ++m) _Pragma("unroll") for (int n = 0; n < 2; ++n) _Pragma("unroll") for (int k = 0; k < 2; ++k) \
;         acc[ai][bj][m][n] = mma16<Epi::I8>(Bt[n][k], At[m][k], acc[ai][bj][m][n]); __builtin_amdgcn_s_setprio(0); } while (0)
; #define PG8_WAIT_V(n) asm volatile("s_waitcnt vmcnt(" #n ")" ::: "memory")
; #define PG8_WAIT_L(n) asm volatile("s_waitcnt lgkmcnt(" #n ")" ::: "memory")
; #define PG8_BAR __builtin_amdgcn_s_barrier()
; #define PG8_SCHED __builtin_amdgcn_sched_barrier(0)
; template <class Epi, class Sched, bool ALIGN_EPI = false, bool SP2 = false>
; __device__ __forceinline__ void gemm_phase(PG8_LAS unsigned char* lds, const Gemm g, const Sched& S, const Epi& E) {
;     ...
;             const bool last = (t == nt - 2);
;             const char* a1 = cA + (size_t)(t + 1) * kstep;
;             const char* a2 = last ? nA : cA + (size_t)(t + 2) * kstep; const char* b2 = last ? nB : cB + (size_t)(t + 2) * kstep;
;             const char* a3 = a2 + kstep; const char* b3 = b2 + kstep;
;             if (last && has_next) S.a_ready(nxt);
;             if constexpr (SP2) {
;             PG8_LDB(B0, 0, 0); PG8_LDB(B1, 0, 1); PG8_SCHED; PG8_LDA(At, 0, 0); PG8_STAGE(PG8_SA(1, 1), a1 + hstep, voffA);
;             PG8_WAIT_V(8); PG8_WAIT_L(0); PG8_BAR; PG8_MMA(0, 0, At, B0); PG8_MMA(0, 1, At, B1); PG8_BAR; PG8_SCHED;
;             PG8_LDA(At, 0, 1); PG8_STAGE(PG8_SB(0, 0), b2, voffB); PG8_STAGE(PG8_SB(0, 1), b2 + hstep, voffB); PG8_STAGE(PG8_SA(0, 0), a2, voffA);
.Lpeel291:
	s_add_u32 s84, s8, 0x100
	s_addc_u32 s85, s9, 0
	s_add_i32 s66, 0, 0x10000
	s_cmp_eq_u32 s10, 12
	s_cselect_b32 vcc_hi, s5, s85
	s_cselect_b32 vcc_lo, s7, s84
	s_cselect_b32 s97, s11, s68
	s_cselect_b32 s96, s67, s69
	s_add_i32 s70, 0, 0x14000
	v_add_u32_e32 v110, s66, v175
	v_add_u32_e32 v168, s70, v175
	s_waitcnt vmcnt(0)
	ds_read_b128 v[66:69], v110
	ds_read_b128 v[70:73], v110 offset:1024
	ds_read_b128 v[106:109], v110 offset:2048
	ds_read_b128 v[110:113], v110 offset:3072
	ds_read_b128 v[114:117], v168
	ds_read_b128 v[118:121], v168 offset:1024
	ds_read_b128 v[126:129], v168 offset:2048
	ds_read_b128 v[178:181], v168 offset:3072
	v_lshl_add_u64 v[168:169], s[8:9], 0, v[164:165]
	s_add_i32 m0, s1, 0xc000
	ds_read_b128 v[182:185], v177
	ds_read_b128 v[186:189], v177 offset:1024
	ds_read_b128 v[190:193], v177 offset:2048
	ds_read_b128 v[194:197], v177 offset:3072
	ds_read_b128 v[198:201], v177 offset:4096
	ds_read_b128 v[210:213], v177 offset:5120
	ds_read_b128 v[214:217], v177 offset:6144
	ds_read_b128 v[218:221], v177 offset:7168
	global_load_lds_dwordx4 v[168:169], off
	v_lshl_add_u64 v[168:169], s[8:9], 0, v[166:167]
	s_add_i32 m0, s1, 0xe000
	s_nop 0
	global_load_lds_dwordx4 v[168:169], off
	s_waitcnt vmcnt(8)
	s_waitcnt lgkmcnt(0)
	s_barrier
	s_setprio 1
	s_waitcnt lgkmcnt(0)
	v_mfma_i32_16x16x64_i8 v[154:157], v[66:69], v[182:185], 0
	v_mfma_i32_16x16x64_i8 v[146:149], v[106:109], v[182:185], 0
	v_mfma_i32_16x16x64_i8 v[138:141], v[106:109], v[190:193], 0
	v_mfma_i32_16x16x64_i8 v[150:153], v[66:69], v[190:193], 0
	v_mfma_i32_16x16x64_i8 v[142:145], v[66:69], v[198:201], 0
	v_mfma_i32_16x16x64_i8 v[130:133], v[106:109], v[198:201], 0
	v_mfma_i32_16x16x64_i8 v[122:125], v[106:109], v[214:217], 0
	v_mfma_i32_16x16x64_i8 v[134:137], v[66:69], v[214:217], 0
	v_mfma_i32_16x16x64_i8 v[154:157], v[70:73], v[186:189], v[154:157]
	v_mfma_i32_16x16x64_i8 v[146:149], v[110:113], v[186:189], v[146:149]
	v_mfma_i32_16x16x64_i8 v[138:141], v[110:113], v[194:197], v[138:141]
	v_mfma_i32_16x16x64_i8 v[150:153], v[70:73], v[194:197], v[150:153]
	v_mfma_i32_16x16x64_i8 v[142:145], v[70:73], v[210:213], v[142:145]
	v_mfma_i32_16x16x64_i8 v[130:133], v[110:113], v[210:213], v[130:133]
	v_mfma_i32_16x16x64_i8 v[122:125], v[110:113], v[218:221], v[122:125]
	v_mfma_i32_16x16x64_i8 v[134:137], v[70:73], v[218:221], v[134:137]
	s_setprio 0
	s_setprio 1
	v_mfma_i32_16x16x64_i8 v[102:105], v[114:117], v[182:185], 0
	v_mfma_i32_16x16x64_i8 v[94:97], v[126:129], v[182:185], 0
	v_mfma_i32_16x16x64_i8 v[86:89], v[126:129], v[190:193], 0
	v_mfma_i32_16x16x64_i8 v[98:101], v[114:117], v[190:193], 0
	v_mfma_i32_16x16x64_i8 v[90:93], v[114:117], v[198:201], 0
	v_mfma_i32_16x16x64_i8 v[78:81], v[126:129], v[198:201], 0
	v_mfma_i32_16x16x64_i8 v[74:77], v[126:129], v[214:217], 0
	v_mfma_i32_16x16x64_i8 v[82:85], v[114:117], v[214:217], 0
	v_mfma_i32_16x16x64_i8 v[102:105], v[118:121], v[186:189], v[102:105]
	v_mfma_i32_16x16x64_i8 v[94:97], v[178:181], v[186:189], v[94:97]
	v_mfma_i32_16x16x64_i8 v[86:89], v[178:181], v[194:197], v[86:89]
	v_mfma_i32_16x16x64_i8 v[98:101], v[118:121], v[194:197], v[98:101]
	v_mfma_i32_16x16x64_i8 v[90:93], v[118:121], v[210:213], v[90:93]
	v_mfma_i32_16x16x64_i8 v[78:81], v[178:181], v[210:213], v[78:81]
	v_mfma_i32_16x16x64_i8 v[74:77], v[178:181], v[218:221], v[74:77]
	v_mfma_i32_16x16x64_i8 v[82:85], v[118:121], v[218:221], v[82:85]
	s_setprio 0
	s_barrier
	s_add_i32 s8, s66, s81
	v_lshl_add_u64 v[168:169], s[96:97], 0, v[0:1]
	s_mov_b32 m0, s8
	ds_read_b128 v[182:185], v177 offset:16384
	ds_read_b128 v[186:189], v177 offset:17408
	ds_read_b128 v[190:193], v177 offset:18432
	ds_read_b128 v[194:197], v177 offset:19456
	ds_read_b128 v[198:201], v177 offset:20480
	ds_read_b128 v[210:213], v177 offset:21504
	ds_read_b128 v[214:217], v177 offset:22528
	ds_read_b128 v[218:221], v177 offset:23552
	global_load_lds_dwordx4 v[168:169], off
	s_add_i32 m0, s8, 0x2000
	s_add_u32 s8, s96, 0x40000
	v_lshl_add_u64 v[206:207], s[96:97], 0, v[158:159]
	s_addc_u32 s9, s97, 0
	s_add_i32 s66, s70, s81
	global_load_lds_dwordx4 v[206:207], off
	v_lshl_add_u64 v[222:223], s[8:9], 0, v[0:1]
	s_mov_b32 m0, s66
	v_lshl_add_u64 v[224:225], vcc, 0, v[160:161]
	global_load_lds_dwordx4 v[222:223], off
	v_lshl_add_u64 v[222:223], s[8:9], 0, v[158:159]
	s_add_i32 m0, s66, 0x2000
	s_nop 0
	global_load_lds_dwordx4 v[222:223], off
	v_lshl_add_u64 v[222:223], vcc, 0, v[162:163]
	s_mov_b32 m0, s1
	s_nop 0
	global_load_lds_dwordx4 v[222:223], off
	s_mov_b32 m0, s58
	s_nop 0
	global_load_lds_dwordx4 v[224:225], off
	s_waitcnt vmcnt(8)
	s_waitcnt lgkmcnt(0)
	s_barrier
; #define PG8_STAGE(bufoff, gbase, voff) do { _Pragma("unroll") for (int _i = 0; _i < 2; ++_i) \
;         __builtin_amdgcn_global_load_lds((const unsigned*)((const char*)(gbase) + (voff)[_i]), (PG8_LAS unsigned*)(lds + (bufoff) + ldsw + _i * 8192), 16, 0, 0); } while (0)
; #define PG8_LDA(dst, b, h) do { _Pragma("unroll") for (int m = 0; m < 4; ++m) _Pragma("unroll") for (int k = 0; k < 2; ++k) dst[m][k] = *(const PG8_LAS bf16x8*)(lds + PG8_SA(b, h) + aoff + m * 2048 + k * 1024); } while (0)
; #define PG8_LDB(dst, b, h) do { _Pragma("unroll") for (int n = 0; n < 2; ++n) _Pragma("unroll") for (int k = 0; k < 2; ++k) dst[n][k] = *(const PG8_LAS bf16x8*)(lds + PG8_SB(b, h) + boff + n * 2048 + k * 1024); } while (0)
; template <bool I8> __device__ __forceinline__ f32x4 mma16(bf16x8 b, bf16x8 a, f32x4 c) {
;     if constexpr (I8) { typedef int i32x4 __attribute__((ext_vector_type(4)));
;         return __builtin_bit_cast(f32x4, __builtin_amdgcn_mfma_i32_16x16x64_i8(__builtin_bit_cast(i32x4, b), __builtin_bit_cast(i32x4, a), __builtin_bit_cast(i32x4, c), 0, 0, 0)); }
;     else return __builtin_amdgcn_mfma_f32_16x16x32_bf16(b, a, c, 0, 0, 0);
; template <class Epi, class Sched, bool ALIGN_EPI = false, bool SP2 = false>
; __device__ __forceinline__ void gemm_phase(PG8_LAS unsigned char* lds, const Gemm g, const Sched& S, const Epi& E) {
;     ...
;             PG8_LDB(B0, 0, 0); PG8_LDB(B1, 0, 1); PG8_SCHED; PG8_LDA(At, 0, 0); PG8_STAGE(PG8_SA(1, 1), a1 + hstep, voffA);
;             PG8_WAIT_V(8); PG8_WAIT_L(0); PG8_BAR; PG8_MMA(0, 0, At, B0); PG8_MMA(0, 1, At, B1); PG8_BAR; PG8_SCHED;
;             PG8_LDA(At, 0, 1); PG8_STAGE(PG8_SB(0, 0), b2, voffB); PG8_STAGE(PG8_SB(0, 1), b2 + hstep, voffB); PG8_STAGE(PG8_SA(0, 0), a2, voffA);
;             PG8_WAIT_V(8); PG8_WAIT_L(0); PG8_BAR; PG8_MMA(1, 0, At, B0); PG8_MMA(1, 1, At, B1); PG8_BAR; PG8_SCHED;
;             PG8_LDB(B0, 1, 0); PG8_LDB(B1, 1, 1); PG8_SCHED; PG8_LDA(At, 1, 0); PG8_STAGE(PG8_SA(0, 1), a2 + hstep, voffA);
;             PG8_WAIT_V(8); PG8_WAIT_L(0); PG8_BAR; PG8_MMA(0, 0, At, B0); PG8_MMA(0, 1, At, B1); PG8_BAR; PG8_SCHED;
;             PG8_LDA(At, 1, 1); PG8_STAGE(PG8_SB(1, 0), b3, voffB); PG8_STAGE(PG8_SB(1, 1), b3 + hstep, voffB); PG8_STAGE(PG8_SA(1, 0), a3, voffA);
;             PG8_WAIT_V(8); PG8_WAIT_L(0); PG8_BAR; PG8_MMA(1, 0, At, B0); PG8_MMA(1, 1, At, B1); PG8_BAR; PG8_SCHED;
	s_setprio 1
	s_waitcnt lgkmcnt(0)
	v_mfma_i32_16x16x64_i8 v[62:65], v[66:69], v[182:185], 0
	v_mfma_i32_16x16x64_i8 v[54:57], v[106:109], v[182:185], 0
	v_mfma_i32_16x16x64_i8 v[46:49], v[106:109], v[190:193], 0
	v_mfma_i32_16x16x64_i8 v[58:61], v[66:69], v[190:193], 0
	v_mfma_i32_16x16x64_i8 v[50:53], v[66:69], v[198:201], 0
	v_mfma_i32_16x16x64_i8 v[38:41], v[106:109], v[198:201], 0
	v_mfma_i32_16x16x64_i8 v[34:37], v[106:109], v[214:217], 0
	v_mfma_i32_16x16x64_i8 v[42:45], v[66:69], v[214:217], 0
	v_mfma_i32_16x16x64_i8 v[62:65], v[70:73], v[186:189], v[62:65]
	v_mfma_i32_16x16x64_i8 v[54:57], v[110:113], v[186:189], v[54:57]
	v_mfma_i32_16x16x64_i8 v[46:49], v[110:113], v[194:197], v[46:49]
	v_mfma_i32_16x16x64_i8 v[58:61], v[70:73], v[194:197], v[58:61]
	v_mfma_i32_16x16x64_i8 v[50:53], v[70:73], v[210:213], v[50:53]
	v_mfma_i32_16x16x64_i8 v[38:41], v[110:113], v[210:213], v[38:41]
	v_mfma_i32_16x16x64_i8 v[34:37], v[110:113], v[218:221], v[34:37]
	v_mfma_i32_16x16x64_i8 v[42:45], v[70:73], v[218:221], v[42:45]
	s_setprio 0
	s_setprio 1
	v_mfma_i32_16x16x64_i8 v[30:33], v[114:117], v[182:185], 0
	v_mfma_i32_16x16x64_i8 v[22:25], v[126:129], v[182:185], 0
	v_mfma_i32_16x16x64_i8 v[14:17], v[126:129], v[190:193], 0
	v_mfma_i32_16x16x64_i8 v[26:29], v[114:117], v[190:193], 0
	v_mfma_i32_16x16x64_i8 v[18:21], v[114:117], v[198:201], 0
	v_mfma_i32_16x16x64_i8 v[6:9], v[126:129], v[198:201], 0
	v_mfma_i32_16x16x64_i8 v[2:5], v[126:129], v[214:217], 0
	v_mfma_i32_16x16x64_i8 v[10:13], v[114:117], v[214:217], 0
	v_mfma_i32_16x16x64_i8 v[30:33], v[118:121], v[186:189], v[30:33]
	v_mfma_i32_16x16x64_i8 v[22:25], v[178:181], v[186:189], v[22:25]
	v_mfma_i32_16x16x64_i8 v[14:17], v[178:181], v[194:197], v[14:17]
	v_mfma_i32_16x16x64_i8 v[26:29], v[118:121], v[194:197], v[26:29]
	v_mfma_i32_16x16x64_i8 v[18:21], v[118:121], v[210:213], v[18:21]
	v_mfma_i32_16x16x64_i8 v[6:9], v[178:181], v[210:213], v[6:9]
	v_mfma_i32_16x16x64_i8 v[2:5], v[178:181], v[218:221], v[2:5]
	v_mfma_i32_16x16x64_i8 v[10:13], v[118:121], v[218:221], v[10:13]
	s_setprio 0
	s_barrier
	s_add_i32 s66, 0, 0x18000
	s_add_i32 s70, 0, 0x1c000
	v_add_u32_e32 v110, s66, v175
	v_add_u32_e32 v170, s70, v175
	ds_read_b128 v[66:69], v110
	ds_read_b128 v[70:73], v110 offset:1024
	ds_read_b128 v[106:109], v110 offset:2048
	ds_read_b128 v[110:113], v110 offset:3072
	ds_read_b128 v[114:117], v170
	ds_read_b128 v[118:121], v170 offset:1024
	ds_read_b128 v[126:129], v170 offset:2048
	ds_read_b128 v[178:181], v170 offset:3072
	s_add_u32 s8, vcc_lo, 0x40000
	s_addc_u32 s9, vcc_hi, 0
	s_mov_b32 m0, s80
	v_lshl_add_u64 v[226:227], s[8:9], 0, v[162:163]
	ds_read_b128 v[182:185], v177 offset:32768
	ds_read_b128 v[186:189], v177 offset:33792
	ds_read_b128 v[190:193], v177 offset:34816
	ds_read_b128 v[194:197], v177 offset:35840
	ds_read_b128 v[198:201], v177 offset:36864
	ds_read_b128 v[210:213], v177 offset:37888
	ds_read_b128 v[214:217], v177 offset:38912
	ds_read_b128 v[218:221], v177 offset:39936
	global_load_lds_dwordx4 v[226:227], off
	v_lshl_add_u64 v[226:227], s[8:9], 0, v[160:161]
	s_mov_b32 m0, s0
	s_nop 0
	global_load_lds_dwordx4 v[226:227], off
	s_waitcnt vmcnt(8)
	s_waitcnt lgkmcnt(0)
	s_barrier
	s_setprio 1
	s_waitcnt lgkmcnt(0)
	v_mfma_i32_16x16x64_i8 v[154:157], v[66:69], v[182:185], v[154:157]
	v_mfma_i32_16x16x64_i8 v[146:149], v[106:109], v[182:185], v[146:149]
	v_mfma_i32_16x16x64_i8 v[138:141], v[106:109], v[190:193], v[138:141]
	v_mfma_i32_16x16x64_i8 v[150:153], v[66:69], v[190:193], v[150:153]
	v_mfma_i32_16x16x64_i8 v[142:145], v[66:69], v[198:201], v[142:145]
	v_mfma_i32_16x16x64_i8 v[130:133], v[106:109], v[198:201], v[130:133]
	v_mfma_i32_16x16x64_i8 v[122:125], v[106:109], v[214:217], v[122:125]
	v_mfma_i32_16x16x64_i8 v[134:137], v[66:69], v[214:217], v[134:137]
	v_mfma_i32_16x16x64_i8 v[154:157], v[70:73], v[186:189], v[154:157]
	v_mfma_i32_16x16x64_i8 v[146:149], v[110:113], v[186:189], v[146:149]
	v_mfma_i32_16x16x64_i8 v[138:141], v[110:113], v[194:197], v[138:141]
	v_mfma_i32_16x16x64_i8 v[150:153], v[70:73], v[194:197], v[150:153]
	v_mfma_i32_16x16x64_i8 v[142:145], v[70:73], v[210:213], v[142:145]
	v_mfma_i32_16x16x64_i8 v[130:133], v[110:113], v[210:213], v[130:133]
	v_mfma_i32_16x16x64_i8 v[122:125], v[110:113], v[218:221], v[122:125]
	v_mfma_i32_16x16x64_i8 v[134:137], v[70:73], v[218:221], v[134:137]
	s_setprio 0
	s_setprio 1
	v_mfma_i32_16x16x64_i8 v[102:105], v[114:117], v[182:185], v[102:105]
	v_mfma_i32_16x16x64_i8 v[94:97], v[126:129], v[182:185], v[94:97]
	v_mfma_i32_16x16x64_i8 v[86:89], v[126:129], v[190:193], v[86:89]
	v_mfma_i32_16x16x64_i8 v[98:101], v[114:117], v[190:193], v[98:101]
	v_mfma_i32_16x16x64_i8 v[90:93], v[114:117], v[198:201], v[90:93]
	v_mfma_i32_16x16x64_i8 v[78:81], v[126:129], v[198:201], v[78:81]
	v_mfma_i32_16x16x64_i8 v[74:77], v[126:129], v[214:217], v[74:77]
	v_mfma_i32_16x16x64_i8 v[82:85], v[114:117], v[214:217], v[82:85]
	v_mfma_i32_16x16x64_i8 v[102:105], v[118:121], v[186:189], v[102:105]
	v_mfma_i32_16x16x64_i8 v[94:97], v[178:181], v[186:189], v[94:97]
	v_mfma_i32_16x16x64_i8 v[86:89], v[178:181], v[194:197], v[86:89]
	v_mfma_i32_16x16x64_i8 v[98:101], v[118:121], v[194:197], v[98:101]
	v_mfma_i32_16x16x64_i8 v[90:93], v[118:121], v[210:213], v[90:93]
	v_mfma_i32_16x16x64_i8 v[78:81], v[178:181], v[210:213], v[78:81]
	v_mfma_i32_16x16x64_i8 v[74:77], v[178:181], v[218:221], v[74:77]
	v_mfma_i32_16x16x64_i8 v[82:85], v[118:121], v[218:221], v[82:85]
	s_setprio 0
	s_barrier
; #define PG8_STAGE(bufoff, gbase, voff) do { _Pragma("unroll") for (int _i = 0; _i < 2; ++_i) \
;         __builtin_amdgcn_global_load_lds((const unsigned*)((const char*)(gbase) + (voff)[_i]), (PG8_LAS unsigned*)(lds + (bufoff) + ldsw + _i * 8192), 16, 0, 0); } while (0)
; #define PG8_LDA(dst, b, h) do { _Pragma("unroll") for (int m = 0; m < 4; ++m) _Pragma("unroll") for (int k = 0; k < 2; ++k) dst[m][k] = *(const PG8_LAS bf16x8*)(lds + PG8_SA(b, h) + aoff + m * 2048 + k * 1024); } while (0)
; #define PG8_LDB(dst, b, h) do { _Pragma("unroll") for (int n = 0; n < 2; ++n) _Pragma("unroll") for (int k = 0; k < 2; ++k) dst[n][k] = *(const PG8_LAS bf16x8*)(lds + PG8_SB(b, h) + boff + n * 2048 + k * 1024); } while (0)
; #define PG8_MMA(ai, bj, At, Bt) do { __builtin_amdgcn_s_setprio(1); _Pragma("unroll") for (int m = 0; m < 4; ++m) _Pragma("unroll") for (int n = 0; n < 2; ++n) _Pragma("unroll") for (int k = 0; k < 2; ++k) \
;         acc[ai][bj][m][n] = mma16<Epi::I8>(Bt[n][k], At[m][k], acc[ai][bj][m][n]); __builtin_amdgcn_s_setprio(0); } while (0)
; #define PG8_WAIT_V(n) asm volatile("s_waitcnt vmcnt(" #n ")" ::: "memory")
; template <class Epi, class Sched, bool ALIGN_EPI = false, bool SP2 = false>
; __device__ __forceinline__ void gemm_phase(PG8_LAS unsigned char* lds, const Gemm g, const Sched& S, const Epi& E) {
;     ...
;             PG8_LDB(B0, 0, 0); PG8_LDB(B1, 0, 1); PG8_SCHED; PG8_LDA(At, 0, 0); PG8_STAGE(PG8_SA(1, 1), a1 + hstep, voffA);
;             PG8_WAIT_V(8); PG8_WAIT_L(0); PG8_BAR; PG8_MMA(0, 0, At, B0); PG8_MMA(0, 1, At, B1); PG8_BAR; PG8_SCHED;
;             PG8_LDA(At, 0, 1); PG8_STAGE(PG8_SB(0, 0), b2, voffB); PG8_STAGE(PG8_SB(0, 1), b2 + hstep, voffB); PG8_STAGE(PG8_SA(0, 0), a2, voffA);
;             PG8_WAIT_V(8); PG8_WAIT_L(0); PG8_BAR; PG8_MMA(1, 0, At, B0); PG8_MMA(1, 1, At, B1); PG8_BAR; PG8_SCHED;
;             PG8_LDB(B0, 1, 0); PG8_LDB(B1, 1, 1); PG8_SCHED; PG8_LDA(At, 1, 0); PG8_STAGE(PG8_SA(0, 1), a2 + hstep, voffA);
;             PG8_WAIT_V(8); PG8_WAIT_L(0); PG8_BAR; PG8_MMA(0, 0, At, B0); PG8_MMA(0, 1, At, B1); PG8_BAR; PG8_SCHED;
;             PG8_LDA(At, 1, 1); PG8_STAGE(PG8_SB(1, 0), b3, voffB); PG8_STAGE(PG8_SB(1, 1), b3 + hstep, voffB); PG8_STAGE(PG8_SA(1, 0), a3, voffA);
;             PG8_WAIT_V(8); PG8_WAIT_L(0); PG8_BAR; PG8_MMA(1, 0, At, B0); PG8_MMA(1, 1, At, B1); PG8_BAR; PG8_SCHED;
	s_add_i32 s8, s66, s81
	v_lshl_add_u64 v[168:169], v[168:169], 0, s[92:93]
	s_mov_b32 m0, s8
	ds_read_b128 v[182:185], v177 offset:49152
	ds_read_b128 v[186:189], v177 offset:50176
	ds_read_b128 v[190:193], v177 offset:51200
	ds_read_b128 v[194:197], v177 offset:52224
	ds_read_b128 v[198:201], v177 offset:53248
	ds_read_b128 v[210:213], v177 offset:54272
	ds_read_b128 v[214:217], v177 offset:55296
	ds_read_b128 v[218:221], v177 offset:56320
	global_load_lds_dwordx4 v[168:169], off
	s_add_i32 m0, s8, 0x2000
	s_add_u32 s8, s96, 0x40080
	v_lshl_add_u64 v[168:169], v[206:207], 0, s[92:93]
	s_addc_u32 s9, s97, 0
	s_add_i32 s66, s70, s81
	global_load_lds_dwordx4 v[168:169], off
	v_lshl_add_u64 v[168:169], s[8:9], 0, v[0:1]
	s_mov_b32 m0, s66
	s_nop 0
	global_load_lds_dwordx4 v[168:169], off
	v_lshl_add_u64 v[168:169], s[8:9], 0, v[158:159]
	s_add_i32 m0, s66, 0x2000
	s_nop 0
	global_load_lds_dwordx4 v[168:169], off
	v_lshl_add_u64 v[168:169], v[222:223], 0, s[92:93]
	s_mov_b32 m0, s13
	s_nop 0
	global_load_lds_dwordx4 v[168:169], off
	v_lshl_add_u64 v[168:169], v[224:225], 0, s[92:93]
	s_mov_b32 m0, s12
	s_nop 0
	global_load_lds_dwordx4 v[168:169], off
	s_waitcnt vmcnt(8)
	s_waitcnt lgkmcnt(0)
	s_barrier
	s_setprio 1
	s_waitcnt lgkmcnt(0)
	v_mfma_i32_16x16x64_i8 v[62:65], v[66:69], v[182:185], v[62:65]
	v_mfma_i32_16x16x64_i8 v[54:57], v[106:109], v[182:185], v[54:57]
	v_mfma_i32_16x16x64_i8 v[46:49], v[106:109], v[190:193], v[46:49]
	v_mfma_i32_16x16x64_i8 v[58:61], v[66:69], v[190:193], v[58:61]
	v_mfma_i32_16x16x64_i8 v[50:53], v[66:69], v[198:201], v[50:53]
	v_mfma_i32_16x16x64_i8 v[38:41], v[106:109], v[198:201], v[38:41]
	v_mfma_i32_16x16x64_i8 v[34:37], v[106:109], v[214:217], v[34:37]
	v_mfma_i32_16x16x64_i8 v[42:45], v[66:69], v[214:217], v[42:45]
	v_mfma_i32_16x16x64_i8 v[62:65], v[70:73], v[186:189], v[62:65]
	v_mfma_i32_16x16x64_i8 v[54:57], v[110:113], v[186:189], v[54:57]
	v_mfma_i32_16x16x64_i8 v[46:49], v[110:113], v[194:197], v[46:49]
	v_mfma_i32_16x16x64_i8 v[58:61], v[70:73], v[194:197], v[58:61]
	v_mfma_i32_16x16x64_i8 v[50:53], v[70:73], v[210:213], v[50:53]
	v_mfma_i32_16x16x64_i8 v[38:41], v[110:113], v[210:213], v[38:41]
	v_mfma_i32_16x16x64_i8 v[34:37], v[110:113], v[218:221], v[34:37]
	v_mfma_i32_16x16x64_i8 v[42:45], v[70:73], v[218:221], v[42:45]
	s_setprio 0
	s_setprio 1
	v_mfma_i32_16x16x64_i8 v[30:33], v[114:117], v[182:185], v[30:33]
	v_mfma_i32_16x16x64_i8 v[22:25], v[126:129], v[182:185], v[22:25]
	v_mfma_i32_16x16x64_i8 v[14:17], v[126:129], v[190:193], v[14:17]
	v_mfma_i32_16x16x64_i8 v[26:29], v[114:117], v[190:193], v[26:29]
	v_mfma_i32_16x16x64_i8 v[18:21], v[114:117], v[198:201], v[18:21]
	v_mfma_i32_16x16x64_i8 v[6:9], v[126:129], v[198:201], v[6:9]
	v_mfma_i32_16x16x64_i8 v[2:5], v[126:129], v[214:217], v[2:5]
	v_mfma_i32_16x16x64_i8 v[10:13], v[114:117], v[214:217], v[10:13]
	v_mfma_i32_16x16x64_i8 v[30:33], v[118:121], v[186:189], v[30:33]
	v_mfma_i32_16x16x64_i8 v[22:25], v[178:181], v[186:189], v[22:25]
	v_mfma_i32_16x16x64_i8 v[14:17], v[178:181], v[194:197], v[14:17]
	v_mfma_i32_16x16x64_i8 v[26:29], v[118:121], v[194:197], v[26:29]
	v_mfma_i32_16x16x64_i8 v[18:21], v[118:121], v[210:213], v[18:21]
	v_mfma_i32_16x16x64_i8 v[6:9], v[178:181], v[210:213], v[6:9]
	v_mfma_i32_16x16x64_i8 v[2:5], v[178:181], v[218:221], v[2:5]
	v_mfma_i32_16x16x64_i8 v[10:13], v[118:121], v[218:221], v[10:13]
	s_setprio 0
	s_barrier
	s_add_i32 s10, s10, 2
	s_add_u32 s69, s69, 0x100
	s_addc_u32 s68, s68, 0
	s_cmp_gt_u32 s10, 13
	s_mov_b64 s[8:9], s[84:85]
	s_cbranch_scc0 .LBB0_291
	s_branch .Lpeelx291
.LBB0_291:
	s_add_u32 s84, s8, 0x100
	s_addc_u32 s85, s9, 0
	s_add_i32 s66, 0, 0x10000
	s_cmp_eq_u32 s10, 12
	s_cselect_b32 vcc_hi, s5, s85
	s_cselect_b32 vcc_lo, s7, s84
	s_cselect_b32 s97, s11, s68
	s_cselect_b32 s96, s67, s69
	s_add_i32 s70, 0, 0x14000
	v_add_u32_e32 v110, s66, v175
	v_add_u32_e32 v168, s70, v175
	s_waitcnt vmcnt(0)
	ds_read_b128 v[66:69], v110
	ds_read_b128 v[70:73], v110 offset:1024
	ds_read_b128 v[106:109], v110 offset:2048
	ds_read_b128 v[110:113], v110 offset:3072
	ds_read_b128 v[114:117], v168
	ds_read_b128 v[118:121], v168 offset:1024
	ds_read_b128 v[126:129], v168 offset:2048
	ds_read_b128 v[178:181], v168 offset:3072
	v_lshl_add_u64 v[168:169], s[8:9], 0, v[164:165]
	s_add_i32 m0, s1, 0xc000
	ds_read_b128 v[182:185], v177
	ds_read_b128 v[186:189], v177 offset:1024
	ds_read_b128 v[190:193], v177 offset:2048
	ds_read_b128 v[194:197], v177 offset:3072
	ds_read_b128 v[198:201], v177 offset:4096
	ds_read_b128 v[210:213], v177 offset:5120
	ds_read_b128 v[214:217], v177 offset:6144
	ds_read_b128 v[218:221], v177 offset:7168
	global_load_lds_dwordx4 v[168:169], off
	v_lshl_add_u64 v[168:169], s[8:9], 0, v[166:167]
	s_add_i32 m0, s1, 0xe000
	s_nop 0
	global_load_lds_dwordx4 v[168:169], off
	s_waitcnt vmcnt(8)
	s_waitcnt lgkmcnt(0)
	s_barrier
; #define PG8_STAGE(bufoff, gbase, voff) do { _Pragma("unroll") for (int _i = 0; _i < 2; ++_i) \
;         __builtin_amdgcn_global_load_lds((const unsigned*)((const char*)(gbase) + (voff)[_i]), (PG8_LAS unsigned*)(lds + (bufoff) + ldsw + _i * 8192), 16, 0, 0); } while (0)
; #define PG8_LDA(dst, b, h) do { _Pragma("unroll") for (int m = 0; m < 4; ++m) _Pragma("unroll") for (int k = 0; k < 2; ++k) dst[m][k] = *(const PG8_LAS bf16x8*)(lds + PG8_SA(b, h) + aoff + m * 2048 + k * 1024); } while (0)
; #define PG8_LDB(dst, b, h) do { _Pragma("unroll") for (int n = 0; n < 2; ++n) _Pragma("unroll") for (int k = 0; k < 2; ++k) dst[n][k] = *(const PG8_LAS bf16x8*)(lds + PG8_SB(b, h) + boff + n * 2048 + k * 1024); } while (0)
; #define PG8_MMA(ai, bj, At, Bt) do { __builtin_amdgcn_s_setprio(1); _Pragma("unroll") for (int m = 0; m < 4; ++m) _Pragma("unroll") for (int n = 0; n < 2; ++n) _Pragma("unroll") for (int k = 0; k < 2; ++k) \
;         acc[ai][bj][m][n] = mma16<Epi::I8>(Bt[n][k], At[m][k], acc[ai][bj][m][n]); __builtin_amdgcn_s_setprio(0); } while (0)
; #define PG8_WAIT_V(n) asm volatile("s_waitcnt vmcnt(" #n ")" ::: "memory")
; template <class Epi, class Sched, bool ALIGN_EPI = false, bool SP2 = false>
; __device__ __forceinline__ void gemm_phase(PG8_LAS unsigned char* lds, const Gemm g, const Sched& S, const Epi& E) {
;     ...
;             PG8_LDB(B0, 0, 0); PG8_LDB(B1, 0, 1); PG8_SCHED; PG8_LDA(At, 0, 0); PG8_STAGE(PG8_SA(1, 1), a1 + hstep, voffA);
;             PG8_WAIT_V(8); PG8_WAIT_L(0); PG8_BAR; PG8_MMA(0, 0, At, B0); PG8_MMA(0, 1, At, B1); PG8_BAR; PG8_SCHED;
;             PG8_LDA(At, 0, 1); PG8_STAGE(PG8_SB(0, 0), b2, voffB); PG8_STAGE(PG8_SB(0, 1), b2 + hstep, voffB); PG8_STAGE(PG8_SA(0, 0), a2, voffA);
;             PG8_WAIT_V(8); PG8_WAIT_L(0); PG8_BAR; PG8_MMA(1, 0, At, B0); PG8_MMA(1, 1, At, B1); PG8_BAR; PG8_SCHED;
;             PG8_LDB(B0, 1, 0); PG8_LDB(B1, 1, 1); PG8_SCHED; PG8_LDA(At, 1, 0); PG8_STAGE(PG8_SA(0, 1), a2 + hstep, voffA);
;             PG8_WAIT_V(8); PG8_WAIT_L(0); PG8_BAR; PG8_MMA(0, 0, At, B0); PG8_MMA(0, 1, At, B1); PG8_BAR; PG8_SCHED;
;             PG8_LDA(At, 1, 1); PG8_STAGE(PG8_SB(1, 0), b3, voffB); PG8_STAGE(PG8_SB(1, 1), b3 + hstep, voffB); PG8_STAGE(PG8_SA(1, 0), a3, voffA);
;             PG8_WAIT_V(8); PG8_WAIT_L(0); PG8_BAR; PG8_MMA(1, 0, At, B0); PG8_MMA(1, 1, At, B1); PG8_BAR; PG8_SCHED;
	s_setprio 1
	s_waitcnt lgkmcnt(0)
	v_mfma_i32_16x16x64_i8 v[154:157], v[66:69], v[182:185], v[154:157]
	v_mfma_i32_16x16x64_i8 v[146:149], v[106:109], v[182:185], v[146:149]
	v_mfma_i32_16x16x64_i8 v[138:141], v[106:109], v[190:193], v[138:141]
	v_mfma_i32_16x16x64_i8 v[150:153], v[66:69], v[190:193], v[150:153]
	v_mfma_i32_16x16x64_i8 v[142:145], v[66:69], v[198:201], v[142:145]
	v_mfma_i32_16x16x64_i8 v[130:133], v[106:109], v[198:201], v[130:133]
	v_mfma_i32_16x16x64_i8 v[122:125], v[106:109], v[214:217], v[122:125]
	v_mfma_i32_16x16x64_i8 v[134:137], v[66:69], v[214:217], v[134:137]
	v_mfma_i32_16x16x64_i8 v[154:157], v[70:73], v[186:189], v[154:157]
	v_mfma_i32_16x16x64_i8 v[146:149], v[110:113], v[186:189], v[146:149]
	v_mfma_i32_16x16x64_i8 v[138:141], v[110:113], v[194:197], v[138:141]
	v_mfma_i32_16x16x64_i8 v[150:153], v[70:73], v[194:197], v[150:153]
	v_mfma_i32_16x16x64_i8 v[142:145], v[70:73], v[210:213], v[142:145]
	v_mfma_i32_16x16x64_i8 v[130:133], v[110:113], v[210:213], v[130:133]
	v_mfma_i32_16x16x64_i8 v[122:125], v[110:113], v[218:221], v[122:125]
	v_mfma_i32_16x16x64_i8 v[134:137], v[70:73], v[218:221], v[134:137]
	s_setprio 0
	s_setprio 1
	v_mfma_i32_16x16x64_i8 v[102:105], v[114:117], v[182:185], v[102:105]
	v_mfma_i32_16x16x64_i8 v[94:97], v[126:129], v[182:185], v[94:97]
	v_mfma_i32_16x16x64_i8 v[86:89], v[126:129], v[190:193], v[86:89]
	v_mfma_i32_16x16x64_i8 v[98:101], v[114:117], v[190:193], v[98:101]
	v_mfma_i32_16x16x64_i8 v[90:93], v[114:117], v[198:201], v[90:93]
	v_mfma_i32_16x16x64_i8 v[78:81], v[126:129], v[198:201], v[78:81]
	v_mfma_i32_16x16x64_i8 v[74:77], v[126:129], v[214:217], v[74:77]
	v_mfma_i32_16x16x64_i8 v[82:85], v[114:117], v[214:217], v[82:85]
	v_mfma_i32_16x16x64_i8 v[102:105], v[118:121], v[186:189], v[102:105]
	v_mfma_i32_16x16x64_i8 v[94:97], v[178:181], v[186:189], v[94:97]
	v_mfma_i32_16x16x64_i8 v[86:89], v[178:181], v[194:197], v[86:89]
	v_mfma_i32_16x16x64_i8 v[98:101], v[118:121], v[194:197], v[98:101]
	v_mfma_i32_16x16x64_i8 v[90:93], v[118:121], v[210:213], v[90:93]
	v_mfma_i32_16x16x64_i8 v[78:81], v[178:181], v[210:213], v[78:81]
	v_mfma_i32_16x16x64_i8 v[74:77], v[178:181], v[218:221], v[74:77]
	v_mfma_i32_16x16x64_i8 v[82:85], v[118:121], v[218:221], v[82:85]
	s_setprio 0
	s_barrier
	s_add_i32 s8, s66, s81
	v_lshl_add_u64 v[168:169], s[96:97], 0, v[0:1]
	s_mov_b32 m0, s8
	ds_read_b128 v[182:185], v177 offset:16384
	ds_read_b128 v[186:189], v177 offset:17408
	ds_read_b128 v[190:193], v177 offset:18432
	ds_read_b128 v[194:197], v177 offset:19456
	ds_read_b128 v[198:201], v177 offset:20480
	ds_read_b128 v[210:213], v177 offset:21504
	ds_read_b128 v[214:217], v177 offset:22528
	ds_read_b128 v[218:221], v177 offset:23552
	global_load_lds_dwordx4 v[168:169], off
	s_add_i32 m0, s8, 0x2000
	s_add_u32 s8, s96, 0x40000
	v_lshl_add_u64 v[206:207], s[96:97], 0, v[158:159]
	s_addc_u32 s9, s97, 0
	s_add_i32 s66, s70, s81
	global_load_lds_dwordx4 v[206:207], off
	v_lshl_add_u64 v[222:223], s[8:9], 0, v[0:1]
	s_mov_b32 m0, s66
	v_lshl_add_u64 v[224:225], vcc, 0, v[160:161]
	global_load_lds_dwordx4 v[222:223], off
	v_lshl_add_u64 v[222:223], s[8:9], 0, v[158:159]
	s_add_i32 m0, s66, 0x2000
	s_nop 0
	global_load_lds_dwordx4 v[222:223], off
	v_lshl_add_u64 v[222:223], vcc, 0, v[162:163]
	s_mov_b32 m0, s1
	s_nop 0
	global_load_lds_dwordx4 v[222:223], off
	s_mov_b32 m0, s58
	s_nop 0
	global_load_lds_dwordx4 v[224:225], off
	s_waitcnt vmcnt(8)
	s_waitcnt lgkmcnt(0)
	s_barrier
	s_setprio 1
	s_waitcnt lgkmcnt(0)
	v_mfma_i32_16x16x64_i8 v[62:65], v[66:69], v[182:185], v[62:65]
	v_mfma_i32_16x16x64_i8 v[54:57], v[106:109], v[182:185], v[54:57]
	v_mfma_i32_16x16x64_i8 v[46:49], v[106:109], v[190:193], v[46:49]
	v_mfma_i32_16x16x64_i8 v[58:61], v[66:69], v[190:193], v[58:61]
	v_mfma_i32_16x16x64_i8 v[50:53], v[66:69], v[198:201], v[50:53]
	v_mfma_i32_16x16x64_i8 v[38:41], v[106:109], v[198:201], v[38:41]
	v_mfma_i32_16x16x64_i8 v[34:37], v[106:109], v[214:217], v[34:37]
	v_mfma_i32_16x16x64_i8 v[42:45], v[66:69], v[214:217], v[42:45]
	v_mfma_i32_16x16x64_i8 v[62:65], v[70:73], v[186:189], v[62:65]
	v_mfma_i32_16x16x64_i8 v[54:57], v[110:113], v[186:189], v[54:57]
	v_mfma_i32_16x16x64_i8 v[46:49], v[110:113], v[194:197], v[46:49]
	v_mfma_i32_16x16x64_i8 v[58:61], v[70:73], v[194:197], v[58:61]
	v_mfma_i32_16x16x64_i8 v[50:53], v[70:73], v[210:213], v[50:53]
	v_mfma_i32_16x16x64_i8 v[38:41], v[110:113], v[210:213], v[38:41]
	v_mfma_i32_16x16x64_i8 v[34:37], v[110:113], v[218:221], v[34:37]
	v_mfma_i32_16x16x64_i8 v[42:45], v[70:73], v[218:221], v[42:45]
	s_setprio 0
	s_setprio 1
	v_mfma_i32_16x16x64_i8 v[30:33], v[114:117], v[182:185], v[30:33]
	v_mfma_i32_16x16x64_i8 v[22:25], v[126:129], v[182:185], v[22:25]
	v_mfma_i32_16x16x64_i8 v[14:17], v[126:129], v[190:193], v[14:17]
	v_mfma_i32_16x16x64_i8 v[26:29], v[114:117], v[190:193], v[26:29]
	v_mfma_i32_16x16x64_i8 v[18:21], v[114:117], v[198:201], v[18:21]
	v_mfma_i32_16x16x64_i8 v[6:9], v[126:129], v[198:201], v[6:9]
	v_mfma_i32_16x16x64_i8 v[2:5], v[126:129], v[214:217], v[2:5]
	v_mfma_i32_16x16x64_i8 v[10:13], v[114:117], v[214:217], v[10:13]
	v_mfma_i32_16x16x64_i8 v[30:33], v[118:121], v[186:189], v[30:33]
	v_mfma_i32_16x16x64_i8 v[22:25], v[178:181], v[186:189], v[22:25]
	v_mfma_i32_16x16x64_i8 v[14:17], v[178:181], v[194:197], v[14:17]
	v_mfma_i32_16x16x64_i8 v[26:29], v[118:121], v[194:197], v[26:29]
	v_mfma_i32_16x16x64_i8 v[18:21], v[118:121], v[210:213], v[18:21]
	v_mfma_i32_16x16x64_i8 v[6:9], v[178:181], v[210:213], v[6:9]
	v_mfma_i32_16x16x64_i8 v[2:5], v[178:181], v[218:221], v[2:5]
	v_mfma_i32_16x16x64_i8 v[10:13], v[118:121], v[218:221], v[10:13]
	s_setprio 0
	s_barrier
; #define PG8_STAGE(bufoff, gbase, voff) do { _Pragma("unroll") for (int _i = 0; _i < 2; ++_i) \
;         __builtin_amdgcn_global_load_lds((const unsigned*)((const char*)(gbase) + (voff)[_i]), (PG8_LAS unsigned*)(lds + (bufoff) + ldsw + _i * 8192), 16, 0, 0); } while (0)
; #define PG8_LDA(dst, b, h) do { _Pragma("unroll") for (int m = 0; m < 4; ++m) _Pragma("unroll") for (int k = 0; k < 2; ++k) dst[m][k] = *(const PG8_LAS bf16x8*)(lds + PG8_SA(b, h) + aoff + m * 2048 + k * 1024); } while (0)
; #define PG8_LDB(dst, b, h) do { _Pragma("unroll") for (int n = 0; n < 2; ++n) _Pragma("unroll") for (int k = 0; k < 2; ++k) dst[n][k] = *(const PG8_LAS bf16x8*)(lds + PG8_SB(b, h) + boff + n * 2048 + k * 1024); } while (0)
; #define PG8_MMA(ai, bj, At, Bt) do { __builtin_amdgcn_s_setprio(1); _Pragma("unroll") for (int m = 0; m < 4; ++m) _Pragma("unroll") for (int n = 0; n < 2; ++n) _Pragma("unroll") for (int k = 0; k < 2; ++k) \
;         acc[ai][bj][m][n] = mma16<Epi::I8>(Bt[n][k], At[m][k], acc[ai][bj][m][n]); __builtin_amdgcn_s_setprio(0); } while (0)
; #define PG8_WAIT_V(n) asm volatile("s_waitcnt vmcnt(" #n ")" ::: "memory")
; template <class Epi, class Sched, bool ALIGN_EPI = false, bool SP2 = false>
; __device__ __forceinline__ void gemm_phase(PG8_LAS unsigned char* lds, const Gemm g, const Sched& S, const Epi& E) {
;     ...
;             PG8_LDB(B0, 0, 0); PG8_LDB(B1, 0, 1); PG8_SCHED; PG8_LDA(At, 0, 0); PG8_STAGE(PG8_SA(1, 1), a1 + hstep, voffA);
;             PG8_WAIT_V(8); PG8_WAIT_L(0); PG8_BAR; PG8_MMA(0, 0, At, B0); PG8_MMA(0, 1, At, B1); PG8_BAR; PG8_SCHED;
;             PG8_LDA(At, 0, 1); PG8_STAGE(PG8_SB(0, 0), b2, voffB); PG8_STAGE(PG8_SB(0, 1), b2 + hstep, voffB); PG8_STAGE(PG8_SA(0, 0), a2, voffA);
;             PG8_WAIT_V(8); PG8_WAIT_L(0); PG8_BAR; PG8_MMA(1, 0, At, B0); PG8_MMA(1, 1, At, B1); PG8_BAR; PG8_SCHED;
;             PG8_LDB(B0, 1, 0); PG8_LDB(B1, 1, 1); PG8_SCHED; PG8_LDA(At, 1, 0); PG8_STAGE(PG8_SA(0, 1), a2 + hstep, voffA);
;             PG8_WAIT_V(8); PG8_WAIT_L(0); PG8_BAR; PG8_MMA(0, 0, At, B0); PG8_MMA(0, 1, At, B1); PG8_BAR; PG8_SCHED;
;             PG8_LDA(At, 1, 1); PG8_STAGE(PG8_SB(1, 0), b3, voffB); PG8_STAGE(PG8_SB(1, 1), b3 + hstep, voffB); PG8_STAGE(PG8_SA(1, 0), a3, voffA);
;             PG8_WAIT_V(8); PG8_WAIT_L(0); PG8_BAR; PG8_MMA(1, 0, At, B0); PG8_MMA(1, 1, At, B1); PG8_BAR; PG8_SCHED;
	s_add_i32 s66, 0, 0x18000
	s_add_i32 s70, 0, 0x1c000
	v_add_u32_e32 v110, s66, v175
	v_add_u32_e32 v170, s70, v175
	ds_read_b128 v[66:69], v110
	ds_read_b128 v[70:73], v110 offset:1024
	ds_read_b128 v[106:109], v110 offset:2048
	ds_read_b128 v[110:113], v110 offset:3072
	ds_read_b128 v[114:117], v170
	ds_read_b128 v[118:121], v170 offset:1024
	ds_read_b128 v[126:129], v170 offset:2048
	ds_read_b128 v[178:181], v170 offset:3072
	s_add_u32 s8, vcc_lo, 0x40000
	s_addc_u32 s9, vcc_hi, 0
	s_mov_b32 m0, s80
	v_lshl_add_u64 v[226:227], s[8:9], 0, v[162:163]
	ds_read_b128 v[182:185], v177 offset:32768
	ds_read_b128 v[186:189], v177 offset:33792
	ds_read_b128 v[190:193], v177 offset:34816
	ds_read_b128 v[194:197], v177 offset:35840
	ds_read_b128 v[198:201], v177 offset:36864
	ds_read_b128 v[210:213], v177 offset:37888
	ds_read_b128 v[214:217], v177 offset:38912
	ds_read_b128 v[218:221], v177 offset:39936
	global_load_lds_dwordx4 v[226:227], off
	v_lshl_add_u64 v[226:227], s[8:9], 0, v[160:161]
	s_mov_b32 m0, s0
	s_nop 0
	global_load_lds_dwordx4 v[226:227], off
	s_waitcnt vmcnt(8)
	s_waitcnt lgkmcnt(0)
	s_barrier
	s_setprio 1
	s_waitcnt lgkmcnt(0)
	v_mfma_i32_16x16x64_i8 v[154:157], v[66:69], v[182:185], v[154:157]
	v_mfma_i32_16x16x64_i8 v[146:149], v[106:109], v[182:185], v[146:149]
	v_mfma_i32_16x16x64_i8 v[138:141], v[106:109], v[190:193], v[138:141]
	v_mfma_i32_16x16x64_i8 v[150:153], v[66:69], v[190:193], v[150:153]
	v_mfma_i32_16x16x64_i8 v[142:145], v[66:69], v[198:201], v[142:145]
	v_mfma_i32_16x16x64_i8 v[130:133], v[106:109], v[198:201], v[130:133]
	v_mfma_i32_16x16x64_i8 v[122:125], v[106:109], v[214:217], v[122:125]
	v_mfma_i32_16x16x64_i8 v[134:137], v[66:69], v[214:217], v[134:137]
	v_mfma_i32_16x16x64_i8 v[154:157], v[70:73], v[186:189], v[154:157]
	v_mfma_i32_16x16x64_i8 v[146:149], v[110:113], v[186:189], v[146:149]
	v_mfma_i32_16x16x64_i8 v[138:141], v[110:113], v[194:197], v[138:141]
	v_mfma_i32_16x16x64_i8 v[150:153], v[70:73], v[194:197], v[150:153]
	v_mfma_i32_16x16x64_i8 v[142:145], v[70:73], v[210:213], v[142:145]
	v_mfma_i32_16x16x64_i8 v[130:133], v[110:113], v[210:213], v[130:133]
	v_mfma_i32_16x16x64_i8 v[122:125], v[110:113], v[218:221], v[122:125]
	v_mfma_i32_16x16x64_i8 v[134:137], v[70:73], v[218:221], v[134:137]
	s_setprio 0
	s_setprio 1
	v_mfma_i32_16x16x64_i8 v[102:105], v[114:117], v[182:185], v[102:105]
	v_mfma_i32_16x16x64_i8 v[94:97], v[126:129], v[182:185], v[94:97]
	v_mfma_i32_16x16x64_i8 v[86:89], v[126:129], v[190:193], v[86:89]
	v_mfma_i32_16x16x64_i8 v[98:101], v[114:117], v[190:193], v[98:101]
	v_mfma_i32_16x16x64_i8 v[90:93], v[114:117], v[198:201], v[90:93]
	v_mfma_i32_16x16x64_i8 v[78:81], v[126:129], v[198:201], v[78:81]
	v_mfma_i32_16x16x64_i8 v[74:77], v[126:129], v[214:217], v[74:77]
	v_mfma_i32_16x16x64_i8 v[82:85], v[114:117], v[214:217], v[82:85]
	v_mfma_i32_16x16x64_i8 v[102:105], v[118:121], v[186:189], v[102:105]
	v_mfma_i32_16x16x64_i8 v[94:97], v[178:181], v[186:189], v[94:97]
	v_mfma_i32_16x16x64_i8 v[86:89], v[178:181], v[194:197], v[86:89]
	v_mfma_i32_16x16x64_i8 v[98:101], v[118:121], v[194:197], v[98:101]
	v_mfma_i32_16x16x64_i8 v[90:93], v[118:121], v[210:213], v[90:93]
	v_mfma_i32_16x16x64_i8 v[78:81], v[178:181], v[210:213], v[78:81]
	v_mfma_i32_16x16x64_i8 v[74:77], v[178:181], v[218:221], v[74:77]
	v_mfma_i32_16x16x64_i8 v[82:85], v[118:121], v[218:221], v[82:85]
	s_setprio 0
	s_barrier
	s_add_i32 s8, s66, s81
	v_lshl_add_u64 v[168:169], v[168:169], 0, s[92:93]
	s_mov_b32 m0, s8
	ds_read_b128 v[182:185], v177 offset:49152
	ds_read_b128 v[186:189], v177 offset:50176
	ds_read_b128 v[190:193], v177 offset:51200
	ds_read_b128 v[194:197], v177 offset:52224
	ds_read_b128 v[198:201], v177 offset:53248
	ds_read_b128 v[210:213], v177 offset:54272
	ds_read_b128 v[214:217], v177 offset:55296
	ds_read_b128 v[218:221], v177 offset:56320
	global_load_lds_dwordx4 v[168:169], off
	s_add_i32 m0, s8, 0x2000
	s_add_u32 s8, s96, 0x40080
	v_lshl_add_u64 v[168:169], v[206:207], 0, s[92:93]
	s_addc_u32 s9, s97, 0
	s_add_i32 s66, s70, s81
	global_load_lds_dwordx4 v[168:169], off
	v_lshl_add_u64 v[168:169], s[8:9], 0, v[0:1]
	s_mov_b32 m0, s66
	s_nop 0
	global_load_lds_dwordx4 v[168:169], off
	v_lshl_add_u64 v[168:169], s[8:9], 0, v[158:159]
	s_add_i32 m0, s66, 0x2000
	s_nop 0
	global_load_lds_dwordx4 v[168:169], off
	v_lshl_add_u64 v[168:169], v[222:223], 0, s[92:93]
	s_mov_b32 m0, s13
	s_nop 0
	global_load_lds_dwordx4 v[168:169], off
	v_lshl_add_u64 v[168:169], v[224:225], 0, s[92:93]
	s_mov_b32 m0, s12
	s_nop 0
	global_load_lds_dwordx4 v[168:169], off
	s_waitcnt vmcnt(8)
	s_waitcnt lgkmcnt(0)
	s_barrier
	s_setprio 1
	s_waitcnt lgkmcnt(0)
	v_mfma_i32_16x16x64_i8 v[62:65], v[66:69], v[182:185], v[62:65]
	v_mfma_i32_16x16x64_i8 v[54:57], v[106:109], v[182:185], v[54:57]
	v_mfma_i32_16x16x64_i8 v[46:49], v[106:109], v[190:193], v[46:49]
	v_mfma_i32_16x16x64_i8 v[58:61], v[66:69], v[190:193], v[58:61]
	v_mfma_i32_16x16x64_i8 v[50:53], v[66:69], v[198:201], v[50:53]
	v_mfma_i32_16x16x64_i8 v[38:41], v[106:109], v[198:201], v[38:41]
	v_mfma_i32_16x16x64_i8 v[34:37], v[106:109], v[214:217], v[34:37]
	v_mfma_i32_16x16x64_i8 v[42:45], v[66:69], v[214:217], v[42:45]
	v_mfma_i32_16x16x64_i8 v[62:65], v[70:73], v[186:189], v[62:65]
	v_mfma_i32_16x16x64_i8 v[54:57], v[110:113], v[186:189], v[54:57]
	v_mfma_i32_16x16x64_i8 v[46:49], v[110:113], v[194:197], v[46:49]
	v_mfma_i32_16x16x64_i8 v[58:61], v[70:73], v[194:197], v[58:61]
	v_mfma_i32_16x16x64_i8 v[50:53], v[70:73], v[210:213], v[50:53]
	v_mfma_i32_16x16x64_i8 v[38:41], v[110:113], v[210:213], v[38:41]
	v_mfma_i32_16x16x64_i8 v[34:37], v[110:113], v[218:221], v[34:37]
	v_mfma_i32_16x16x64_i8 v[42:45], v[70:73], v[218:221], v[42:45]
	s_setprio 0
	s_setprio 1
	v_mfma_i32_16x16x64_i8 v[30:33], v[114:117], v[182:185], v[30:33]
	v_mfma_i32_16x16x64_i8 v[22:25], v[126:129], v[182:185], v[22:25]
	v_mfma_i32_16x16x64_i8 v[14:17], v[126:129], v[190:193], v[14:17]
	v_mfma_i32_16x16x64_i8 v[26:29], v[114:117], v[190:193], v[26:29]
	v_mfma_i32_16x16x64_i8 v[18:21], v[114:117], v[198:201], v[18:21]
	v_mfma_i32_16x16x64_i8 v[6:9], v[126:129], v[198:201], v[6:9]
	v_mfma_i32_16x16x64_i8 v[2:5], v[126:129], v[214:217], v[2:5]
	v_mfma_i32_16x16x64_i8 v[10:13], v[114:117], v[214:217], v[10:13]
	v_mfma_i32_16x16x64_i8 v[30:33], v[118:121], v[186:189], v[30:33]
	v_mfma_i32_16x16x64_i8 v[22:25], v[178:181], v[186:189], v[22:25]
	v_mfma_i32_16x16x64_i8 v[14:17], v[178:181], v[194:197], v[14:17]
	v_mfma_i32_16x16x64_i8 v[26:29], v[118:121], v[194:197], v[26:29]
	v_mfma_i32_16x16x64_i8 v[18:21], v[118:121], v[210:213], v[18:21]
	v_mfma_i32_16x16x64_i8 v[6:9], v[178:181], v[210:213], v[6:9]
	v_mfma_i32_16x16x64_i8 v[2:5], v[178:181], v[218:221], v[2:5]
	v_mfma_i32_16x16x64_i8 v[10:13], v[118:121], v[218:221], v[10:13]
	s_setprio 0
	s_barrier
	s_add_i32 s10, s10, 2
	s_add_u32 s69, s69, 0x100
	s_addc_u32 s68, s68, 0
	s_cmp_gt_u32 s10, 13
	s_mov_b64 s[8:9], s[84:85]
	s_cbranch_scc0 .LBB0_291

; #define PG8_STAGE(bufoff, gbase, voff) do { _Pragma("unroll") for (int _i = 0; _i < 2; ++_i) \
;         __builtin_amdgcn_global_load_lds((const unsigned*)((const char*)(gbase) + (voff)[_i]), (PG8_LAS unsigned*)(lds + (bufoff) + ldsw + _i * 8192), 16, 0, 0); } while (0)
; #define PG8_LDA(dst, b, h) do { _Pragma("unroll") for (int m = 0; m < 4; ++m) _Pragma("unroll") for (int k = 0; k < 2; ++k) dst[m][k] = *(const PG8_LAS bf16x8*)(lds + PG8_SA(b, h) + aoff + m * 2048 + k * 1024); } while (0)
; #define PG8_LDB(dst, b, h) do { _Pragma("unroll") for (int n = 0; n < 2; ++n) _Pragma("unroll") for (int k = 0; k < 2; ++k) dst[n][k] = *(const PG8_LAS bf16x8*)(lds + PG8_SB(b, h) + boff + n * 2048 + k * 1024); } while (0)
; #define PG8_MMA(ai, bj, At, Bt) do { __builtin_amdgcn_s_setprio(1); _Pragma("unroll") for (int m = 0; m < 4; ++m) _Pragma("unroll") for (int n = 0; n < 2; ++n) _Pragma("unroll") for (int k = 0; k < 2; ++k) \
;         acc[ai][bj][m][n] = mma16<Epi::I8>(Bt[n][k], At[m][k], acc[ai][bj][m][n]); __builtin_amdgcn_s_setprio(0); } while (0)
; #define PG8_WAIT_V(n) asm volatile("s_waitcnt vmcnt(" #n ")" ::: "memory")
; template <class Epi, class Sched, bool ALIGN_EPI = false, bool SP2 = false>
; __device__ __forceinline__ void gemm_phase(PG8_LAS unsigned char* lds, const Gemm g, const Sched& S, const Epi& E) {
;     ...
;             PG8_LDB(B0, 0, 0); PG8_LDB(B1, 0, 1); PG8_SCHED; PG8_LDA(At, 0, 0); PG8_STAGE(PG8_SA(1, 1), a1 + hstep, voffA);
;             PG8_WAIT_V(8); PG8_WAIT_L(0); PG8_BAR; PG8_MMA(0, 0, At, B0); PG8_MMA(0, 1, At, B1); PG8_BAR; PG8_SCHED;
;             PG8_LDA(At, 0, 1); PG8_STAGE(PG8_SB(0, 0), b2, voffB); PG8_STAGE(PG8_SB(0, 1), b2 + hstep, voffB); PG8_STAGE(PG8_SA(0, 0), a2, voffA);
;             PG8_WAIT_V(8); PG8_WAIT_L(0); PG8_BAR; PG8_MMA(1, 0, At, B0); PG8_MMA(1, 1, At, B1); PG8_BAR; PG8_SCHED;
;             PG8_LDB(B0, 1, 0); PG8_LDB(B1, 1, 1); PG8_SCHED; PG8_LDA(At, 1, 0); PG8_STAGE(PG8_SA(0, 1), a2 + hstep, voffA);
;             PG8_WAIT_V(8); PG8_WAIT_L(0); PG8_BAR; PG8_MMA(0, 0, At, B0); PG8_MMA(0, 1, At, B1); PG8_BAR; PG8_SCHED;
;             PG8_LDA(At, 1, 1); PG8_STAGE(PG8_SB(1, 0), b3, voffB); PG8_STAGE(PG8_SB(1, 1), b3 + hstep, voffB); PG8_STAGE(PG8_SA(1, 0), a3, voffA);
;             PG8_WAIT_V(8); PG8_WAIT_L(0); PG8_BAR; PG8_MMA(1, 0, At, B0); PG8_MMA(1, 1, At, B1); PG8_BAR; PG8_SCHED;
.Lpeel327:
	s_add_u32 s68, s8, 0x100
	s_addc_u32 s69, s9, 0
	s_add_i32 s84, 0, 0x10000
	s_cmp_eq_u32 s4, 28
	s_cselect_b32 vcc_hi, s1, s69
	s_cselect_b32 vcc_lo, s5, s68
	v_add_u32_e32 v0, s84, v188
	s_cselect_b32 s71, s7, s96
	s_cselect_b32 s70, s85, s97
	s_add_i32 s10, 0, 0x14000
	ds_read_b128 v[52:55], v0
	ds_read_b128 v[56:59], v0 offset:1024
	ds_read_b128 v[76:79], v0 offset:2048
	ds_read_b128 v[80:83], v0 offset:3072
	v_add_u32_e32 v0, s10, v188
	ds_read_b128 v[116:119], v0
	ds_read_b128 v[120:123], v0 offset:1024
	ds_read_b128 v[168:171], v0 offset:2048
	ds_read_b128 v[172:175], v0 offset:3072
	v_lshl_add_u64 v[2:3], s[8:9], 0, v[164:165]
	s_add_i32 m0, s58, 0xc000
	ds_read_b128 v[176:179], v189
	ds_read_b128 v[180:183], v189 offset:1024
	ds_read_b128 v[190:193], v189 offset:2048
	ds_read_b128 v[194:197], v189 offset:3072
	ds_read_b128 v[198:201], v189 offset:4096
	ds_read_b128 v[210:213], v189 offset:5120
	ds_read_b128 v[214:217], v189 offset:6144
	ds_read_b128 v[218:221], v189 offset:7168
	global_load_lds_dwordx4 v[2:3], off
	v_lshl_add_u64 v[2:3], s[8:9], 0, v[166:167]
	s_add_i32 m0, s58, 0xe000
	s_nop 0
	global_load_lds_dwordx4 v[2:3], off
	s_waitcnt vmcnt(8)
	s_waitcnt lgkmcnt(0)
	s_barrier
	s_setprio 1
	s_waitcnt lgkmcnt(0)
	v_mfma_f32_16x16x32_bf16 v[152:155], v[52:55], v[176:179], 0
	v_mfma_f32_16x16x32_bf16 v[144:147], v[76:79], v[176:179], 0
	v_mfma_f32_16x16x32_bf16 v[140:143], v[76:79], v[190:193], 0
	v_mfma_f32_16x16x32_bf16 v[148:151], v[52:55], v[190:193], 0
	v_mfma_f32_16x16x32_bf16 v[136:139], v[52:55], v[198:201], 0
	v_mfma_f32_16x16x32_bf16 v[132:135], v[76:79], v[198:201], 0
	v_mfma_f32_16x16x32_bf16 v[124:127], v[76:79], v[214:217], 0
	v_mfma_f32_16x16x32_bf16 v[128:131], v[52:55], v[214:217], 0
	v_mfma_f32_16x16x32_bf16 v[152:155], v[56:59], v[180:183], v[152:155]
	v_mfma_f32_16x16x32_bf16 v[144:147], v[80:83], v[180:183], v[144:147]
	v_mfma_f32_16x16x32_bf16 v[140:143], v[80:83], v[194:197], v[140:143]
	v_mfma_f32_16x16x32_bf16 v[148:151], v[56:59], v[194:197], v[148:151]
	v_mfma_f32_16x16x32_bf16 v[136:139], v[56:59], v[210:213], v[136:139]
	v_mfma_f32_16x16x32_bf16 v[132:135], v[80:83], v[210:213], v[132:135]
	v_mfma_f32_16x16x32_bf16 v[124:127], v[80:83], v[218:221], v[124:127]
	v_mfma_f32_16x16x32_bf16 v[128:131], v[56:59], v[218:221], v[128:131]
	s_setprio 0
	s_setprio 1
	v_mfma_f32_16x16x32_bf16 v[112:115], v[116:119], v[176:179], 0
	v_mfma_f32_16x16x32_bf16 v[104:107], v[168:171], v[176:179], 0
	v_mfma_f32_16x16x32_bf16 v[100:103], v[168:171], v[190:193], 0
	v_mfma_f32_16x16x32_bf16 v[108:111], v[116:119], v[190:193], 0
	v_mfma_f32_16x16x32_bf16 v[96:99], v[116:119], v[198:201], 0
	v_mfma_f32_16x16x32_bf16 v[92:95], v[168:171], v[198:201], 0
	v_mfma_f32_16x16x32_bf16 v[84:87], v[168:171], v[214:217], 0
	v_mfma_f32_16x16x32_bf16 v[88:91], v[116:119], v[214:217], 0
	v_mfma_f32_16x16x32_bf16 v[112:115], v[120:123], v[180:183], v[112:115]
	v_mfma_f32_16x16x32_bf16 v[104:107], v[172:175], v[180:183], v[104:107]
	v_mfma_f32_16x16x32_bf16 v[100:103], v[172:175], v[194:197], v[100:103]
	v_mfma_f32_16x16x32_bf16 v[108:111], v[120:123], v[194:197], v[108:111]
	v_mfma_f32_16x16x32_bf16 v[96:99], v[120:123], v[210:213], v[96:99]
	v_mfma_f32_16x16x32_bf16 v[92:95], v[172:175], v[210:213], v[92:95]
	v_mfma_f32_16x16x32_bf16 v[84:87], v[172:175], v[218:221], v[84:87]
	v_mfma_f32_16x16x32_bf16 v[88:91], v[120:123], v[218:221], v[88:91]
	s_setprio 0
	s_barrier
	s_add_i32 s8, s84, s80
	v_lshl_add_u64 v[184:185], s[70:71], 0, v[158:159]
	s_mov_b32 m0, s8
	ds_read_b128 v[176:179], v189 offset:16384
	ds_read_b128 v[180:183], v189 offset:17408
	ds_read_b128 v[190:193], v189 offset:18432
	ds_read_b128 v[194:197], v189 offset:19456
	ds_read_b128 v[198:201], v189 offset:20480
	ds_read_b128 v[210:213], v189 offset:21504
	ds_read_b128 v[214:217], v189 offset:22528
	ds_read_b128 v[218:221], v189 offset:23552
	global_load_lds_dwordx4 v[184:185], off
	s_add_i32 m0, s8, 0x2000
	s_add_u32 s8, s70, 0x80000
	v_lshl_add_u64 v[206:207], s[70:71], 0, v[162:163]
	s_addc_u32 s9, s71, 0
	s_add_i32 s10, s10, s80
	global_load_lds_dwordx4 v[206:207], off
	v_lshl_add_u64 v[2:3], s[8:9], 0, v[158:159]
	s_mov_b32 m0, s10
	v_lshl_add_u64 v[222:223], vcc, 0, v[156:157]
	global_load_lds_dwordx4 v[2:3], off
	v_lshl_add_u64 v[2:3], s[8:9], 0, v[162:163]
	s_add_i32 m0, s10, 0x2000
	v_lshl_add_u64 v[224:225], vcc, 0, v[160:161]
	global_load_lds_dwordx4 v[2:3], off
	s_mov_b32 m0, s58
	s_nop 0
	global_load_lds_dwordx4 v[222:223], off
	s_mov_b32 m0, s12
	s_nop 0
	global_load_lds_dwordx4 v[224:225], off
	s_waitcnt vmcnt(8)
	s_waitcnt lgkmcnt(0)
	s_barrier
; #define PG8_STAGE(bufoff, gbase, voff) do { _Pragma("unroll") for (int _i = 0; _i < 2; ++_i) \
;         __builtin_amdgcn_global_load_lds((const unsigned*)((const char*)(gbase) + (voff)[_i]), (PG8_LAS unsigned*)(lds + (bufoff) + ldsw + _i * 8192), 16, 0, 0); } while (0)
; #define PG8_LDA(dst, b, h) do { _Pragma("unroll") for (int m = 0; m < 4; ++m) _Pragma("unroll") for (int k = 0; k < 2; ++k) dst[m][k] = *(const PG8_LAS bf16x8*)(lds + PG8_SA(b, h) + aoff + m * 2048 + k * 1024); } while (0)
; #define PG8_LDB(dst, b, h) do { _Pragma("unroll") for (int n = 0; n < 2; ++n) _Pragma("unroll") for (int k = 0; k < 2; ++k) dst[n][k] = *(const PG8_LAS bf16x8*)(lds + PG8_SB(b, h) + boff + n * 2048 + k * 1024); } while (0)
; #define PG8_MMA(ai, bj, At, Bt) do { __builtin_amdgcn_s_setprio(1); _Pragma("unroll") for (int m = 0; m < 4; ++m) _Pragma("unroll") for (int n = 0; n < 2; ++n) _Pragma("unroll") for (int k = 0; k < 2; ++k) \
;         acc[ai][bj][m][n] = mma16<Epi::I8>(Bt[n][k], At[m][k], acc[ai][bj][m][n]); __builtin_amdgcn_s_setprio(0); } while (0)
; #define PG8_WAIT_V(n) asm volatile("s_waitcnt vmcnt(" #n ")" ::: "memory")
; template <class Epi, class Sched, bool ALIGN_EPI = false, bool SP2 = false>
; __device__ __forceinline__ void gemm_phase(PG8_LAS unsigned char* lds, const Gemm g, const Sched& S, const Epi& E) {
;     ...
;             PG8_LDB(B0, 0, 0); PG8_LDB(B1, 0, 1); PG8_SCHED; PG8_LDA(At, 0, 0); PG8_STAGE(PG8_SA(1, 1), a1 + hstep, voffA);
;             PG8_WAIT_V(8); PG8_WAIT_L(0); PG8_BAR; PG8_MMA(0, 0, At, B0); PG8_MMA(0, 1, At, B1); PG8_BAR; PG8_SCHED;
;             PG8_LDA(At, 0, 1); PG8_STAGE(PG8_SB(0, 0), b2, voffB); PG8_STAGE(PG8_SB(0, 1), b2 + hstep, voffB); PG8_STAGE(PG8_SA(0, 0), a2, voffA);
;             PG8_WAIT_V(8); PG8_WAIT_L(0); PG8_BAR; PG8_MMA(1, 0, At, B0); PG8_MMA(1, 1, At, B1); PG8_BAR; PG8_SCHED;
;             PG8_LDB(B0, 1, 0); PG8_LDB(B1, 1, 1); PG8_SCHED; PG8_LDA(At, 1, 0); PG8_STAGE(PG8_SA(0, 1), a2 + hstep, voffA);
;             PG8_WAIT_V(8); PG8_WAIT_L(0); PG8_BAR; PG8_MMA(0, 0, At, B0); PG8_MMA(0, 1, At, B1); PG8_BAR; PG8_SCHED;
;             PG8_LDA(At, 1, 1); PG8_STAGE(PG8_SB(1, 0), b3, voffB); PG8_STAGE(PG8_SB(1, 1), b3 + hstep, voffB); PG8_STAGE(PG8_SA(1, 0), a3, voffA);
;             PG8_WAIT_V(8); PG8_WAIT_L(0); PG8_BAR; PG8_MMA(1, 0, At, B0); PG8_MMA(1, 1, At, B1); PG8_BAR; PG8_SCHED;
	s_setprio 1
	s_waitcnt lgkmcnt(0)
	v_mfma_f32_16x16x32_bf16 v[72:75], v[52:55], v[176:179], 0
	v_mfma_f32_16x16x32_bf16 v[64:67], v[76:79], v[176:179], 0
	v_mfma_f32_16x16x32_bf16 v[60:63], v[76:79], v[190:193], 0
	v_mfma_f32_16x16x32_bf16 v[68:71], v[52:55], v[190:193], 0
	v_mfma_f32_16x16x32_bf16 v[48:51], v[52:55], v[198:201], 0
	v_mfma_f32_16x16x32_bf16 v[44:47], v[76:79], v[198:201], 0
	v_mfma_f32_16x16x32_bf16 v[36:39], v[76:79], v[214:217], 0
	v_mfma_f32_16x16x32_bf16 v[40:43], v[52:55], v[214:217], 0
	v_mfma_f32_16x16x32_bf16 v[72:75], v[56:59], v[180:183], v[72:75]
	v_mfma_f32_16x16x32_bf16 v[64:67], v[80:83], v[180:183], v[64:67]
	v_mfma_f32_16x16x32_bf16 v[60:63], v[80:83], v[194:197], v[60:63]
	v_mfma_f32_16x16x32_bf16 v[68:71], v[56:59], v[194:197], v[68:71]
	v_mfma_f32_16x16x32_bf16 v[48:51], v[56:59], v[210:213], v[48:51]
	v_mfma_f32_16x16x32_bf16 v[44:47], v[80:83], v[210:213], v[44:47]
	v_mfma_f32_16x16x32_bf16 v[36:39], v[80:83], v[218:221], v[36:39]
	v_mfma_f32_16x16x32_bf16 v[40:43], v[56:59], v[218:221], v[40:43]
	s_setprio 0
	s_setprio 1
	v_mfma_f32_16x16x32_bf16 v[32:35], v[116:119], v[176:179], 0
	v_mfma_f32_16x16x32_bf16 v[24:27], v[168:171], v[176:179], 0
	v_mfma_f32_16x16x32_bf16 v[20:23], v[168:171], v[190:193], 0
	v_mfma_f32_16x16x32_bf16 v[28:31], v[116:119], v[190:193], 0
	v_mfma_f32_16x16x32_bf16 v[16:19], v[116:119], v[198:201], 0
	v_mfma_f32_16x16x32_bf16 v[12:15], v[168:171], v[198:201], 0
	v_mfma_f32_16x16x32_bf16 v[2:5], v[168:171], v[214:217], 0
	v_mfma_f32_16x16x32_bf16 v[8:11], v[116:119], v[214:217], 0
	v_mfma_f32_16x16x32_bf16 v[32:35], v[120:123], v[180:183], v[32:35]
	v_mfma_f32_16x16x32_bf16 v[24:27], v[172:175], v[180:183], v[24:27]
	v_mfma_f32_16x16x32_bf16 v[20:23], v[172:175], v[194:197], v[20:23]
	v_mfma_f32_16x16x32_bf16 v[28:31], v[120:123], v[194:197], v[28:31]
	v_mfma_f32_16x16x32_bf16 v[16:19], v[120:123], v[210:213], v[16:19]
	v_mfma_f32_16x16x32_bf16 v[12:15], v[172:175], v[210:213], v[12:15]
	v_mfma_f32_16x16x32_bf16 v[2:5], v[172:175], v[218:221], v[2:5]
	v_mfma_f32_16x16x32_bf16 v[8:11], v[120:123], v[218:221], v[8:11]
	s_setprio 0
	s_barrier
	s_add_i32 s10, 0, 0x18000
	v_add_u32_e32 v0, s10, v188
	s_add_i32 s11, 0, 0x1c000
	ds_read_b128 v[52:55], v0
	ds_read_b128 v[56:59], v0 offset:1024
	ds_read_b128 v[76:79], v0 offset:2048
	ds_read_b128 v[80:83], v0 offset:3072
	v_add_u32_e32 v0, s11, v188
	ds_read_b128 v[116:119], v0
	ds_read_b128 v[120:123], v0 offset:1024
	ds_read_b128 v[168:171], v0 offset:2048
	ds_read_b128 v[172:175], v0 offset:3072
	s_add_u32 s8, vcc_lo, 0x80000
	s_addc_u32 s9, vcc_hi, 0
	s_mov_b32 m0, s13
	v_lshl_add_u64 v[6:7], s[8:9], 0, v[156:157]
	ds_read_b128 v[176:179], v189 offset:32768
	ds_read_b128 v[180:183], v189 offset:33792
	ds_read_b128 v[190:193], v189 offset:34816
	ds_read_b128 v[194:197], v189 offset:35840
	ds_read_b128 v[198:201], v189 offset:36864
	ds_read_b128 v[210:213], v189 offset:37888
	ds_read_b128 v[214:217], v189 offset:38912
	ds_read_b128 v[218:221], v189 offset:39936
	global_load_lds_dwordx4 v[6:7], off
	v_lshl_add_u64 v[6:7], s[8:9], 0, v[160:161]
	s_mov_b32 m0, s66
	s_nop 0
	global_load_lds_dwordx4 v[6:7], off
	s_waitcnt vmcnt(8)
	s_waitcnt lgkmcnt(0)
	s_barrier
	s_setprio 1
	s_waitcnt lgkmcnt(0)
	v_mfma_f32_16x16x32_bf16 v[152:155], v[52:55], v[176:179], v[152:155]
	v_mfma_f32_16x16x32_bf16 v[144:147], v[76:79], v[176:179], v[144:147]
	v_mfma_f32_16x16x32_bf16 v[140:143], v[76:79], v[190:193], v[140:143]
	v_mfma_f32_16x16x32_bf16 v[148:151], v[52:55], v[190:193], v[148:151]
	v_mfma_f32_16x16x32_bf16 v[136:139], v[52:55], v[198:201], v[136:139]
	v_mfma_f32_16x16x32_bf16 v[132:135], v[76:79], v[198:201], v[132:135]
	v_mfma_f32_16x16x32_bf16 v[124:127], v[76:79], v[214:217], v[124:127]
	v_mfma_f32_16x16x32_bf16 v[128:131], v[52:55], v[214:217], v[128:131]
	v_mfma_f32_16x16x32_bf16 v[152:155], v[56:59], v[180:183], v[152:155]
	v_mfma_f32_16x16x32_bf16 v[144:147], v[80:83], v[180:183], v[144:147]
	v_mfma_f32_16x16x32_bf16 v[140:143], v[80:83], v[194:197], v[140:143]
	v_mfma_f32_16x16x32_bf16 v[148:151], v[56:59], v[194:197], v[148:151]
	v_mfma_f32_16x16x32_bf16 v[136:139], v[56:59], v[210:213], v[136:139]
	v_mfma_f32_16x16x32_bf16 v[132:135], v[80:83], v[210:213], v[132:135]
	v_mfma_f32_16x16x32_bf16 v[124:127], v[80:83], v[218:221], v[124:127]
	v_mfma_f32_16x16x32_bf16 v[128:131], v[56:59], v[218:221], v[128:131]
	s_setprio 0
	s_setprio 1
	v_mfma_f32_16x16x32_bf16 v[112:115], v[116:119], v[176:179], v[112:115]
	v_mfma_f32_16x16x32_bf16 v[104:107], v[168:171], v[176:179], v[104:107]
	v_mfma_f32_16x16x32_bf16 v[100:103], v[168:171], v[190:193], v[100:103]
	v_mfma_f32_16x16x32_bf16 v[108:111], v[116:119], v[190:193], v[108:111]
	v_mfma_f32_16x16x32_bf16 v[96:99], v[116:119], v[198:201], v[96:99]
	v_mfma_f32_16x16x32_bf16 v[92:95], v[168:171], v[198:201], v[92:95]
	v_mfma_f32_16x16x32_bf16 v[84:87], v[168:171], v[214:217], v[84:87]
	v_mfma_f32_16x16x32_bf16 v[88:91], v[116:119], v[214:217], v[88:91]
	v_mfma_f32_16x16x32_bf16 v[112:115], v[120:123], v[180:183], v[112:115]
	v_mfma_f32_16x16x32_bf16 v[104:107], v[172:175], v[180:183], v[104:107]
	v_mfma_f32_16x16x32_bf16 v[100:103], v[172:175], v[194:197], v[100:103]
	v_mfma_f32_16x16x32_bf16 v[108:111], v[120:123], v[194:197], v[108:111]
	v_mfma_f32_16x16x32_bf16 v[96:99], v[120:123], v[210:213], v[96:99]
	v_mfma_f32_16x16x32_bf16 v[92:95], v[172:175], v[210:213], v[92:95]
	v_mfma_f32_16x16x32_bf16 v[84:87], v[172:175], v[218:221], v[84:87]
	v_mfma_f32_16x16x32_bf16 v[88:91], v[120:123], v[218:221], v[88:91]
	s_setprio 0
	s_barrier
; #define PG8_STAGE(bufoff, gbase, voff) do { _Pragma("unroll") for (int _i = 0; _i < 2; ++_i) \
;         __builtin_amdgcn_global_load_lds((const unsigned*)((const char*)(gbase) + (voff)[_i]), (PG8_LAS unsigned*)(lds + (bufoff) + ldsw + _i * 8192), 16, 0, 0); } while (0)
; #define PG8_LDA(dst, b, h) do { _Pragma("unroll") for (int m = 0; m < 4; ++m) _Pragma("unroll") for (int k = 0; k < 2; ++k) dst[m][k] = *(const PG8_LAS bf16x8*)(lds + PG8_SA(b, h) + aoff + m * 2048 + k * 1024); } while (0)
; #define PG8_LDB(dst, b, h) do { _Pragma("unroll") for (int n = 0; n < 2; ++n) _Pragma("unroll") for (int k = 0; k < 2; ++k) dst[n][k] = *(const PG8_LAS bf16x8*)(lds + PG8_SB(b, h) + boff + n * 2048 + k * 1024); } while (0)
; #define PG8_MMA(ai, bj, At, Bt) do { __builtin_amdgcn_s_setprio(1); _Pragma("unroll") for (int m = 0; m < 4; ++m) _Pragma("unroll") for (int n = 0; n < 2; ++n) _Pragma("unroll") for (int k = 0; k < 2; ++k) \
;         acc[ai][bj][m][n] = mma16<Epi::I8>(Bt[n][k], At[m][k], acc[ai][bj][m][n]); __builtin_amdgcn_s_setprio(0); } while (0)
; #define PG8_WAIT_V(n) asm volatile("s_waitcnt vmcnt(" #n ")" ::: "memory")
; template <class Epi, class Sched, bool ALIGN_EPI = false, bool SP2 = false>
; __device__ __forceinline__ void gemm_phase(PG8_LAS unsigned char* lds, const Gemm g, const Sched& S, const Epi& E) {
;     ...
;             PG8_LDB(B0, 0, 0); PG8_LDB(B1, 0, 1); PG8_SCHED; PG8_LDA(At, 0, 0); PG8_STAGE(PG8_SA(1, 1), a1 + hstep, voffA);
;             PG8_WAIT_V(8); PG8_WAIT_L(0); PG8_BAR; PG8_MMA(0, 0, At, B0); PG8_MMA(0, 1, At, B1); PG8_BAR; PG8_SCHED;
;             PG8_LDA(At, 0, 1); PG8_STAGE(PG8_SB(0, 0), b2, voffB); PG8_STAGE(PG8_SB(0, 1), b2 + hstep, voffB); PG8_STAGE(PG8_SA(0, 0), a2, voffA);
;             PG8_WAIT_V(8); PG8_WAIT_L(0); PG8_BAR; PG8_MMA(1, 0, At, B0); PG8_MMA(1, 1, At, B1); PG8_BAR; PG8_SCHED;
;             PG8_LDB(B0, 1, 0); PG8_LDB(B1, 1, 1); PG8_SCHED; PG8_LDA(At, 1, 0); PG8_STAGE(PG8_SA(0, 1), a2 + hstep, voffA);
;             PG8_WAIT_V(8); PG8_WAIT_L(0); PG8_BAR; PG8_MMA(0, 0, At, B0); PG8_MMA(0, 1, At, B1); PG8_BAR; PG8_SCHED;
;             PG8_LDA(At, 1, 1); PG8_STAGE(PG8_SB(1, 0), b3, voffB); PG8_STAGE(PG8_SB(1, 1), b3 + hstep, voffB); PG8_STAGE(PG8_SA(1, 0), a3, voffA);
;             PG8_WAIT_V(8); PG8_WAIT_L(0); PG8_BAR; PG8_MMA(1, 0, At, B0); PG8_MMA(1, 1, At, B1); PG8_BAR; PG8_SCHED;
	s_add_i32 s8, s10, s80
	v_lshl_add_u64 v[6:7], v[184:185], 0, s[92:93]
	s_mov_b32 m0, s8
	ds_read_b128 v[176:179], v189 offset:49152
	ds_read_b128 v[180:183], v189 offset:50176
	ds_read_b128 v[190:193], v189 offset:51200
	ds_read_b128 v[194:197], v189 offset:52224
	ds_read_b128 v[198:201], v189 offset:53248
	ds_read_b128 v[210:213], v189 offset:54272
	ds_read_b128 v[214:217], v189 offset:55296
	ds_read_b128 v[218:221], v189 offset:56320
	global_load_lds_dwordx4 v[6:7], off
	s_add_i32 m0, s8, 0x2000
	s_add_u32 s8, s70, 0x80080
	v_lshl_add_u64 v[6:7], v[206:207], 0, s[92:93]
	s_addc_u32 s9, s71, 0
	s_add_i32 s10, s11, s80
	global_load_lds_dwordx4 v[6:7], off
	v_lshl_add_u64 v[6:7], s[8:9], 0, v[158:159]
	s_mov_b32 m0, s10
	s_nop 0
	global_load_lds_dwordx4 v[6:7], off
	v_lshl_add_u64 v[6:7], s[8:9], 0, v[162:163]
	s_add_i32 m0, s10, 0x2000
	s_nop 0
	global_load_lds_dwordx4 v[6:7], off
	v_lshl_add_u64 v[6:7], v[222:223], 0, s[92:93]
	s_mov_b32 m0, s67
	s_nop 0
	global_load_lds_dwordx4 v[6:7], off
	v_lshl_add_u64 v[6:7], v[224:225], 0, s[92:93]
	s_mov_b32 m0, s81
	s_nop 0
	global_load_lds_dwordx4 v[6:7], off
	s_waitcnt vmcnt(8)
	s_waitcnt lgkmcnt(0)
	s_barrier
	s_setprio 1
	s_waitcnt lgkmcnt(0)
	v_mfma_f32_16x16x32_bf16 v[72:75], v[52:55], v[176:179], v[72:75]
	v_mfma_f32_16x16x32_bf16 v[64:67], v[76:79], v[176:179], v[64:67]
	v_mfma_f32_16x16x32_bf16 v[60:63], v[76:79], v[190:193], v[60:63]
	v_mfma_f32_16x16x32_bf16 v[68:71], v[52:55], v[190:193], v[68:71]
	v_mfma_f32_16x16x32_bf16 v[48:51], v[52:55], v[198:201], v[48:51]
	v_mfma_f32_16x16x32_bf16 v[44:47], v[76:79], v[198:201], v[44:47]
	v_mfma_f32_16x16x32_bf16 v[36:39], v[76:79], v[214:217], v[36:39]
	v_mfma_f32_16x16x32_bf16 v[40:43], v[52:55], v[214:217], v[40:43]
	v_mfma_f32_16x16x32_bf16 v[72:75], v[56:59], v[180:183], v[72:75]
	v_mfma_f32_16x16x32_bf16 v[64:67], v[80:83], v[180:183], v[64:67]
	v_mfma_f32_16x16x32_bf16 v[60:63], v[80:83], v[194:197], v[60:63]
	v_mfma_f32_16x16x32_bf16 v[68:71], v[56:59], v[194:197], v[68:71]
	v_mfma_f32_16x16x32_bf16 v[48:51], v[56:59], v[210:213], v[48:51]
	v_mfma_f32_16x16x32_bf16 v[44:47], v[80:83], v[210:213], v[44:47]
	v_mfma_f32_16x16x32_bf16 v[36:39], v[80:83], v[218:221], v[36:39]
	v_mfma_f32_16x16x32_bf16 v[40:43], v[56:59], v[218:221], v[40:43]
	s_setprio 0
	s_setprio 1
	v_mfma_f32_16x16x32_bf16 v[32:35], v[116:119], v[176:179], v[32:35]
	v_mfma_f32_16x16x32_bf16 v[24:27], v[168:171], v[176:179], v[24:27]
	v_mfma_f32_16x16x32_bf16 v[20:23], v[168:171], v[190:193], v[20:23]
	v_mfma_f32_16x16x32_bf16 v[28:31], v[116:119], v[190:193], v[28:31]
	v_mfma_f32_16x16x32_bf16 v[16:19], v[116:119], v[198:201], v[16:19]
	v_mfma_f32_16x16x32_bf16 v[12:15], v[168:171], v[198:201], v[12:15]
	v_mfma_f32_16x16x32_bf16 v[2:5], v[168:171], v[214:217], v[2:5]
	v_mfma_f32_16x16x32_bf16 v[6:9], v[116:119], v[214:217], v[8:11]
	v_mfma_f32_16x16x32_bf16 v[32:35], v[120:123], v[180:183], v[32:35]
	v_mfma_f32_16x16x32_bf16 v[24:27], v[172:175], v[180:183], v[24:27]
	v_mfma_f32_16x16x32_bf16 v[20:23], v[172:175], v[194:197], v[20:23]
	v_mfma_f32_16x16x32_bf16 v[28:31], v[120:123], v[194:197], v[28:31]
	v_mfma_f32_16x16x32_bf16 v[16:19], v[120:123], v[210:213], v[16:19]
	v_mfma_f32_16x16x32_bf16 v[12:15], v[172:175], v[210:213], v[12:15]
	v_mfma_f32_16x16x32_bf16 v[8:11], v[120:123], v[218:221], v[6:9]
	v_mfma_f32_16x16x32_bf16 v[4:7], v[172:175], v[218:221], v[2:5]
	s_setprio 0
	s_barrier
	s_add_i32 s4, s4, 2
	s_add_u32 s97, s97, 0x100
	s_addc_u32 s96, s96, 0
	s_cmp_gt_u32 s4, 29
	s_mov_b64 s[8:9], s[68:69]
	s_cbranch_scc0 .LBB0_327
	s_branch .Lpeelx327
.LBB0_327:
	s_add_u32 s68, s8, 0x100
	s_addc_u32 s69, s9, 0
	s_add_i32 s84, 0, 0x10000
	s_cmp_eq_u32 s4, 28
	s_cselect_b32 vcc_hi, s1, s69
	s_cselect_b32 vcc_lo, s5, s68
	v_add_u32_e32 v0, s84, v188
	s_cselect_b32 s71, s7, s96
	s_cselect_b32 s70, s85, s97
	s_add_i32 s10, 0, 0x14000
	ds_read_b128 v[52:55], v0
	ds_read_b128 v[56:59], v0 offset:1024
	ds_read_b128 v[76:79], v0 offset:2048
	ds_read_b128 v[80:83], v0 offset:3072
	v_add_u32_e32 v0, s10, v188
	ds_read_b128 v[116:119], v0
	ds_read_b128 v[120:123], v0 offset:1024
	ds_read_b128 v[168:171], v0 offset:2048
	ds_read_b128 v[172:175], v0 offset:3072
	v_lshl_add_u64 v[2:3], s[8:9], 0, v[164:165]
	s_add_i32 m0, s58, 0xc000
	ds_read_b128 v[176:179], v189
	ds_read_b128 v[180:183], v189 offset:1024
	ds_read_b128 v[190:193], v189 offset:2048
	ds_read_b128 v[194:197], v189 offset:3072
	ds_read_b128 v[198:201], v189 offset:4096
	ds_read_b128 v[210:213], v189 offset:5120
	ds_read_b128 v[214:217], v189 offset:6144
	ds_read_b128 v[218:221], v189 offset:7168
	global_load_lds_dwordx4 v[2:3], off
	v_lshl_add_u64 v[2:3], s[8:9], 0, v[166:167]
	s_add_i32 m0, s58, 0xe000
	s_nop 0
	global_load_lds_dwordx4 v[2:3], off
	s_waitcnt vmcnt(8)
	s_waitcnt lgkmcnt(0)
	s_barrier
; #define PG8_STAGE(bufoff, gbase, voff) do { _Pragma("unroll") for (int _i = 0; _i < 2; ++_i) \
;         __builtin_amdgcn_global_load_lds((const unsigned*)((const char*)(gbase) + (voff)[_i]), (PG8_LAS unsigned*)(lds + (bufoff) + ldsw + _i * 8192), 16, 0, 0); } while (0)
; #define PG8_LDA(dst, b, h) do { _Pragma("unroll") for (int m = 0; m < 4; ++m) _Pragma("unroll") for (int k = 0; k < 2; ++k) dst[m][k] = *(const PG8_LAS bf16x8*)(lds + PG8_SA(b, h) + aoff + m * 2048 + k * 1024); } while (0)
; #define PG8_LDB(dst, b, h) do { _Pragma("unroll") for (int n = 0; n < 2; ++n) _Pragma("unroll") for (int k = 0; k < 2; ++k) dst[n][k] = *(const PG8_LAS bf16x8*)(lds + PG8_SB(b, h) + boff + n * 2048 + k * 1024); } while (0)
; #define PG8_MMA(ai, bj, At, Bt) do { __builtin_amdgcn_s_setprio(1); _Pragma("unroll") for (int m = 0; m < 4; ++m) _Pragma("unroll") for (int n = 0; n < 2; ++n) _Pragma("unroll") for (int k = 0; k < 2; ++k) \
;         acc[ai][bj][m][n] = mma16<Epi::I8>(Bt[n][k], At[m][k], acc[ai][bj][m][n]); __builtin_amdgcn_s_setprio(0); } while (0)
; #define PG8_WAIT_V(n) asm volatile("s_waitcnt vmcnt(" #n ")" ::: "memory")
; template <class Epi, class Sched, bool ALIGN_EPI = false, bool SP2 = false>
; __device__ __forceinline__ void gemm_phase(PG8_LAS unsigned char* lds, const Gemm g, const Sched& S, const Epi& E) {
;     ...
;             PG8_LDB(B0, 0, 0); PG8_LDB(B1, 0, 1); PG8_SCHED; PG8_LDA(At, 0, 0); PG8_STAGE(PG8_SA(1, 1), a1 + hstep, voffA);
;             PG8_WAIT_V(8); PG8_WAIT_L(0); PG8_BAR; PG8_MMA(0, 0, At, B0); PG8_MMA(0, 1, At, B1); PG8_BAR; PG8_SCHED;
;             PG8_LDA(At, 0, 1); PG8_STAGE(PG8_SB(0, 0), b2, voffB); PG8_STAGE(PG8_SB(0, 1), b2 + hstep, voffB); PG8_STAGE(PG8_SA(0, 0), a2, voffA);
;             PG8_WAIT_V(8); PG8_WAIT_L(0); PG8_BAR; PG8_MMA(1, 0, At, B0); PG8_MMA(1, 1, At, B1); PG8_BAR; PG8_SCHED;
;             PG8_LDB(B0, 1, 0); PG8_LDB(B1, 1, 1); PG8_SCHED; PG8_LDA(At, 1, 0); PG8_STAGE(PG8_SA(0, 1), a2 + hstep, voffA);
;             PG8_WAIT_V(8); PG8_WAIT_L(0); PG8_BAR; PG8_MMA(0, 0, At, B0); PG8_MMA(0, 1, At, B1); PG8_BAR; PG8_SCHED;
;             PG8_LDA(At, 1, 1); PG8_STAGE(PG8_SB(1, 0), b3, voffB); PG8_STAGE(PG8_SB(1, 1), b3 + hstep, voffB); PG8_STAGE(PG8_SA(1, 0), a3, voffA);
;             PG8_WAIT_V(8); PG8_WAIT_L(0); PG8_BAR; PG8_MMA(1, 0, At, B0); PG8_MMA(1, 1, At, B1); PG8_BAR; PG8_SCHED;
	s_setprio 1
	s_waitcnt lgkmcnt(0)
	v_mfma_f32_16x16x32_bf16 v[152:155], v[52:55], v[176:179], v[152:155]
	v_mfma_f32_16x16x32_bf16 v[144:147], v[76:79], v[176:179], v[144:147]
	v_mfma_f32_16x16x32_bf16 v[140:143], v[76:79], v[190:193], v[140:143]
	v_mfma_f32_16x16x32_bf16 v[148:151], v[52:55], v[190:193], v[148:151]
	v_mfma_f32_16x16x32_bf16 v[136:139], v[52:55], v[198:201], v[136:139]
	v_mfma_f32_16x16x32_bf16 v[132:135], v[76:79], v[198:201], v[132:135]
	v_mfma_f32_16x16x32_bf16 v[124:127], v[76:79], v[214:217], v[124:127]
	v_mfma_f32_16x16x32_bf16 v[128:131], v[52:55], v[214:217], v[128:131]
	v_mfma_f32_16x16x32_bf16 v[152:155], v[56:59], v[180:183], v[152:155]
	v_mfma_f32_16x16x32_bf16 v[144:147], v[80:83], v[180:183], v[144:147]
	v_mfma_f32_16x16x32_bf16 v[140:143], v[80:83], v[194:197], v[140:143]
	v_mfma_f32_16x16x32_bf16 v[148:151], v[56:59], v[194:197], v[148:151]
	v_mfma_f32_16x16x32_bf16 v[136:139], v[56:59], v[210:213], v[136:139]
	v_mfma_f32_16x16x32_bf16 v[132:135], v[80:83], v[210:213], v[132:135]
	v_mfma_f32_16x16x32_bf16 v[124:127], v[80:83], v[218:221], v[124:127]
	v_mfma_f32_16x16x32_bf16 v[128:131], v[56:59], v[218:221], v[128:131]
	s_setprio 0
	s_setprio 1
	v_mfma_f32_16x16x32_bf16 v[112:115], v[116:119], v[176:179], v[112:115]
	v_mfma_f32_16x16x32_bf16 v[104:107], v[168:171], v[176:179], v[104:107]
	v_mfma_f32_16x16x32_bf16 v[100:103], v[168:171], v[190:193], v[100:103]
	v_mfma_f32_16x16x32_bf16 v[108:111], v[116:119], v[190:193], v[108:111]
	v_mfma_f32_16x16x32_bf16 v[96:99], v[116:119], v[198:201], v[96:99]
	v_mfma_f32_16x16x32_bf16 v[92:95], v[168:171], v[198:201], v[92:95]
	v_mfma_f32_16x16x32_bf16 v[84:87], v[168:171], v[214:217], v[84:87]
	v_mfma_f32_16x16x32_bf16 v[88:91], v[116:119], v[214:217], v[88:91]
	v_mfma_f32_16x16x32_bf16 v[112:115], v[120:123], v[180:183], v[112:115]
	v_mfma_f32_16x16x32_bf16 v[104:107], v[172:175], v[180:183], v[104:107]
	v_mfma_f32_16x16x32_bf16 v[100:103], v[172:175], v[194:197], v[100:103]
	v_mfma_f32_16x16x32_bf16 v[108:111], v[120:123], v[194:197], v[108:111]
	v_mfma_f32_16x16x32_bf16 v[96:99], v[120:123], v[210:213], v[96:99]
	v_mfma_f32_16x16x32_bf16 v[92:95], v[172:175], v[210:213], v[92:95]
	v_mfma_f32_16x16x32_bf16 v[84:87], v[172:175], v[218:221], v[84:87]
	v_mfma_f32_16x16x32_bf16 v[88:91], v[120:123], v[218:221], v[88:91]
	s_setprio 0
	s_barrier
	s_add_i32 s8, s84, s80
	v_lshl_add_u64 v[184:185], s[70:71], 0, v[158:159]
	s_mov_b32 m0, s8
	ds_read_b128 v[176:179], v189 offset:16384
	ds_read_b128 v[180:183], v189 offset:17408
	ds_read_b128 v[190:193], v189 offset:18432
	ds_read_b128 v[194:197], v189 offset:19456
	ds_read_b128 v[198:201], v189 offset:20480
	ds_read_b128 v[210:213], v189 offset:21504
	ds_read_b128 v[214:217], v189 offset:22528
	ds_read_b128 v[218:221], v189 offset:23552
	global_load_lds_dwordx4 v[184:185], off
	s_add_i32 m0, s8, 0x2000
	s_add_u32 s8, s70, 0x80000
	v_lshl_add_u64 v[206:207], s[70:71], 0, v[162:163]
	s_addc_u32 s9, s71, 0
	s_add_i32 s10, s10, s80
	global_load_lds_dwordx4 v[206:207], off
	v_lshl_add_u64 v[2:3], s[8:9], 0, v[158:159]
	s_mov_b32 m0, s10
	v_lshl_add_u64 v[222:223], vcc, 0, v[156:157]
	global_load_lds_dwordx4 v[2:3], off
	v_lshl_add_u64 v[2:3], s[8:9], 0, v[162:163]
	s_add_i32 m0, s10, 0x2000
	v_lshl_add_u64 v[224:225], vcc, 0, v[160:161]
	global_load_lds_dwordx4 v[2:3], off
	s_mov_b32 m0, s58
	s_nop 0
	global_load_lds_dwordx4 v[222:223], off
	s_mov_b32 m0, s12
	s_nop 0
	global_load_lds_dwordx4 v[224:225], off
	s_waitcnt vmcnt(8)
	s_waitcnt lgkmcnt(0)
	s_barrier
	s_setprio 1
	s_waitcnt lgkmcnt(0)
	v_mfma_f32_16x16x32_bf16 v[72:75], v[52:55], v[176:179], v[72:75]
	v_mfma_f32_16x16x32_bf16 v[64:67], v[76:79], v[176:179], v[64:67]
	v_mfma_f32_16x16x32_bf16 v[60:63], v[76:79], v[190:193], v[60:63]
	v_mfma_f32_16x16x32_bf16 v[68:71], v[52:55], v[190:193], v[68:71]
	v_mfma_f32_16x16x32_bf16 v[48:51], v[52:55], v[198:201], v[48:51]
	v_mfma_f32_16x16x32_bf16 v[44:47], v[76:79], v[198:201], v[44:47]
	v_mfma_f32_16x16x32_bf16 v[36:39], v[76:79], v[214:217], v[36:39]
	v_mfma_f32_16x16x32_bf16 v[40:43], v[52:55], v[214:217], v[40:43]
	v_mfma_f32_16x16x32_bf16 v[72:75], v[56:59], v[180:183], v[72:75]
	v_mfma_f32_16x16x32_bf16 v[64:67], v[80:83], v[180:183], v[64:67]
	v_mfma_f32_16x16x32_bf16 v[60:63], v[80:83], v[194:197], v[60:63]
	v_mfma_f32_16x16x32_bf16 v[68:71], v[56:59], v[194:197], v[68:71]
	v_mfma_f32_16x16x32_bf16 v[48:51], v[56:59], v[210:213], v[48:51]
	v_mfma_f32_16x16x32_bf16 v[44:47], v[80:83], v[210:213], v[44:47]
	v_mfma_f32_16x16x32_bf16 v[36:39], v[80:83], v[218:221], v[36:39]
	v_mfma_f32_16x16x32_bf16 v[40:43], v[56:59], v[218:221], v[40:43]
	s_setprio 0
	s_setprio 1
	v_mfma_f32_16x16x32_bf16 v[32:35], v[116:119], v[176:179], v[32:35]
	v_mfma_f32_16x16x32_bf16 v[24:27], v[168:171], v[176:179], v[24:27]
	v_mfma_f32_16x16x32_bf16 v[20:23], v[168:171], v[190:193], v[20:23]
	v_mfma_f32_16x16x32_bf16 v[28:31], v[116:119], v[190:193], v[28:31]
	v_mfma_f32_16x16x32_bf16 v[16:19], v[116:119], v[198:201], v[16:19]
	v_mfma_f32_16x16x32_bf16 v[12:15], v[168:171], v[198:201], v[12:15]
	v_mfma_f32_16x16x32_bf16 v[2:5], v[168:171], v[214:217], v[4:7]
	v_mfma_f32_16x16x32_bf16 v[8:11], v[116:119], v[214:217], v[8:11]
	v_mfma_f32_16x16x32_bf16 v[32:35], v[120:123], v[180:183], v[32:35]
	v_mfma_f32_16x16x32_bf16 v[24:27], v[172:175], v[180:183], v[24:27]
	v_mfma_f32_16x16x32_bf16 v[20:23], v[172:175], v[194:197], v[20:23]
	v_mfma_f32_16x16x32_bf16 v[28:31], v[120:123], v[194:197], v[28:31]
	v_mfma_f32_16x16x32_bf16 v[16:19], v[120:123], v[210:213], v[16:19]
	v_mfma_f32_16x16x32_bf16 v[12:15], v[172:175], v[210:213], v[12:15]
	v_mfma_f32_16x16x32_bf16 v[2:5], v[172:175], v[218:221], v[2:5]
	v_mfma_f32_16x16x32_bf16 v[8:11], v[120:123], v[218:221], v[8:11]
	s_setprio 0
	s_barrier
; #define PG8_STAGE(bufoff, gbase, voff) do { _Pragma("unroll") for (int _i = 0; _i < 2; ++_i) \
;         __builtin_amdgcn_global_load_lds((const unsigned*)((const char*)(gbase) + (voff)[_i]), (PG8_LAS unsigned*)(lds + (bufoff) + ldsw + _i * 8192), 16, 0, 0); } while (0)
; #define PG8_LDA(dst, b, h) do { _Pragma("unroll") for (int m = 0; m < 4; ++m) _Pragma("unroll") for (int k = 0; k < 2; ++k) dst[m][k] = *(const PG8_LAS bf16x8*)(lds + PG8_SA(b, h) + aoff + m * 2048 + k * 1024); } while (0)
; #define PG8_LDB(dst, b, h) do { _Pragma("unroll") for (int n = 0; n < 2; ++n) _Pragma("unroll") for (int k = 0; k < 2; ++k) dst[n][k] = *(const PG8_LAS bf16x8*)(lds + PG8_SB(b, h) + boff + n * 2048 + k * 1024); } while (0)
; #define PG8_MMA(ai, bj, At, Bt) do { __builtin_amdgcn_s_setprio(1); _Pragma("unroll") for (int m = 0; m < 4; ++m) _Pragma("unroll") for (int n = 0; n < 2; ++n) _Pragma("unroll") for (int k = 0; k < 2; ++k) \
;         acc[ai][bj][m][n] = mma16<Epi::I8>(Bt[n][k], At[m][k], acc[ai][bj][m][n]); __builtin_amdgcn_s_setprio(0); } while (0)
; #define PG8_WAIT_V(n) asm volatile("s_waitcnt vmcnt(" #n ")" ::: "memory")
; template <class Epi, class Sched, bool ALIGN_EPI = false, bool SP2 = false>
; __device__ __forceinline__ void gemm_phase(PG8_LAS unsigned char* lds, const Gemm g, const Sched& S, const Epi& E) {
;     ...
;             PG8_LDB(B0, 0, 0); PG8_LDB(B1, 0, 1); PG8_SCHED; PG8_LDA(At, 0, 0); PG8_STAGE(PG8_SA(1, 1), a1 + hstep, voffA);
;             PG8_WAIT_V(8); PG8_WAIT_L(0); PG8_BAR; PG8_MMA(0, 0, At, B0); PG8_MMA(0, 1, At, B1); PG8_BAR; PG8_SCHED;
;             PG8_LDA(At, 0, 1); PG8_STAGE(PG8_SB(0, 0), b2, voffB); PG8_STAGE(PG8_SB(0, 1), b2 + hstep, voffB); PG8_STAGE(PG8_SA(0, 0), a2, voffA);
;             PG8_WAIT_V(8); PG8_WAIT_L(0); PG8_BAR; PG8_MMA(1, 0, At, B0); PG8_MMA(1, 1, At, B1); PG8_BAR; PG8_SCHED;
;             PG8_LDB(B0, 1, 0); PG8_LDB(B1, 1, 1); PG8_SCHED; PG8_LDA(At, 1, 0); PG8_STAGE(PG8_SA(0, 1), a2 + hstep, voffA);
;             PG8_WAIT_V(8); PG8_WAIT_L(0); PG8_BAR; PG8_MMA(0, 0, At, B0); PG8_MMA(0, 1, At, B1); PG8_BAR; PG8_SCHED;
;             PG8_LDA(At, 1, 1); PG8_STAGE(PG8_SB(1, 0), b3, voffB); PG8_STAGE(PG8_SB(1, 1), b3 + hstep, voffB); PG8_STAGE(PG8_SA(1, 0), a3, voffA);
;             PG8_WAIT_V(8); PG8_WAIT_L(0); PG8_BAR; PG8_MMA(1, 0, At, B0); PG8_MMA(1, 1, At, B1); PG8_BAR; PG8_SCHED;
	s_add_i32 s10, 0, 0x18000
	v_add_u32_e32 v0, s10, v188
	s_add_i32 s11, 0, 0x1c000
	ds_read_b128 v[52:55], v0
	ds_read_b128 v[56:59], v0 offset:1024
	ds_read_b128 v[76:79], v0 offset:2048
	ds_read_b128 v[80:83], v0 offset:3072
	v_add_u32_e32 v0, s11, v188
	ds_read_b128 v[116:119], v0
	ds_read_b128 v[120:123], v0 offset:1024
	ds_read_b128 v[168:171], v0 offset:2048
	ds_read_b128 v[172:175], v0 offset:3072
	s_add_u32 s8, vcc_lo, 0x80000
	s_addc_u32 s9, vcc_hi, 0
	s_mov_b32 m0, s13
	v_lshl_add_u64 v[6:7], s[8:9], 0, v[156:157]
	ds_read_b128 v[176:179], v189 offset:32768
	ds_read_b128 v[180:183], v189 offset:33792
	ds_read_b128 v[190:193], v189 offset:34816
	ds_read_b128 v[194:197], v189 offset:35840
	ds_read_b128 v[198:201], v189 offset:36864
	ds_read_b128 v[210:213], v189 offset:37888
	ds_read_b128 v[214:217], v189 offset:38912
	ds_read_b128 v[218:221], v189 offset:39936
	global_load_lds_dwordx4 v[6:7], off
	v_lshl_add_u64 v[6:7], s[8:9], 0, v[160:161]
	s_mov_b32 m0, s66
	s_nop 0
	global_load_lds_dwordx4 v[6:7], off
	s_waitcnt vmcnt(8)
	s_waitcnt lgkmcnt(0)
	s_barrier
	s_setprio 1
	s_waitcnt lgkmcnt(0)
	v_mfma_f32_16x16x32_bf16 v[152:155], v[52:55], v[176:179], v[152:155]
	v_mfma_f32_16x16x32_bf16 v[144:147], v[76:79], v[176:179], v[144:147]
	v_mfma_f32_16x16x32_bf16 v[140:143], v[76:79], v[190:193], v[140:143]
	v_mfma_f32_16x16x32_bf16 v[148:151], v[52:55], v[190:193], v[148:151]
	v_mfma_f32_16x16x32_bf16 v[136:139], v[52:55], v[198:201], v[136:139]
	v_mfma_f32_16x16x32_bf16 v[132:135], v[76:79], v[198:201], v[132:135]
	v_mfma_f32_16x16x32_bf16 v[124:127], v[76:79], v[214:217], v[124:127]
	v_mfma_f32_16x16x32_bf16 v[128:131], v[52:55], v[214:217], v[128:131]
	v_mfma_f32_16x16x32_bf16 v[152:155], v[56:59], v[180:183], v[152:155]
	v_mfma_f32_16x16x32_bf16 v[144:147], v[80:83], v[180:183], v[144:147]
	v_mfma_f32_16x16x32_bf16 v[140:143], v[80:83], v[194:197], v[140:143]
	v_mfma_f32_16x16x32_bf16 v[148:151], v[56:59], v[194:197], v[148:151]
	v_mfma_f32_16x16x32_bf16 v[136:139], v[56:59], v[210:213], v[136:139]
	v_mfma_f32_16x16x32_bf16 v[132:135], v[80:83], v[210:213], v[132:135]
	v_mfma_f32_16x16x32_bf16 v[124:127], v[80:83], v[218:221], v[124:127]
	v_mfma_f32_16x16x32_bf16 v[128:131], v[56:59], v[218:221], v[128:131]
	s_setprio 0
	s_setprio 1
	v_mfma_f32_16x16x32_bf16 v[112:115], v[116:119], v[176:179], v[112:115]
	v_mfma_f32_16x16x32_bf16 v[104:107], v[168:171], v[176:179], v[104:107]
	v_mfma_f32_16x16x32_bf16 v[100:103], v[168:171], v[190:193], v[100:103]
	v_mfma_f32_16x16x32_bf16 v[108:111], v[116:119], v[190:193], v[108:111]
	v_mfma_f32_16x16x32_bf16 v[96:99], v[116:119], v[198:201], v[96:99]
	v_mfma_f32_16x16x32_bf16 v[92:95], v[168:171], v[198:201], v[92:95]
	v_mfma_f32_16x16x32_bf16 v[84:87], v[168:171], v[214:217], v[84:87]
	v_mfma_f32_16x16x32_bf16 v[88:91], v[116:119], v[214:217], v[88:91]
	v_mfma_f32_16x16x32_bf16 v[112:115], v[120:123], v[180:183], v[112:115]
	v_mfma_f32_16x16x32_bf16 v[104:107], v[172:175], v[180:183], v[104:107]
	v_mfma_f32_16x16x32_bf16 v[100:103], v[172:175], v[194:197], v[100:103]
	v_mfma_f32_16x16x32_bf16 v[108:111], v[120:123], v[194:197], v[108:111]
	v_mfma_f32_16x16x32_bf16 v[96:99], v[120:123], v[210:213], v[96:99]
	v_mfma_f32_16x16x32_bf16 v[92:95], v[172:175], v[210:213], v[92:95]
	v_mfma_f32_16x16x32_bf16 v[84:87], v[172:175], v[218:221], v[84:87]
	v_mfma_f32_16x16x32_bf16 v[88:91], v[120:123], v[218:221], v[88:91]
	s_setprio 0
	s_barrier
	s_add_i32 s8, s10, s80
	v_lshl_add_u64 v[6:7], v[184:185], 0, s[92:93]
	s_mov_b32 m0, s8
	ds_read_b128 v[176:179], v189 offset:49152
	ds_read_b128 v[180:183], v189 offset:50176
	ds_read_b128 v[190:193], v189 offset:51200
	ds_read_b128 v[194:197], v189 offset:52224
	ds_read_b128 v[198:201], v189 offset:53248
	ds_read_b128 v[210:213], v189 offset:54272
	ds_read_b128 v[214:217], v189 offset:55296
	ds_read_b128 v[218:221], v189 offset:56320
	global_load_lds_dwordx4 v[6:7], off
	s_add_i32 m0, s8, 0x2000
	s_add_u32 s8, s70, 0x80080
	v_lshl_add_u64 v[6:7], v[206:207], 0, s[92:93]
	s_addc_u32 s9, s71, 0
	s_add_i32 s10, s11, s80
	global_load_lds_dwordx4 v[6:7], off
	v_lshl_add_u64 v[6:7], s[8:9], 0, v[158:159]
	s_mov_b32 m0, s10
	s_nop 0
	global_load_lds_dwordx4 v[6:7], off
	v_lshl_add_u64 v[6:7], s[8:9], 0, v[162:163]
	s_add_i32 m0, s10, 0x2000
	s_nop 0
	global_load_lds_dwordx4 v[6:7], off
	v_lshl_add_u64 v[6:7], v[222:223], 0, s[92:93]
	s_mov_b32 m0, s67
	s_nop 0
	global_load_lds_dwordx4 v[6:7], off
	v_lshl_add_u64 v[6:7], v[224:225], 0, s[92:93]
	s_mov_b32 m0, s81
	s_nop 0
	global_load_lds_dwordx4 v[6:7], off
	s_waitcnt vmcnt(8)
	s_waitcnt lgkmcnt(0)
	s_barrier
	s_setprio 1
	s_waitcnt lgkmcnt(0)
	v_mfma_f32_16x16x32_bf16 v[72:75], v[52:55], v[176:179], v[72:75]
	v_mfma_f32_16x16x32_bf16 v[64:67], v[76:79], v[176:179], v[64:67]
	v_mfma_f32_16x16x32_bf16 v[60:63], v[76:79], v[190:193], v[60:63]
	v_mfma_f32_16x16x32_bf16 v[68:71], v[52:55], v[190:193], v[68:71]
	v_mfma_f32_16x16x32_bf16 v[48:51], v[52:55], v[198:201], v[48:51]
	v_mfma_f32_16x16x32_bf16 v[44:47], v[76:79], v[198:201], v[44:47]
	v_mfma_f32_16x16x32_bf16 v[36:39], v[76:79], v[214:217], v[36:39]
	v_mfma_f32_16x16x32_bf16 v[40:43], v[52:55], v[214:217], v[40:43]
	v_mfma_f32_16x16x32_bf16 v[72:75], v[56:59], v[180:183], v[72:75]
	v_mfma_f32_16x16x32_bf16 v[64:67], v[80:83], v[180:183], v[64:67]
	v_mfma_f32_16x16x32_bf16 v[60:63], v[80:83], v[194:197], v[60:63]
	v_mfma_f32_16x16x32_bf16 v[68:71], v[56:59], v[194:197], v[68:71]
	v_mfma_f32_16x16x32_bf16 v[48:51], v[56:59], v[210:213], v[48:51]
	v_mfma_f32_16x16x32_bf16 v[44:47], v[80:83], v[210:213], v[44:47]
	v_mfma_f32_16x16x32_bf16 v[36:39], v[80:83], v[218:221], v[36:39]
	v_mfma_f32_16x16x32_bf16 v[40:43], v[56:59], v[218:221], v[40:43]
	s_setprio 0
	s_setprio 1
	v_mfma_f32_16x16x32_bf16 v[32:35], v[116:119], v[176:179], v[32:35]
	v_mfma_f32_16x16x32_bf16 v[24:27], v[168:171], v[176:179], v[24:27]
	v_mfma_f32_16x16x32_bf16 v[20:23], v[168:171], v[190:193], v[20:23]
	v_mfma_f32_16x16x32_bf16 v[28:31], v[116:119], v[190:193], v[28:31]
	v_mfma_f32_16x16x32_bf16 v[16:19], v[116:119], v[198:201], v[16:19]
	v_mfma_f32_16x16x32_bf16 v[12:15], v[168:171], v[198:201], v[12:15]
	v_mfma_f32_16x16x32_bf16 v[2:5], v[168:171], v[214:217], v[2:5]
	v_mfma_f32_16x16x32_bf16 v[6:9], v[116:119], v[214:217], v[8:11]
	v_mfma_f32_16x16x32_bf16 v[32:35], v[120:123], v[180:183], v[32:35]
	v_mfma_f32_16x16x32_bf16 v[24:27], v[172:175], v[180:183], v[24:27]
	v_mfma_f32_16x16x32_bf16 v[20:23], v[172:175], v[194:197], v[20:23]
	v_mfma_f32_16x16x32_bf16 v[28:31], v[120:123], v[194:197], v[28:31]
	v_mfma_f32_16x16x32_bf16 v[16:19], v[120:123], v[210:213], v[16:19]
	v_mfma_f32_16x16x32_bf16 v[12:15], v[172:175], v[210:213], v[12:15]
	v_mfma_f32_16x16x32_bf16 v[8:11], v[120:123], v[218:221], v[6:9]
	v_mfma_f32_16x16x32_bf16 v[4:7], v[172:175], v[218:221], v[2:5]
	s_setprio 0
	s_barrier
	s_add_i32 s4, s4, 2
	s_add_u32 s97, s97, 0x100
	s_addc_u32 s96, s96, 0
	s_cmp_gt_u32 s4, 29
	s_mov_b64 s[8:9], s[68:69]
	s_cbranch_scc0 .LBB0_327

; #define PG8_STAGE(bufoff, gbase, voff) do { _Pragma("unroll") for (int _i = 0; _i < 2; ++_i) \
;         __builtin_amdgcn_global_load_lds((const unsigned*)((const char*)(gbase) + (voff)[_i]), (PG8_LAS unsigned*)(lds + (bufoff) + ldsw + _i * 8192), 16, 0, 0); } while (0)
; #define PG8_LDA(dst, b, h) do { _Pragma("unroll") for (int m = 0; m < 4; ++m) _Pragma("unroll") for (int k = 0; k < 2; ++k) dst[m][k] = *(const PG8_LAS bf16x8*)(lds + PG8_SA(b, h) + aoff + m * 2048 + k * 1024); } while (0)
; #define PG8_LDB(dst, b, h) do { _Pragma("unroll") for (int n = 0; n < 2; ++n) _Pragma("unroll") for (int k = 0; k < 2; ++k) dst[n][k] = *(const PG8_LAS bf16x8*)(lds + PG8_SB(b, h) + boff + n * 2048 + k * 1024); } while (0)
; #define PG8_MMA(ai, bj, At, Bt) do { __builtin_amdgcn_s_setprio(1); _Pragma("unroll") for (int m = 0; m < 4; ++m) _Pragma("unroll") for (int n = 0; n < 2; ++n) _Pragma("unroll") for (int k = 0; k < 2; ++k) \
;         acc[ai][bj][m][n] = mma16<Epi::I8>(Bt[n][k], At[m][k], acc[ai][bj][m][n]); __builtin_amdgcn_s_setprio(0); } while (0)
; #define PG8_WAIT_V(n) asm volatile("s_waitcnt vmcnt(" #n ")" ::: "memory")
; template <class Epi, class Sched, bool ALIGN_EPI = false, bool SP2 = false>
; __device__ __forceinline__ void gemm_phase(PG8_LAS unsigned char* lds, const Gemm g, const Sched& S, const Epi& E) {
;     ...
;             PG8_LDB(B0, 0, 0); PG8_LDB(B1, 0, 1); PG8_SCHED; PG8_LDA(At, 0, 0); PG8_STAGE(PG8_SA(1, 1), a1 + hstep, voffA);
;             PG8_WAIT_V(8); PG8_WAIT_L(0); PG8_BAR; PG8_MMA(0, 0, At, B0); PG8_MMA(0, 1, At, B1); PG8_BAR; PG8_SCHED;
;             PG8_LDA(At, 0, 1); PG8_STAGE(PG8_SB(0, 0), b2, voffB); PG8_STAGE(PG8_SB(0, 1), b2 + hstep, voffB); PG8_STAGE(PG8_SA(0, 0), a2, voffA);
;             PG8_WAIT_V(8); PG8_WAIT_L(0); PG8_BAR; PG8_MMA(1, 0, At, B0); PG8_MMA(1, 1, At, B1); PG8_BAR; PG8_SCHED;
;             PG8_LDB(B0, 1, 0); PG8_LDB(B1, 1, 1); PG8_SCHED; PG8_LDA(At, 1, 0); PG8_STAGE(PG8_SA(0, 1), a2 + hstep, voffA);
;             PG8_WAIT_V(8); PG8_WAIT_L(0); PG8_BAR; PG8_MMA(0, 0, At, B0); PG8_MMA(0, 1, At, B1); PG8_BAR; PG8_SCHED;
;             PG8_LDA(At, 1, 1); PG8_STAGE(PG8_SB(1, 0), b3, voffB); PG8_STAGE(PG8_SB(1, 1), b3 + hstep, voffB); PG8_STAGE(PG8_SA(1, 0), a3, voffA);
;             PG8_WAIT_V(8); PG8_WAIT_L(0); PG8_BAR; PG8_MMA(1, 0, At, B0); PG8_MMA(1, 1, At, B1); PG8_BAR; PG8_SCHED;
.Lpeel385:
	s_add_u32 s70, s8, 0x100
	s_addc_u32 s71, s9, 0
	s_add_i32 s84, 0, 0x10000
	s_cmp_eq_u32 s5, 12
	s_cselect_b32 vcc_hi, s1, s71
	s_cselect_b32 vcc_lo, s7, s70
	v_add_u32_e32 v0, s84, v214
	s_cselect_b32 s83, s69, s68
	s_cselect_b32 s82, s81, s85
	s_add_i32 s10, 0, 0x14000
	ds_read_b128 v[44:47], v0
	ds_read_b128 v[52:55], v0 offset:1024
	ds_read_b128 v[60:63], v0 offset:2048
	ds_read_b128 v[64:67], v0 offset:3072
	v_add_u32_e32 v0, s10, v214
	ds_read_b128 v[84:87], v0
	ds_read_b128 v[88:91], v0 offset:1024
	ds_read_b128 v[92:95], v0 offset:2048
	ds_read_b128 v[100:103], v0 offset:3072
	v_lshl_add_u64 v[2:3], s[8:9], 0, v[184:185]
	s_add_i32 m0, s13, 0xc000
	ds_read_b128 v[124:127], v215
	ds_read_b128 v[128:131], v215 offset:1024
	ds_read_b128 v[140:143], v215 offset:2048
	ds_read_b128 v[188:191], v215 offset:3072
	ds_read_b128 v[192:195], v215 offset:4096
	ds_read_b128 v[196:199], v215 offset:5120
	ds_read_b128 v[216:219], v215 offset:6144
	ds_read_b128 v[220:223], v215 offset:7168
	global_load_lds_dwordx4 v[2:3], off
	v_lshl_add_u64 v[2:3], s[8:9], 0, v[186:187]
	s_add_i32 m0, s13, 0xe000
	s_nop 0
	global_load_lds_dwordx4 v[2:3], off
	s_waitcnt vmcnt(8)
	s_waitcnt lgkmcnt(0)
	s_barrier
	s_setprio 1
	s_waitcnt lgkmcnt(0)
	v_mfma_i32_16x16x64_i8 v[172:175], v[44:47], v[124:127], 0
	v_mfma_i32_16x16x64_i8 v[164:167], v[60:63], v[124:127], 0
	v_mfma_i32_16x16x64_i8 v[160:163], v[60:63], v[140:143], 0
	v_mfma_i32_16x16x64_i8 v[168:171], v[44:47], v[140:143], 0
	v_mfma_i32_16x16x64_i8 v[156:159], v[44:47], v[192:195], 0
	v_mfma_i32_16x16x64_i8 v[152:155], v[60:63], v[192:195], 0
	v_mfma_i32_16x16x64_i8 v[144:147], v[60:63], v[216:219], 0
	v_mfma_i32_16x16x64_i8 v[148:151], v[44:47], v[216:219], 0
	v_mfma_i32_16x16x64_i8 v[172:175], v[52:55], v[128:131], v[172:175]
	v_mfma_i32_16x16x64_i8 v[164:167], v[64:67], v[128:131], v[164:167]
	v_mfma_i32_16x16x64_i8 v[160:163], v[64:67], v[188:191], v[160:163]
	v_mfma_i32_16x16x64_i8 v[168:171], v[52:55], v[188:191], v[168:171]
	v_mfma_i32_16x16x64_i8 v[156:159], v[52:55], v[196:199], v[156:159]
	v_mfma_i32_16x16x64_i8 v[152:155], v[64:67], v[196:199], v[152:155]
	v_mfma_i32_16x16x64_i8 v[144:147], v[64:67], v[220:223], v[144:147]
	v_mfma_i32_16x16x64_i8 v[148:151], v[52:55], v[220:223], v[148:151]
	s_setprio 0
	s_setprio 1
	v_mfma_i32_16x16x64_i8 v[136:139], v[84:87], v[124:127], 0
	v_mfma_i32_16x16x64_i8 v[120:123], v[92:95], v[124:127], 0
	v_mfma_i32_16x16x64_i8 v[116:119], v[92:95], v[140:143], 0
	v_mfma_i32_16x16x64_i8 v[108:111], v[92:95], v[192:195], 0
	v_mfma_i32_16x16x64_i8 v[112:115], v[84:87], v[192:195], 0
	v_mfma_i32_16x16x64_i8 v[104:107], v[84:87], v[216:219], 0
	v_mfma_i32_16x16x64_i8 v[96:99], v[92:95], v[216:219], 0
	v_mfma_i32_16x16x64_i8 v[136:139], v[88:91], v[128:131], v[136:139]
	v_mfma_i32_16x16x64_i8 v[120:123], v[100:103], v[128:131], v[120:123]
	v_mfma_i32_16x16x64_i8 v[116:119], v[100:103], v[188:191], v[116:119]
	v_mfma_i32_16x16x64_i8 v[108:111], v[100:103], v[196:199], v[108:111]
	v_mfma_i32_16x16x64_i8 v[112:115], v[88:91], v[196:199], v[112:115]
	v_mfma_i32_16x16x64_i8 v[104:107], v[88:91], v[220:223], v[104:107]
	v_mfma_i32_16x16x64_i8 v[96:99], v[100:103], v[220:223], v[96:99]
	v_mfma_i32_16x16x64_i8 v[124:127], v[84:87], v[140:143], 0
	v_mfma_i32_16x16x64_i8 v[124:127], v[88:91], v[188:191], v[124:127]
	s_setprio 0
	s_barrier
	s_add_i32 s8, s84, s12
	v_lshl_add_u64 v[200:201], s[82:83], 0, v[178:179]
	s_mov_b32 m0, s8
	ds_read_b128 v[128:131], v215 offset:16384
	ds_read_b128 v[132:135], v215 offset:17408
	ds_read_b128 v[140:143], v215 offset:18432
	ds_read_b128 v[188:191], v215 offset:19456
	ds_read_b128 v[192:195], v215 offset:20480
	ds_read_b128 v[196:199], v215 offset:21504
	ds_read_b128 v[216:219], v215 offset:22528
	ds_read_b128 v[220:223], v215 offset:23552
	global_load_lds_dwordx4 v[200:201], off
	s_add_i32 m0, s8, 0x2000
	s_add_u32 s8, s82, 0x40000
	v_lshl_add_u64 v[206:207], s[82:83], 0, v[182:183]
	s_addc_u32 s9, s83, 0
	s_add_i32 s10, s10, s12
	global_load_lds_dwordx4 v[206:207], off
	v_lshl_add_u64 v[2:3], s[8:9], 0, v[178:179]
	s_mov_b32 m0, s10
	v_lshl_add_u64 v[210:211], vcc, 0, v[176:177]
	global_load_lds_dwordx4 v[2:3], off
	v_lshl_add_u64 v[2:3], s[8:9], 0, v[182:183]
	s_add_i32 m0, s10, 0x2000
	v_lshl_add_u64 v[224:225], vcc, 0, v[180:181]
	global_load_lds_dwordx4 v[2:3], off
	s_mov_b32 m0, s13
	s_nop 0
	global_load_lds_dwordx4 v[210:211], off
	s_mov_b32 m0, s66
	s_nop 0
	global_load_lds_dwordx4 v[224:225], off
	s_waitcnt vmcnt(8)
	s_waitcnt lgkmcnt(0)
	s_barrier
	s_setprio 1
	s_waitcnt lgkmcnt(0)
	v_mfma_i32_16x16x64_i8 v[80:83], v[44:47], v[128:131], 0
	v_mfma_i32_16x16x64_i8 v[72:75], v[60:63], v[128:131], 0
	v_mfma_i32_16x16x64_i8 v[68:71], v[60:63], v[140:143], 0
	v_mfma_i32_16x16x64_i8 v[76:79], v[44:47], v[140:143], 0
	v_mfma_i32_16x16x64_i8 v[56:59], v[44:47], v[192:195], 0
	v_mfma_i32_16x16x64_i8 v[48:51], v[60:63], v[192:195], 0
	v_mfma_i32_16x16x64_i8 v[36:39], v[60:63], v[216:219], 0
	v_mfma_i32_16x16x64_i8 v[40:43], v[44:47], v[216:219], 0
	v_mfma_i32_16x16x64_i8 v[80:83], v[52:55], v[132:135], v[80:83]
	v_mfma_i32_16x16x64_i8 v[72:75], v[64:67], v[132:135], v[72:75]
	v_mfma_i32_16x16x64_i8 v[68:71], v[64:67], v[188:191], v[68:71]
	v_mfma_i32_16x16x64_i8 v[76:79], v[52:55], v[188:191], v[76:79]
	v_mfma_i32_16x16x64_i8 v[56:59], v[52:55], v[196:199], v[56:59]
	v_mfma_i32_16x16x64_i8 v[48:51], v[64:67], v[196:199], v[48:51]
	v_mfma_i32_16x16x64_i8 v[36:39], v[64:67], v[220:223], v[36:39]
	v_mfma_i32_16x16x64_i8 v[40:43], v[52:55], v[220:223], v[40:43]
	s_setprio 0
	s_setprio 1
	v_mfma_i32_16x16x64_i8 v[32:35], v[84:87], v[128:131], 0
	v_mfma_i32_16x16x64_i8 v[24:27], v[92:95], v[128:131], 0
	v_mfma_i32_16x16x64_i8 v[20:23], v[92:95], v[140:143], 0
	v_mfma_i32_16x16x64_i8 v[28:31], v[84:87], v[140:143], 0
	v_mfma_i32_16x16x64_i8 v[16:19], v[84:87], v[192:195], 0
	v_mfma_i32_16x16x64_i8 v[12:15], v[92:95], v[192:195], 0
	v_mfma_i32_16x16x64_i8 v[2:5], v[92:95], v[216:219], 0
	v_mfma_i32_16x16x64_i8 v[8:11], v[84:87], v[216:219], 0
	v_mfma_i32_16x16x64_i8 v[32:35], v[88:91], v[132:135], v[32:35]
	v_mfma_i32_16x16x64_i8 v[24:27], v[100:103], v[132:135], v[24:27]
	v_mfma_i32_16x16x64_i8 v[20:23], v[100:103], v[188:191], v[20:23]
	v_mfma_i32_16x16x64_i8 v[28:31], v[88:91], v[188:191], v[28:31]
	v_mfma_i32_16x16x64_i8 v[16:19], v[88:91], v[196:199], v[16:19]
	v_mfma_i32_16x16x64_i8 v[12:15], v[100:103], v[196:199], v[12:15]
	v_mfma_i32_16x16x64_i8 v[2:5], v[100:103], v[220:223], v[2:5]
	v_mfma_i32_16x16x64_i8 v[8:11], v[88:91], v[220:223], v[8:11]
	s_setprio 0
	s_barrier
; #define PG8_STAGE(bufoff, gbase, voff) do { _Pragma("unroll") for (int _i = 0; _i < 2; ++_i) \
;         __builtin_amdgcn_global_load_lds((const unsigned*)((const char*)(gbase) + (voff)[_i]), (PG8_LAS unsigned*)(lds + (bufoff) + ldsw + _i * 8192), 16, 0, 0); } while (0)
; #define PG8_LDA(dst, b, h) do { _Pragma("unroll") for (int m = 0; m < 4; ++m) _Pragma("unroll") for (int k = 0; k < 2; ++k) dst[m][k] = *(const PG8_LAS bf16x8*)(lds + PG8_SA(b, h) + aoff + m * 2048 + k * 1024); } while (0)
; #define PG8_LDB(dst, b, h) do { _Pragma("unroll") for (int n = 0; n < 2; ++n) _Pragma("unroll") for (int k = 0; k < 2; ++k) dst[n][k] = *(const PG8_LAS bf16x8*)(lds + PG8_SB(b, h) + boff + n * 2048 + k * 1024); } while (0)
; #define PG8_MMA(ai, bj, At, Bt) do { __builtin_amdgcn_s_setprio(1); _Pragma("unroll") for (int m = 0; m < 4; ++m) _Pragma("unroll") for (int n = 0; n < 2; ++n) _Pragma("unroll") for (int k = 0; k < 2; ++k) \
;         acc[ai][bj][m][n] = mma16<Epi::I8>(Bt[n][k], At[m][k], acc[ai][bj][m][n]); __builtin_amdgcn_s_setprio(0); } while (0)
; #define PG8_WAIT_V(n) asm volatile("s_waitcnt vmcnt(" #n ")" ::: "memory")
; template <class Epi, class Sched, bool ALIGN_EPI = false, bool SP2 = false>
; __device__ __forceinline__ void gemm_phase(PG8_LAS unsigned char* lds, const Gemm g, const Sched& S, const Epi& E) {
;     ...
;             PG8_LDB(B0, 0, 0); PG8_LDB(B1, 0, 1); PG8_SCHED; PG8_LDA(At, 0, 0); PG8_STAGE(PG8_SA(1, 1), a1 + hstep, voffA);
;             PG8_WAIT_V(8); PG8_WAIT_L(0); PG8_BAR; PG8_MMA(0, 0, At, B0); PG8_MMA(0, 1, At, B1); PG8_BAR; PG8_SCHED;
;             PG8_LDA(At, 0, 1); PG8_STAGE(PG8_SB(0, 0), b2, voffB); PG8_STAGE(PG8_SB(0, 1), b2 + hstep, voffB); PG8_STAGE(PG8_SA(0, 0), a2, voffA);
;             PG8_WAIT_V(8); PG8_WAIT_L(0); PG8_BAR; PG8_MMA(1, 0, At, B0); PG8_MMA(1, 1, At, B1); PG8_BAR; PG8_SCHED;
;             PG8_LDB(B0, 1, 0); PG8_LDB(B1, 1, 1); PG8_SCHED; PG8_LDA(At, 1, 0); PG8_STAGE(PG8_SA(0, 1), a2 + hstep, voffA);
;             PG8_WAIT_V(8); PG8_WAIT_L(0); PG8_BAR; PG8_MMA(0, 0, At, B0); PG8_MMA(0, 1, At, B1); PG8_BAR; PG8_SCHED;
;             PG8_LDA(At, 1, 1); PG8_STAGE(PG8_SB(1, 0), b3, voffB); PG8_STAGE(PG8_SB(1, 1), b3 + hstep, voffB); PG8_STAGE(PG8_SA(1, 0), a3, voffA);
;             PG8_WAIT_V(8); PG8_WAIT_L(0); PG8_BAR; PG8_MMA(1, 0, At, B0); PG8_MMA(1, 1, At, B1); PG8_BAR; PG8_SCHED;
	s_add_i32 s10, 0, 0x18000
	v_add_u32_e32 v0, s10, v214
	s_add_i32 s11, 0, 0x1c000
	ds_read_b128 v[44:47], v0
	ds_read_b128 v[52:55], v0 offset:1024
	ds_read_b128 v[60:63], v0 offset:2048
	ds_read_b128 v[64:67], v0 offset:3072
	v_add_u32_e32 v0, s11, v214
	ds_read_b128 v[84:87], v0
	ds_read_b128 v[88:91], v0 offset:1024
	ds_read_b128 v[92:95], v0 offset:2048
	ds_read_b128 v[100:103], v0 offset:3072
	s_add_u32 s8, vcc_lo, 0x40000
	s_addc_u32 s9, vcc_hi, 0
	s_mov_b32 m0, s67
	v_lshl_add_u64 v[6:7], s[8:9], 0, v[176:177]
	ds_read_b128 v[128:131], v215 offset:32768
	ds_read_b128 v[132:135], v215 offset:33792
	ds_read_b128 v[140:143], v215 offset:34816
	ds_read_b128 v[188:191], v215 offset:35840
	ds_read_b128 v[192:195], v215 offset:36864
	ds_read_b128 v[196:199], v215 offset:37888
	ds_read_b128 v[216:219], v215 offset:38912
	ds_read_b128 v[220:223], v215 offset:39936
	global_load_lds_dwordx4 v[6:7], off
	v_lshl_add_u64 v[6:7], s[8:9], 0, v[180:181]
	s_mov_b32 m0, s80
	s_nop 0
	global_load_lds_dwordx4 v[6:7], off
	s_waitcnt vmcnt(8)
	s_waitcnt lgkmcnt(0)
	s_barrier
	s_setprio 1
	s_waitcnt lgkmcnt(0)
	v_mfma_i32_16x16x64_i8 v[172:175], v[44:47], v[128:131], v[172:175]
	v_mfma_i32_16x16x64_i8 v[164:167], v[60:63], v[128:131], v[164:167]
	v_mfma_i32_16x16x64_i8 v[160:163], v[60:63], v[140:143], v[160:163]
	v_mfma_i32_16x16x64_i8 v[168:171], v[44:47], v[140:143], v[168:171]
	v_mfma_i32_16x16x64_i8 v[156:159], v[44:47], v[192:195], v[156:159]
	v_mfma_i32_16x16x64_i8 v[152:155], v[60:63], v[192:195], v[152:155]
	v_mfma_i32_16x16x64_i8 v[144:147], v[60:63], v[216:219], v[144:147]
	v_mfma_i32_16x16x64_i8 v[148:151], v[44:47], v[216:219], v[148:151]
	v_mfma_i32_16x16x64_i8 v[172:175], v[52:55], v[132:135], v[172:175]
	v_mfma_i32_16x16x64_i8 v[164:167], v[64:67], v[132:135], v[164:167]
	v_mfma_i32_16x16x64_i8 v[160:163], v[64:67], v[188:191], v[160:163]
	v_mfma_i32_16x16x64_i8 v[168:171], v[52:55], v[188:191], v[168:171]
	v_mfma_i32_16x16x64_i8 v[156:159], v[52:55], v[196:199], v[156:159]
	v_mfma_i32_16x16x64_i8 v[152:155], v[64:67], v[196:199], v[152:155]
	v_mfma_i32_16x16x64_i8 v[144:147], v[64:67], v[220:223], v[144:147]
	v_mfma_i32_16x16x64_i8 v[148:151], v[52:55], v[220:223], v[148:151]
	s_setprio 0
	s_setprio 1
	v_mfma_i32_16x16x64_i8 v[136:139], v[84:87], v[128:131], v[136:139]
	v_mfma_i32_16x16x64_i8 v[120:123], v[92:95], v[128:131], v[120:123]
	v_mfma_i32_16x16x64_i8 v[116:119], v[92:95], v[140:143], v[116:119]
	v_mfma_i32_16x16x64_i8 v[124:127], v[84:87], v[140:143], v[124:127]
	v_mfma_i32_16x16x64_i8 v[112:115], v[84:87], v[192:195], v[112:115]
	v_mfma_i32_16x16x64_i8 v[108:111], v[92:95], v[192:195], v[108:111]
	v_mfma_i32_16x16x64_i8 v[96:99], v[92:95], v[216:219], v[96:99]
	v_mfma_i32_16x16x64_i8 v[104:107], v[84:87], v[216:219], v[104:107]
	v_mfma_i32_16x16x64_i8 v[136:139], v[88:91], v[132:135], v[136:139]
	v_mfma_i32_16x16x64_i8 v[120:123], v[100:103], v[132:135], v[120:123]
	v_mfma_i32_16x16x64_i8 v[116:119], v[100:103], v[188:191], v[116:119]
	v_mfma_i32_16x16x64_i8 v[132:135], v[88:91], v[188:191], v[124:127]
	v_mfma_i32_16x16x64_i8 v[112:115], v[88:91], v[196:199], v[112:115]
	v_mfma_i32_16x16x64_i8 v[108:111], v[100:103], v[196:199], v[108:111]
	v_mfma_i32_16x16x64_i8 v[96:99], v[100:103], v[220:223], v[96:99]
	v_mfma_i32_16x16x64_i8 v[104:107], v[88:91], v[220:223], v[104:107]
	s_setprio 0
	s_barrier
	s_add_i32 s8, s10, s12
	v_lshl_add_u64 v[6:7], v[200:201], 0, s[92:93]
	s_mov_b32 m0, s8
	ds_read_b128 v[124:127], v215 offset:49152
	ds_read_b128 v[128:131], v215 offset:50176
	ds_read_b128 v[140:143], v215 offset:51200
	ds_read_b128 v[188:191], v215 offset:52224
	ds_read_b128 v[192:195], v215 offset:53248
	ds_read_b128 v[196:199], v215 offset:54272
	ds_read_b128 v[216:219], v215 offset:55296
	ds_read_b128 v[220:223], v215 offset:56320
	global_load_lds_dwordx4 v[6:7], off
	s_add_i32 m0, s8, 0x2000
	s_add_u32 s8, s82, 0x40080
	v_lshl_add_u64 v[6:7], v[206:207], 0, s[92:93]
	s_addc_u32 s9, s83, 0
	s_add_i32 s10, s11, s12
	global_load_lds_dwordx4 v[6:7], off
	v_lshl_add_u64 v[6:7], s[8:9], 0, v[178:179]
	s_mov_b32 m0, s10
	s_nop 0
	global_load_lds_dwordx4 v[6:7], off
	v_lshl_add_u64 v[6:7], s[8:9], 0, v[182:183]
	s_add_i32 m0, s10, 0x2000
	s_nop 0
	global_load_lds_dwordx4 v[6:7], off
	v_lshl_add_u64 v[6:7], v[210:211], 0, s[92:93]
	s_mov_b32 m0, s58
	s_nop 0
	global_load_lds_dwordx4 v[6:7], off
	v_lshl_add_u64 v[6:7], v[224:225], 0, s[92:93]
	s_mov_b32 m0, s4
	s_nop 0
	global_load_lds_dwordx4 v[6:7], off
	s_waitcnt vmcnt(8)
	s_waitcnt lgkmcnt(0)
	s_barrier
	s_setprio 1
	s_waitcnt lgkmcnt(0)
	v_mfma_i32_16x16x64_i8 v[80:83], v[44:47], v[124:127], v[80:83]
	v_mfma_i32_16x16x64_i8 v[72:75], v[60:63], v[124:127], v[72:75]
	v_mfma_i32_16x16x64_i8 v[68:71], v[60:63], v[140:143], v[68:71]
	v_mfma_i32_16x16x64_i8 v[76:79], v[44:47], v[140:143], v[76:79]
	v_mfma_i32_16x16x64_i8 v[56:59], v[44:47], v[192:195], v[56:59]
	v_mfma_i32_16x16x64_i8 v[48:51], v[60:63], v[192:195], v[48:51]
	v_mfma_i32_16x16x64_i8 v[36:39], v[60:63], v[216:219], v[36:39]
	v_mfma_i32_16x16x64_i8 v[40:43], v[44:47], v[216:219], v[40:43]
	v_mfma_i32_16x16x64_i8 v[80:83], v[52:55], v[128:131], v[80:83]
	v_mfma_i32_16x16x64_i8 v[72:75], v[64:67], v[128:131], v[72:75]
	v_mfma_i32_16x16x64_i8 v[68:71], v[64:67], v[188:191], v[68:71]
	v_mfma_i32_16x16x64_i8 v[76:79], v[52:55], v[188:191], v[76:79]
	v_mfma_i32_16x16x64_i8 v[56:59], v[52:55], v[196:199], v[56:59]
	v_mfma_i32_16x16x64_i8 v[48:51], v[64:67], v[196:199], v[48:51]
	v_mfma_i32_16x16x64_i8 v[36:39], v[64:67], v[220:223], v[36:39]
	v_mfma_i32_16x16x64_i8 v[40:43], v[52:55], v[220:223], v[40:43]
	s_setprio 0
	s_setprio 1
	v_mfma_i32_16x16x64_i8 v[32:35], v[84:87], v[124:127], v[32:35]
	v_mfma_i32_16x16x64_i8 v[24:27], v[92:95], v[124:127], v[24:27]
	v_mfma_i32_16x16x64_i8 v[20:23], v[92:95], v[140:143], v[20:23]
	v_mfma_i32_16x16x64_i8 v[28:31], v[84:87], v[140:143], v[28:31]
	v_mfma_i32_16x16x64_i8 v[16:19], v[84:87], v[192:195], v[16:19]
	v_mfma_i32_16x16x64_i8 v[12:15], v[92:95], v[192:195], v[12:15]
	v_mfma_i32_16x16x64_i8 v[2:5], v[92:95], v[216:219], v[2:5]
	v_mfma_i32_16x16x64_i8 v[6:9], v[84:87], v[216:219], v[8:11]
	v_mfma_i32_16x16x64_i8 v[32:35], v[88:91], v[128:131], v[32:35]
	v_mfma_i32_16x16x64_i8 v[24:27], v[100:103], v[128:131], v[24:27]
	v_mfma_i32_16x16x64_i8 v[20:23], v[100:103], v[188:191], v[20:23]
	v_mfma_i32_16x16x64_i8 v[28:31], v[88:91], v[188:191], v[28:31]
	v_mfma_i32_16x16x64_i8 v[16:19], v[88:91], v[196:199], v[16:19]
	v_mfma_i32_16x16x64_i8 v[12:15], v[100:103], v[196:199], v[12:15]
	v_mfma_i32_16x16x64_i8 v[8:11], v[88:91], v[220:223], v[6:9]
	v_mfma_i32_16x16x64_i8 v[4:7], v[100:103], v[220:223], v[2:5]
	s_setprio 0
	s_barrier
	s_add_i32 s5, s5, 2
	s_add_u32 s85, s85, 0x100
	s_addc_u32 s68, s68, 0
	s_cmp_gt_u32 s5, 13
	s_mov_b64 s[8:9], s[70:71]
	s_cbranch_scc0 .LBB0_385
	s_branch .Lpeelx385
; #define PG8_STAGE(bufoff, gbase, voff) do { _Pragma("unroll") for (int _i = 0; _i < 2; ++_i) \
;         __builtin_amdgcn_global_load_lds((const unsigned*)((const char*)(gbase) + (voff)[_i]), (PG8_LAS unsigned*)(lds + (bufoff) + ldsw + _i * 8192), 16, 0, 0); } while (0)
; #define PG8_LDA(dst, b, h) do { _Pragma("unroll") for (int m = 0; m < 4; ++m) _Pragma("unroll") for (int k = 0; k < 2; ++k) dst[m][k] = *(const PG8_LAS bf16x8*)(lds + PG8_SA(b, h) + aoff + m * 2048 + k * 1024); } while (0)
; #define PG8_LDB(dst, b, h) do { _Pragma("unroll") for (int n = 0; n < 2; ++n) _Pragma("unroll") for (int k = 0; k < 2; ++k) dst[n][k] = *(const PG8_LAS bf16x8*)(lds + PG8_SB(b, h) + boff + n * 2048 + k * 1024); } while (0)
; #define PG8_MMA(ai, bj, At, Bt) do { __builtin_amdgcn_s_setprio(1); _Pragma("unroll") for (int m = 0; m < 4; ++m) _Pragma("unroll") for (int n = 0; n < 2; ++n) _Pragma("unroll") for (int k = 0; k < 2; ++k) \
;         acc[ai][bj][m][n] = mma16<Epi::I8>(Bt[n][k], At[m][k], acc[ai][bj][m][n]); __builtin_amdgcn_s_setprio(0); } while (0)
; #define PG8_WAIT_V(n) asm volatile("s_waitcnt vmcnt(" #n ")" ::: "memory")
; template <class Epi, class Sched, bool ALIGN_EPI = false, bool SP2 = false>
; __device__ __forceinline__ void gemm_phase(PG8_LAS unsigned char* lds, const Gemm g, const Sched& S, const Epi& E) {
;     ...
;             PG8_LDB(B0, 0, 0); PG8_LDB(B1, 0, 1); PG8_SCHED; PG8_LDA(At, 0, 0); PG8_STAGE(PG8_SA(1, 1), a1 + hstep, voffA);
;             PG8_WAIT_V(8); PG8_WAIT_L(0); PG8_BAR; PG8_MMA(0, 0, At, B0); PG8_MMA(0, 1, At, B1); PG8_BAR; PG8_SCHED;
;             PG8_LDA(At, 0, 1); PG8_STAGE(PG8_SB(0, 0), b2, voffB); PG8_STAGE(PG8_SB(0, 1), b2 + hstep, voffB); PG8_STAGE(PG8_SA(0, 0), a2, voffA);
;             PG8_WAIT_V(8); PG8_WAIT_L(0); PG8_BAR; PG8_MMA(1, 0, At, B0); PG8_MMA(1, 1, At, B1); PG8_BAR; PG8_SCHED;
;             PG8_LDB(B0, 1, 0); PG8_LDB(B1, 1, 1); PG8_SCHED; PG8_LDA(At, 1, 0); PG8_STAGE(PG8_SA(0, 1), a2 + hstep, voffA);
;             PG8_WAIT_V(8); PG8_WAIT_L(0); PG8_BAR; PG8_MMA(0, 0, At, B0); PG8_MMA(0, 1, At, B1); PG8_BAR; PG8_SCHED;
;             PG8_LDA(At, 1, 1); PG8_STAGE(PG8_SB(1, 0), b3, voffB); PG8_STAGE(PG8_SB(1, 1), b3 + hstep, voffB); PG8_STAGE(PG8_SA(1, 0), a3, voffA);
;             PG8_WAIT_V(8); PG8_WAIT_L(0); PG8_BAR; PG8_MMA(1, 0, At, B0); PG8_MMA(1, 1, At, B1); PG8_BAR; PG8_SCHED;
.LBB0_385:
	s_add_u32 s70, s8, 0x100
	s_addc_u32 s71, s9, 0
	s_add_i32 s84, 0, 0x10000
	s_cmp_eq_u32 s5, 12
	s_cselect_b32 vcc_hi, s1, s71
	s_cselect_b32 vcc_lo, s7, s70
	v_add_u32_e32 v0, s84, v214
	s_cselect_b32 s83, s69, s68
	s_cselect_b32 s82, s81, s85
	s_add_i32 s10, 0, 0x14000
	ds_read_b128 v[44:47], v0
	ds_read_b128 v[52:55], v0 offset:1024
	ds_read_b128 v[60:63], v0 offset:2048
	ds_read_b128 v[64:67], v0 offset:3072
	v_add_u32_e32 v0, s10, v214
	ds_read_b128 v[84:87], v0
	ds_read_b128 v[88:91], v0 offset:1024
	ds_read_b128 v[92:95], v0 offset:2048
	ds_read_b128 v[100:103], v0 offset:3072
	v_lshl_add_u64 v[2:3], s[8:9], 0, v[184:185]
	s_add_i32 m0, s13, 0xc000
	ds_read_b128 v[124:127], v215
	ds_read_b128 v[128:131], v215 offset:1024
	ds_read_b128 v[140:143], v215 offset:2048
	ds_read_b128 v[188:191], v215 offset:3072
	ds_read_b128 v[192:195], v215 offset:4096
	ds_read_b128 v[196:199], v215 offset:5120
	ds_read_b128 v[216:219], v215 offset:6144
	ds_read_b128 v[220:223], v215 offset:7168
	global_load_lds_dwordx4 v[2:3], off
	v_lshl_add_u64 v[2:3], s[8:9], 0, v[186:187]
	s_add_i32 m0, s13, 0xe000
	s_nop 0
	global_load_lds_dwordx4 v[2:3], off
	s_waitcnt vmcnt(8)
	s_waitcnt lgkmcnt(0)
	s_barrier
	s_setprio 1
	s_waitcnt lgkmcnt(0)
	v_mfma_i32_16x16x64_i8 v[172:175], v[44:47], v[124:127], v[172:175]
	v_mfma_i32_16x16x64_i8 v[164:167], v[60:63], v[124:127], v[164:167]
	v_mfma_i32_16x16x64_i8 v[160:163], v[60:63], v[140:143], v[160:163]
	v_mfma_i32_16x16x64_i8 v[168:171], v[44:47], v[140:143], v[168:171]
	v_mfma_i32_16x16x64_i8 v[156:159], v[44:47], v[192:195], v[156:159]
	v_mfma_i32_16x16x64_i8 v[152:155], v[60:63], v[192:195], v[152:155]
	v_mfma_i32_16x16x64_i8 v[144:147], v[60:63], v[216:219], v[144:147]
	v_mfma_i32_16x16x64_i8 v[148:151], v[44:47], v[216:219], v[148:151]
	v_mfma_i32_16x16x64_i8 v[172:175], v[52:55], v[128:131], v[172:175]
	v_mfma_i32_16x16x64_i8 v[164:167], v[64:67], v[128:131], v[164:167]
	v_mfma_i32_16x16x64_i8 v[160:163], v[64:67], v[188:191], v[160:163]
	v_mfma_i32_16x16x64_i8 v[168:171], v[52:55], v[188:191], v[168:171]
	v_mfma_i32_16x16x64_i8 v[156:159], v[52:55], v[196:199], v[156:159]
	v_mfma_i32_16x16x64_i8 v[152:155], v[64:67], v[196:199], v[152:155]
	v_mfma_i32_16x16x64_i8 v[144:147], v[64:67], v[220:223], v[144:147]
	v_mfma_i32_16x16x64_i8 v[148:151], v[52:55], v[220:223], v[148:151]
	s_setprio 0
	s_setprio 1
	v_mfma_i32_16x16x64_i8 v[136:139], v[84:87], v[124:127], v[136:139]
	v_mfma_i32_16x16x64_i8 v[120:123], v[92:95], v[124:127], v[120:123]
	v_mfma_i32_16x16x64_i8 v[116:119], v[92:95], v[140:143], v[116:119]
	v_mfma_i32_16x16x64_i8 v[108:111], v[92:95], v[192:195], v[108:111]
	v_mfma_i32_16x16x64_i8 v[112:115], v[84:87], v[192:195], v[112:115]
	v_mfma_i32_16x16x64_i8 v[104:107], v[84:87], v[216:219], v[104:107]
	v_mfma_i32_16x16x64_i8 v[96:99], v[92:95], v[216:219], v[96:99]
	v_mfma_i32_16x16x64_i8 v[136:139], v[88:91], v[128:131], v[136:139]
	v_mfma_i32_16x16x64_i8 v[120:123], v[100:103], v[128:131], v[120:123]
	v_mfma_i32_16x16x64_i8 v[116:119], v[100:103], v[188:191], v[116:119]
	v_mfma_i32_16x16x64_i8 v[108:111], v[100:103], v[196:199], v[108:111]
	v_mfma_i32_16x16x64_i8 v[112:115], v[88:91], v[196:199], v[112:115]
	v_mfma_i32_16x16x64_i8 v[104:107], v[88:91], v[220:223], v[104:107]
	v_mfma_i32_16x16x64_i8 v[96:99], v[100:103], v[220:223], v[96:99]
	v_mfma_i32_16x16x64_i8 v[124:127], v[84:87], v[140:143], v[132:135]
	v_mfma_i32_16x16x64_i8 v[124:127], v[88:91], v[188:191], v[124:127]
	s_setprio 0
	s_barrier
	s_add_i32 s8, s84, s12
	v_lshl_add_u64 v[200:201], s[82:83], 0, v[178:179]
	s_mov_b32 m0, s8
	ds_read_b128 v[128:131], v215 offset:16384
	ds_read_b128 v[132:135], v215 offset:17408
	ds_read_b128 v[140:143], v215 offset:18432
	ds_read_b128 v[188:191], v215 offset:19456
	ds_read_b128 v[192:195], v215 offset:20480
	ds_read_b128 v[196:199], v215 offset:21504
	ds_read_b128 v[216:219], v215 offset:22528
	ds_read_b128 v[220:223], v215 offset:23552
	global_load_lds_dwordx4 v[200:201], off
	s_add_i32 m0, s8, 0x2000
	s_add_u32 s8, s82, 0x40000
	v_lshl_add_u64 v[206:207], s[82:83], 0, v[182:183]
	s_addc_u32 s9, s83, 0
	s_add_i32 s10, s10, s12
	global_load_lds_dwordx4 v[206:207], off
	v_lshl_add_u64 v[2:3], s[8:9], 0, v[178:179]
	s_mov_b32 m0, s10
	v_lshl_add_u64 v[210:211], vcc, 0, v[176:177]
	global_load_lds_dwordx4 v[2:3], off
	v_lshl_add_u64 v[2:3], s[8:9], 0, v[182:183]
	s_add_i32 m0, s10, 0x2000
	v_lshl_add_u64 v[224:225], vcc, 0, v[180:181]
	global_load_lds_dwordx4 v[2:3], off
	s_mov_b32 m0, s13
	s_nop 0
	global_load_lds_dwordx4 v[210:211], off
	s_mov_b32 m0, s66
	s_nop 0
	global_load_lds_dwordx4 v[224:225], off
	s_waitcnt vmcnt(8)
	s_waitcnt lgkmcnt(0)
	s_barrier
; #define PG8_STAGE(bufoff, gbase, voff) do { _Pragma("unroll") for (int _i = 0; _i < 2; ++_i) \
;         __builtin_amdgcn_global_load_lds((const unsigned*)((const char*)(gbase) + (voff)[_i]), (PG8_LAS unsigned*)(lds + (bufoff) + ldsw + _i * 8192), 16, 0, 0); } while (0)
; #define PG8_LDA(dst, b, h) do { _Pragma("unroll") for (int m = 0; m < 4; ++m) _Pragma("unroll") for (int k = 0; k < 2; ++k) dst[m][k] = *(const PG8_LAS bf16x8*)(lds + PG8_SA(b, h) + aoff + m * 2048 + k * 1024); } while (0)
; #define PG8_LDB(dst, b, h) do { _Pragma("unroll") for (int n = 0; n < 2; ++n) _Pragma("unroll") for (int k = 0; k < 2; ++k) dst[n][k] = *(const PG8_LAS bf16x8*)(lds + PG8_SB(b, h) + boff + n * 2048 + k * 1024); } while (0)
; #define PG8_MMA(ai, bj, At, Bt) do { __builtin_amdgcn_s_setprio(1); _Pragma("unroll") for (int m = 0; m < 4; ++m) _Pragma("unroll") for (int n = 0; n < 2; ++n) _Pragma("unroll") for (int k = 0; k < 2; ++k) \
;         acc[ai][bj][m][n] = mma16<Epi::I8>(Bt[n][k], At[m][k], acc[ai][bj][m][n]); __builtin_amdgcn_s_setprio(0); } while (0)
; #define PG8_WAIT_V(n) asm volatile("s_waitcnt vmcnt(" #n ")" ::: "memory")
; template <class Epi, class Sched, bool ALIGN_EPI = false, bool SP2 = false>
; __device__ __forceinline__ void gemm_phase(PG8_LAS unsigned char* lds, const Gemm g, const Sched& S, const Epi& E) {
;     ...
;             PG8_LDB(B0, 0, 0); PG8_LDB(B1, 0, 1); PG8_SCHED; PG8_LDA(At, 0, 0); PG8_STAGE(PG8_SA(1, 1), a1 + hstep, voffA);
;             PG8_WAIT_V(8); PG8_WAIT_L(0); PG8_BAR; PG8_MMA(0, 0, At, B0); PG8_MMA(0, 1, At, B1); PG8_BAR; PG8_SCHED;
;             PG8_LDA(At, 0, 1); PG8_STAGE(PG8_SB(0, 0), b2, voffB); PG8_STAGE(PG8_SB(0, 1), b2 + hstep, voffB); PG8_STAGE(PG8_SA(0, 0), a2, voffA);
;             PG8_WAIT_V(8); PG8_WAIT_L(0); PG8_BAR; PG8_MMA(1, 0, At, B0); PG8_MMA(1, 1, At, B1); PG8_BAR; PG8_SCHED;
;             PG8_LDB(B0, 1, 0); PG8_LDB(B1, 1, 1); PG8_SCHED; PG8_LDA(At, 1, 0); PG8_STAGE(PG8_SA(0, 1), a2 + hstep, voffA);
;             PG8_WAIT_V(8); PG8_WAIT_L(0); PG8_BAR; PG8_MMA(0, 0, At, B0); PG8_MMA(0, 1, At, B1); PG8_BAR; PG8_SCHED;
;             PG8_LDA(At, 1, 1); PG8_STAGE(PG8_SB(1, 0), b3, voffB); PG8_STAGE(PG8_SB(1, 1), b3 + hstep, voffB); PG8_STAGE(PG8_SA(1, 0), a3, voffA);
;             PG8_WAIT_V(8); PG8_WAIT_L(0); PG8_BAR; PG8_MMA(1, 0, At, B0); PG8_MMA(1, 1, At, B1); PG8_BAR; PG8_SCHED;
	s_setprio 1
	s_waitcnt lgkmcnt(0)
	v_mfma_i32_16x16x64_i8 v[80:83], v[44:47], v[128:131], v[80:83]
	v_mfma_i32_16x16x64_i8 v[72:75], v[60:63], v[128:131], v[72:75]
	v_mfma_i32_16x16x64_i8 v[68:71], v[60:63], v[140:143], v[68:71]
	v_mfma_i32_16x16x64_i8 v[76:79], v[44:47], v[140:143], v[76:79]
	v_mfma_i32_16x16x64_i8 v[56:59], v[44:47], v[192:195], v[56:59]
	v_mfma_i32_16x16x64_i8 v[48:51], v[60:63], v[192:195], v[48:51]
	v_mfma_i32_16x16x64_i8 v[36:39], v[60:63], v[216:219], v[36:39]
	v_mfma_i32_16x16x64_i8 v[40:43], v[44:47], v[216:219], v[40:43]
	v_mfma_i32_16x16x64_i8 v[80:83], v[52:55], v[132:135], v[80:83]
	v_mfma_i32_16x16x64_i8 v[72:75], v[64:67], v[132:135], v[72:75]
	v_mfma_i32_16x16x64_i8 v[68:71], v[64:67], v[188:191], v[68:71]
	v_mfma_i32_16x16x64_i8 v[76:79], v[52:55], v[188:191], v[76:79]
	v_mfma_i32_16x16x64_i8 v[56:59], v[52:55], v[196:199], v[56:59]
	v_mfma_i32_16x16x64_i8 v[48:51], v[64:67], v[196:199], v[48:51]
	v_mfma_i32_16x16x64_i8 v[36:39], v[64:67], v[220:223], v[36:39]
	v_mfma_i32_16x16x64_i8 v[40:43], v[52:55], v[220:223], v[40:43]
	s_setprio 0
	s_setprio 1
	v_mfma_i32_16x16x64_i8 v[32:35], v[84:87], v[128:131], v[32:35]
	v_mfma_i32_16x16x64_i8 v[24:27], v[92:95], v[128:131], v[24:27]
	v_mfma_i32_16x16x64_i8 v[20:23], v[92:95], v[140:143], v[20:23]
	v_mfma_i32_16x16x64_i8 v[28:31], v[84:87], v[140:143], v[28:31]
	v_mfma_i32_16x16x64_i8 v[16:19], v[84:87], v[192:195], v[16:19]
	v_mfma_i32_16x16x64_i8 v[12:15], v[92:95], v[192:195], v[12:15]
	v_mfma_i32_16x16x64_i8 v[2:5], v[92:95], v[216:219], v[4:7]
	v_mfma_i32_16x16x64_i8 v[8:11], v[84:87], v[216:219], v[8:11]
	v_mfma_i32_16x16x64_i8 v[32:35], v[88:91], v[132:135], v[32:35]
	v_mfma_i32_16x16x64_i8 v[24:27], v[100:103], v[132:135], v[24:27]
	v_mfma_i32_16x16x64_i8 v[20:23], v[100:103], v[188:191], v[20:23]
	v_mfma_i32_16x16x64_i8 v[28:31], v[88:91], v[188:191], v[28:31]
	v_mfma_i32_16x16x64_i8 v[16:19], v[88:91], v[196:199], v[16:19]
	v_mfma_i32_16x16x64_i8 v[12:15], v[100:103], v[196:199], v[12:15]
	v_mfma_i32_16x16x64_i8 v[2:5], v[100:103], v[220:223], v[2:5]
	v_mfma_i32_16x16x64_i8 v[8:11], v[88:91], v[220:223], v[8:11]
	s_setprio 0
	s_barrier
	s_add_i32 s10, 0, 0x18000
	v_add_u32_e32 v0, s10, v214
	s_add_i32 s11, 0, 0x1c000
	ds_read_b128 v[44:47], v0
	ds_read_b128 v[52:55], v0 offset:1024
	ds_read_b128 v[60:63], v0 offset:2048
	ds_read_b128 v[64:67], v0 offset:3072
	v_add_u32_e32 v0, s11, v214
	ds_read_b128 v[84:87], v0
	ds_read_b128 v[88:91], v0 offset:1024
	ds_read_b128 v[92:95], v0 offset:2048
	ds_read_b128 v[100:103], v0 offset:3072
	s_add_u32 s8, vcc_lo, 0x40000
	s_addc_u32 s9, vcc_hi, 0
	s_mov_b32 m0, s67
	v_lshl_add_u64 v[6:7], s[8:9], 0, v[176:177]
	ds_read_b128 v[128:131], v215 offset:32768
	ds_read_b128 v[132:135], v215 offset:33792
	ds_read_b128 v[140:143], v215 offset:34816
	ds_read_b128 v[188:191], v215 offset:35840
	ds_read_b128 v[192:195], v215 offset:36864
	ds_read_b128 v[196:199], v215 offset:37888
	ds_read_b128 v[216:219], v215 offset:38912
	ds_read_b128 v[220:223], v215 offset:39936
	global_load_lds_dwordx4 v[6:7], off
	v_lshl_add_u64 v[6:7], s[8:9], 0, v[180:181]
	s_mov_b32 m0, s80
	s_nop 0
	global_load_lds_dwordx4 v[6:7], off
	s_waitcnt vmcnt(8)
	s_waitcnt lgkmcnt(0)
	s_barrier
	s_setprio 1
	s_waitcnt lgkmcnt(0)
	v_mfma_i32_16x16x64_i8 v[172:175], v[44:47], v[128:131], v[172:175]
	v_mfma_i32_16x16x64_i8 v[164:167], v[60:63], v[128:131], v[164:167]
	v_mfma_i32_16x16x64_i8 v[160:163], v[60:63], v[140:143], v[160:163]
	v_mfma_i32_16x16x64_i8 v[168:171], v[44:47], v[140:143], v[168:171]
	v_mfma_i32_16x16x64_i8 v[156:159], v[44:47], v[192:195], v[156:159]
	v_mfma_i32_16x16x64_i8 v[152:155], v[60:63], v[192:195], v[152:155]
	v_mfma_i32_16x16x64_i8 v[144:147], v[60:63], v[216:219], v[144:147]
	v_mfma_i32_16x16x64_i8 v[148:151], v[44:47], v[216:219], v[148:151]
	v_mfma_i32_16x16x64_i8 v[172:175], v[52:55], v[132:135], v[172:175]
	v_mfma_i32_16x16x64_i8 v[164:167], v[64:67], v[132:135], v[164:167]
	v_mfma_i32_16x16x64_i8 v[160:163], v[64:67], v[188:191], v[160:163]
	v_mfma_i32_16x16x64_i8 v[168:171], v[52:55], v[188:191], v[168:171]
	v_mfma_i32_16x16x64_i8 v[156:159], v[52:55], v[196:199], v[156:159]
	v_mfma_i32_16x16x64_i8 v[152:155], v[64:67], v[196:199], v[152:155]
	v_mfma_i32_16x16x64_i8 v[144:147], v[64:67], v[220:223], v[144:147]
	v_mfma_i32_16x16x64_i8 v[148:151], v[52:55], v[220:223], v[148:151]
	s_setprio 0
	s_setprio 1
	v_mfma_i32_16x16x64_i8 v[136:139], v[84:87], v[128:131], v[136:139]
	v_mfma_i32_16x16x64_i8 v[120:123], v[92:95], v[128:131], v[120:123]
	v_mfma_i32_16x16x64_i8 v[116:119], v[92:95], v[140:143], v[116:119]
	v_mfma_i32_16x16x64_i8 v[124:127], v[84:87], v[140:143], v[124:127]
	v_mfma_i32_16x16x64_i8 v[112:115], v[84:87], v[192:195], v[112:115]
	v_mfma_i32_16x16x64_i8 v[108:111], v[92:95], v[192:195], v[108:111]
	v_mfma_i32_16x16x64_i8 v[96:99], v[92:95], v[216:219], v[96:99]
	v_mfma_i32_16x16x64_i8 v[104:107], v[84:87], v[216:219], v[104:107]
	v_mfma_i32_16x16x64_i8 v[136:139], v[88:91], v[132:135], v[136:139]
	v_mfma_i32_16x16x64_i8 v[120:123], v[100:103], v[132:135], v[120:123]
	v_mfma_i32_16x16x64_i8 v[116:119], v[100:103], v[188:191], v[116:119]
	v_mfma_i32_16x16x64_i8 v[132:135], v[88:91], v[188:191], v[124:127]
	v_mfma_i32_16x16x64_i8 v[112:115], v[88:91], v[196:199], v[112:115]
	v_mfma_i32_16x16x64_i8 v[108:111], v[100:103], v[196:199], v[108:111]
	v_mfma_i32_16x16x64_i8 v[96:99], v[100:103], v[220:223], v[96:99]
	v_mfma_i32_16x16x64_i8 v[104:107], v[88:91], v[220:223], v[104:107]
	s_setprio 0
	s_barrier
; #define PG8_STAGE(bufoff, gbase, voff) do { _Pragma("unroll") for (int _i = 0; _i < 2; ++_i) \
;         __builtin_amdgcn_global_load_lds((const unsigned*)((const char*)(gbase) + (voff)[_i]), (PG8_LAS unsigned*)(lds + (bufoff) + ldsw + _i * 8192), 16, 0, 0); } while (0)
; #define PG8_LDA(dst, b, h) do { _Pragma("unroll") for (int m = 0; m < 4; ++m) _Pragma("unroll") for (int k = 0; k < 2; ++k) dst[m][k] = *(const PG8_LAS bf16x8*)(lds + PG8_SA(b, h) + aoff + m * 2048 + k * 1024); } while (0)
; #define PG8_LDB(dst, b, h) do { _Pragma("unroll") for (int n = 0; n < 2; ++n) _Pragma("unroll") for (int k = 0; k < 2; ++k) dst[n][k] = *(const PG8_LAS bf16x8*)(lds + PG8_SB(b, h) + boff + n * 2048 + k * 1024); } while (0)
; #define PG8_MMA(ai, bj, At, Bt) do { __builtin_amdgcn_s_setprio(1); _Pragma("unroll") for (int m = 0; m < 4; ++m) _Pragma("unroll") for (int n = 0; n < 2; ++n) _Pragma("unroll") for (int k = 0; k < 2; ++k) \
;         acc[ai][bj][m][n] = mma16<Epi::I8>(Bt[n][k], At[m][k], acc[ai][bj][m][n]); __builtin_amdgcn_s_setprio(0); } while (0)
; #define PG8_WAIT_V(n) asm volatile("s_waitcnt vmcnt(" #n ")" ::: "memory")
; template <class Epi, class Sched, bool ALIGN_EPI = false, bool SP2 = false>
; __device__ __forceinline__ void gemm_phase(PG8_LAS unsigned char* lds, const Gemm g, const Sched& S, const Epi& E) {
;     ...
;             PG8_LDB(B0, 0, 0); PG8_LDB(B1, 0, 1); PG8_SCHED; PG8_LDA(At, 0, 0); PG8_STAGE(PG8_SA(1, 1), a1 + hstep, voffA);
;             PG8_WAIT_V(8); PG8_WAIT_L(0); PG8_BAR; PG8_MMA(0, 0, At, B0); PG8_MMA(0, 1, At, B1); PG8_BAR; PG8_SCHED;
;             PG8_LDA(At, 0, 1); PG8_STAGE(PG8_SB(0, 0), b2, voffB); PG8_STAGE(PG8_SB(0, 1), b2 + hstep, voffB); PG8_STAGE(PG8_SA(0, 0), a2, voffA);
;             PG8_WAIT_V(8); PG8_WAIT_L(0); PG8_BAR; PG8_MMA(1, 0, At, B0); PG8_MMA(1, 1, At, B1); PG8_BAR; PG8_SCHED;
;             PG8_LDB(B0, 1, 0); PG8_LDB(B1, 1, 1); PG8_SCHED; PG8_LDA(At, 1, 0); PG8_STAGE(PG8_SA(0, 1), a2 + hstep, voffA);
;             PG8_WAIT_V(8); PG8_WAIT_L(0); PG8_BAR; PG8_MMA(0, 0, At, B0); PG8_MMA(0, 1, At, B1); PG8_BAR; PG8_SCHED;
;             PG8_LDA(At, 1, 1); PG8_STAGE(PG8_SB(1, 0), b3, voffB); PG8_STAGE(PG8_SB(1, 1), b3 + hstep, voffB); PG8_STAGE(PG8_SA(1, 0), a3, voffA);
;             PG8_WAIT_V(8); PG8_WAIT_L(0); PG8_BAR; PG8_MMA(1, 0, At, B0); PG8_MMA(1, 1, At, B1); PG8_BAR; PG8_SCHED;
	s_add_i32 s8, s10, s12
	v_lshl_add_u64 v[6:7], v[200:201], 0, s[92:93]
	s_mov_b32 m0, s8
	ds_read_b128 v[124:127], v215 offset:49152
	ds_read_b128 v[128:131], v215 offset:50176
	ds_read_b128 v[140:143], v215 offset:51200
	ds_read_b128 v[188:191], v215 offset:52224
	ds_read_b128 v[192:195], v215 offset:53248
	ds_read_b128 v[196:199], v215 offset:54272
	ds_read_b128 v[216:219], v215 offset:55296
	ds_read_b128 v[220:223], v215 offset:56320
	global_load_lds_dwordx4 v[6:7], off
	s_add_i32 m0, s8, 0x2000
	s_add_u32 s8, s82, 0x40080
	v_lshl_add_u64 v[6:7], v[206:207], 0, s[92:93]
	s_addc_u32 s9, s83, 0
	s_add_i32 s10, s11, s12
	global_load_lds_dwordx4 v[6:7], off
	v_lshl_add_u64 v[6:7], s[8:9], 0, v[178:179]
	s_mov_b32 m0, s10
	s_nop 0
	global_load_lds_dwordx4 v[6:7], off
	v_lshl_add_u64 v[6:7], s[8:9], 0, v[182:183]
	s_add_i32 m0, s10, 0x2000
	s_nop 0
	global_load_lds_dwordx4 v[6:7], off
	v_lshl_add_u64 v[6:7], v[210:211], 0, s[92:93]
	s_mov_b32 m0, s58
	s_nop 0
	global_load_lds_dwordx4 v[6:7], off
	v_lshl_add_u64 v[6:7], v[224:225], 0, s[92:93]
	s_mov_b32 m0, s4
	s_nop 0
	global_load_lds_dwordx4 v[6:7], off
	s_waitcnt vmcnt(8)
	s_waitcnt lgkmcnt(0)
	s_barrier
	s_setprio 1
	s_waitcnt lgkmcnt(0)
	v_mfma_i32_16x16x64_i8 v[80:83], v[44:47], v[124:127], v[80:83]
	v_mfma_i32_16x16x64_i8 v[72:75], v[60:63], v[124:127], v[72:75]
	v_mfma_i32_16x16x64_i8 v[68:71], v[60:63], v[140:143], v[68:71]
	v_mfma_i32_16x16x64_i8 v[76:79], v[44:47], v[140:143], v[76:79]
	v_mfma_i32_16x16x64_i8 v[56:59], v[44:47], v[192:195], v[56:59]
	v_mfma_i32_16x16x64_i8 v[48:51], v[60:63], v[192:195], v[48:51]
	v_mfma_i32_16x16x64_i8 v[36:39], v[60:63], v[216:219], v[36:39]
	v_mfma_i32_16x16x64_i8 v[40:43], v[44:47], v[216:219], v[40:43]
	v_mfma_i32_16x16x64_i8 v[80:83], v[52:55], v[128:131], v[80:83]
	v_mfma_i32_16x16x64_i8 v[72:75], v[64:67], v[128:131], v[72:75]
	v_mfma_i32_16x16x64_i8 v[68:71], v[64:67], v[188:191], v[68:71]
	v_mfma_i32_16x16x64_i8 v[76:79], v[52:55], v[188:191], v[76:79]
	v_mfma_i32_16x16x64_i8 v[56:59], v[52:55], v[196:199], v[56:59]
	v_mfma_i32_16x16x64_i8 v[48:51], v[64:67], v[196:199], v[48:51]
	v_mfma_i32_16x16x64_i8 v[36:39], v[64:67], v[220:223], v[36:39]
	v_mfma_i32_16x16x64_i8 v[40:43], v[52:55], v[220:223], v[40:43]
	s_setprio 0
	s_setprio 1
	v_mfma_i32_16x16x64_i8 v[32:35], v[84:87], v[124:127], v[32:35]
	v_mfma_i32_16x16x64_i8 v[24:27], v[92:95], v[124:127], v[24:27]
	v_mfma_i32_16x16x64_i8 v[20:23], v[92:95], v[140:143], v[20:23]
	v_mfma_i32_16x16x64_i8 v[28:31], v[84:87], v[140:143], v[28:31]
	v_mfma_i32_16x16x64_i8 v[16:19], v[84:87], v[192:195], v[16:19]
	v_mfma_i32_16x16x64_i8 v[12:15], v[92:95], v[192:195], v[12:15]
	v_mfma_i32_16x16x64_i8 v[2:5], v[92:95], v[216:219], v[2:5]
	v_mfma_i32_16x16x64_i8 v[6:9], v[84:87], v[216:219], v[8:11]
	v_mfma_i32_16x16x64_i8 v[32:35], v[88:91], v[128:131], v[32:35]
	v_mfma_i32_16x16x64_i8 v[24:27], v[100:103], v[128:131], v[24:27]
	v_mfma_i32_16x16x64_i8 v[20:23], v[100:103], v[188:191], v[20:23]
	v_mfma_i32_16x16x64_i8 v[28:31], v[88:91], v[188:191], v[28:31]
	v_mfma_i32_16x16x64_i8 v[16:19], v[88:91], v[196:199], v[16:19]
	v_mfma_i32_16x16x64_i8 v[12:15], v[100:103], v[196:199], v[12:15]
	v_mfma_i32_16x16x64_i8 v[8:11], v[88:91], v[220:223], v[6:9]
	v_mfma_i32_16x16x64_i8 v[4:7], v[100:103], v[220:223], v[2:5]
	s_setprio 0
	s_barrier
	s_add_i32 s5, s5, 2
	s_add_u32 s85, s85, 0x100
	s_addc_u32 s68, s68, 0
	s_cmp_gt_u32 s5, 13
	s_mov_b64 s[8:9], s[70:71]
	s_cbranch_scc0 .LBB0_385
